# LRU gates: non-transcendental elementwise ops as packed f32 (v_pk_add/mul/fma_f32) on token pairs
# speedup vs baseline: 1.0008x; 1.0008x over previous
; __device__ __forceinline__ void lru_tile(const Params& P, int chunk, int head, int pass, char* smem_raw) {
;     ...
;   const int tid = VTID, lane = tid & 63, wid = tid >> 6;
;   const int q = tid >> 6, ch = tid & 63;
;   const int row0 = chunk * 128;
;   int seq_lo, seq_hi;
;   if (chunk < 256) { seq_lo = (chunk >> 6) << 13; seq_hi = seq_lo + 8192; }
;   else { const int b = (chunk - 256) >> 1; seq_lo = N_X + b * 256; seq_hi = seq_lo + 256; }
;   const int gch = head * 64 + ch;
;   const float* hfbuf = reinterpret_cast<const float*>(P.hy);
;   float* hfw = reinterpret_cast<float*>(P.hy);
;   {
;     const float w0 = P.conv_w[gch], w1 = P.conv_w[512 + gch], w2 = P.conv_w[1024 + gch], w3 = P.conv_w[1536 + gch];
;     const float cb = P.conv_b[gch];
; __device__ __forceinline__ void run_phase(const Params& P, const int ph, char* smem_raw) {
;     ...
;       for (int t = VBID; t < 2112; t += VGRID) lru_tile(P, t >> 3, t & 7, 2, smv_raw);
.LBB0_287:
	v_readlane_b32 s0, v252, 0
	v_readlane_b32 s1, v252, 1
	v_readfirstlane_b32 s68, v153
	s_nop 3
	s_sub_u32 s0, s0, 0x170
	s_subb_u32 s1, s1, 0
	s_load_dwordx2 s[10:11], s[0:1], 0x148
	s_load_dwordx2 s[12:13], s[0:1], 0x158
	s_load_dwordx2 s[18:19], s[0:1], 0x130
	s_load_dwordx2 s[20:21], s[0:1], 0x128
	s_load_dwordx4 s[24:27], s[0:1], 0x70
	s_load_dwordx2 s[28:29], s[0:1], 0x88
	s_load_dwordx2 s[30:31], s[0:1], 0x98
	s_load_dwordx2 s[36:37], s[0:1], 0xa0
	s_lshl_b32 s4, s2, 1
	s_add_u32 s68, s4, s68
	s_mov_b32 s69, 0
	s_mov_b32 s70, 4
	s_cmp_lt_u32 s68, 64
	s_cselect_b32 s70, 5, 4
	s_mov_b32 s72, 0xffff0000
	s_mov_b32 s73, -1
	s_mov_b32 s74, 0
	s_mov_b32 s75, -1
	s_mov_b32 s76, 0
	s_mov_b32 s77, 0xffff0000
	s_mov_b32 s78, -1
	s_mov_b32 s79, 0x0000ffff
	s_mov_b32 s80, -1
	s_mov_b32 s81, 0
	s_mov_b32 s82, 0x0000ffff
	s_mov_b32 s83, 0
	v_and_b32_e32 v138, 63, v152
	v_lshrrev_b32_e32 v139, 4, v138
	v_and_b32_e32 v140, 15, v138
	v_bfe_u32 v141, v152, 6, 2
	v_lshl_add_u32 v255, v141, 4, v140
	v_mul_u32_u24_e32 v253, 0x12000, v153
	v_add_u32_e32 v253, 16, v253
	v_mul_u32_u24_e32 v134, 0x18000, v139
	v_lshl_add_u32 v134, v255, 1, v134
	v_lshlrev_b32_e32 v237, 16, v139
	v_lshl_add_u32 v237, v255, 1, v237
	v_lshlrev_b32_e32 v250, 3, v255
	v_lshlrev_b32_e32 v251, 7, v255
	v_lshl_add_u32 v251, v139, 4, v251
	v_lshrrev_b32_e32 v254, 3, v140
	v_lshl_add_u32 v254, v141, 1, v254
	v_lshlrev_b32_e32 v202, 1, v139
	v_xor_b32_e32 v89, v254, v202
	v_xor_b32_e32 v130, 1, v89
	v_and_b32_e32 v203, 7, v140
	v_lshl_add_u32 v202, v139, 12, v253
	v_lshl_add_u32 v202, v203, 1, v202
	v_lshl_add_u32 v89, v89, 4, v202
	v_lshl_add_u32 v130, v130, 4, v202
	v_lshrrev_b32_e32 v202, 2, v140
	v_and_b32_e32 v203, 3, v140
	v_lshl_add_u32 v254, v202, 5, v203
	v_lshl_add_u32 v254, v254, 7, v253
	v_lshrrev_b32_e32 v203, 1, v203
	v_lshl_add_u32 v202, v202, 1, v203
	v_xor_b32_e32 v202, v139, v202
	v_lshl_add_u32 v131, v202, 4, v254
	v_xor_b32_e32 v202, 4, v202
	v_lshl_add_u32 v133, v202, 4, v254
	v_cmp_eq_u32_e32 vcc, 0, v139
	s_mov_b64 s[84:85], vcc
	v_cmp_eq_u32_e32 vcc, 3, v139
	s_mov_b64 s[86:87], vcc
	s_waitcnt lgkmcnt(0)
; __device__ __forceinline__ float bf2f(u16 h) { return __uint_as_float(((unsigned)h) << 16); }
; __device__ __forceinline__ void lru_tile(const Params& P, int chunk, int head, int pass, char* smem_raw) {
;     ...
;     const float w0 = P.conv_w[gch], w1 = P.conv_w[512 + gch], w2 = P.conv_w[1024 + gch], w3 = P.conv_w[1536 + gch];
;     const float cb = P.conv_b[gch];
;     const u16* zu = P.zq + gch;
;     const int r = row0 + q * 32;
;     float uv[35];
; #pragma unroll
;     for (int i = 0; i < 35; ++i) {
;       const int rr = r - 2 + i;
;       uv[i] = (rr >= seq_lo && rr < seq_hi) ? bf2f(zu[(long)rr * 1536]) : 0.f;
;     ...
;     for (int tc = 0; tc < 4; ++tc) {
;       const int cidx = d * 512 + head * 64 + 16 * tc + (lane & 15);
;       ba[tc] = P.b_a[cidx] * -1.4426950408889634f; bi[tc] = P.b_i[cidx] * -1.4426950408889634f;
;       const float nl = -P.lam[cidx];
;       const float e_ = __expf(nl);
;       const float sp = (nl > 20.f) ? nl
;                      : (e_ < 0.03f ? e_ * (1.f - e_ * (0.5f - e_ * (0.33333334f - 0.25f * e_))) : __logf(1.f + e_));
;       c8[tc] = 8.f * 1.4426950408889634f * sp;
;     }
	s_and_b32 s56, s68, 7
	s_lshl_b32 s56, s56, 6
	s_lshr_b32 s59, s68, 3
	s_cmp_lt_u32 s59, 256
	s_cselect_b32 s60, 63, 1
	s_and_b32 s57, s59, s60
	s_cmp_eq_u32 s57, 0
	s_cselect_b64 s[0:1], s[84:85], 0
	s_cmp_eq_u32 s57, s60
	s_cselect_b64 s[4:5], s[86:87], 0
	v_mov_b32_e32 v255, 0x1800
	v_cndmask_b32_e64 v150, 0, v255, s[0:1]
	v_lshlrev_b32_e32 v136, 1, v150
	v_add_u32_e32 v136, v134, v136
	v_add_u32_e32 v150, v134, v150
	v_cndmask_b32_e64 v151, 0, v255, s[4:5]
	v_sub_u32_e32 v151, v134, v151
	s_lshl_b32 s61, s59, 7
	s_mul_i32 s0, s61, 0xc00
	s_lshl_b32 s1, s56, 1
	s_add_u32 s0, s0, s1
	s_add_u32 s4, s10, s0
	s_addc_u32 s5, s11, 0
	s_sub_u32 s4, s4, 0x1800
	s_subb_u32 s5, s5, 0
	global_load_ushort v205, v136, s[4:5]
	s_add_u32 s4, s4, 0xc00
	s_addc_u32 s5, s5, 0
	global_load_ushort v206, v150, s[4:5]
	s_add_u32 s4, s4, 0xc00
	s_addc_u32 s5, s5, 0
	global_load_ushort v207, v134, s[4:5]
	s_add_u32 s4, s4, 0xc00
	s_addc_u32 s5, s5, 0
	global_load_ushort v208, v134, s[4:5]
	s_add_u32 s4, s4, 0xc00
	s_addc_u32 s5, s5, 0
	global_load_ushort v209, v134, s[4:5]
	s_add_u32 s4, s4, 0xc00
	s_addc_u32 s5, s5, 0
	global_load_ushort v210, v134, s[4:5]
	s_add_u32 s4, s4, 0xc00
	s_addc_u32 s5, s5, 0
	global_load_ushort v211, v134, s[4:5]
	s_add_u32 s4, s4, 0xc00
	s_addc_u32 s5, s5, 0
	global_load_ushort v212, v134, s[4:5]
	s_add_u32 s4, s4, 0xc00
	s_addc_u32 s5, s5, 0
	global_load_ushort v213, v134, s[4:5]
	s_add_u32 s4, s4, 0xc00
	s_addc_u32 s5, s5, 0
	global_load_ushort v214, v134, s[4:5]
	s_add_u32 s4, s4, 0xc00
	s_addc_u32 s5, s5, 0
	global_load_ushort v215, v134, s[4:5]
	s_add_u32 s4, s4, 0xc00
	s_addc_u32 s5, s5, 0
	global_load_ushort v216, v134, s[4:5]
	s_add_u32 s4, s4, 0xc00
	s_addc_u32 s5, s5, 0
	global_load_ushort v217, v134, s[4:5]
	s_add_u32 s4, s4, 0xc00
	s_addc_u32 s5, s5, 0
	global_load_ushort v218, v134, s[4:5]
	s_add_u32 s4, s4, 0xc00
	s_addc_u32 s5, s5, 0
	global_load_ushort v219, v134, s[4:5]
	s_add_u32 s4, s4, 0xc00
	s_addc_u32 s5, s5, 0
	global_load_ushort v220, v134, s[4:5]
	s_add_u32 s4, s4, 0xc00
	s_addc_u32 s5, s5, 0
	global_load_ushort v221, v134, s[4:5]
	s_add_u32 s4, s4, 0xc00
	s_addc_u32 s5, s5, 0
	global_load_ushort v222, v134, s[4:5]
	s_add_u32 s4, s4, 0xc00
	s_addc_u32 s5, s5, 0
	global_load_ushort v223, v134, s[4:5]
	s_add_u32 s4, s4, 0xc00
	s_addc_u32 s5, s5, 0
	global_load_ushort v224, v134, s[4:5]
	s_add_u32 s4, s4, 0xc00
	s_addc_u32 s5, s5, 0
	global_load_ushort v225, v134, s[4:5]
	s_add_u32 s4, s4, 0xc00
	s_addc_u32 s5, s5, 0
	global_load_ushort v226, v134, s[4:5]
	s_add_u32 s4, s4, 0xc00
	s_addc_u32 s5, s5, 0
	global_load_ushort v227, v134, s[4:5]
	s_add_u32 s4, s4, 0xc00
	s_addc_u32 s5, s5, 0
	global_load_ushort v228, v134, s[4:5]
	s_add_u32 s4, s4, 0xc00
	s_addc_u32 s5, s5, 0
	global_load_ushort v229, v134, s[4:5]
	s_add_u32 s4, s4, 0xc00
	s_addc_u32 s5, s5, 0
	global_load_ushort v230, v134, s[4:5]
	s_add_u32 s4, s4, 0xc00
	s_addc_u32 s5, s5, 0
	global_load_ushort v231, v134, s[4:5]
	s_add_u32 s4, s4, 0xc00
	s_addc_u32 s5, s5, 0
	global_load_ushort v232, v134, s[4:5]
	s_add_u32 s4, s4, 0xc00
	s_addc_u32 s5, s5, 0
	global_load_ushort v233, v134, s[4:5]
	s_add_u32 s4, s4, 0xc00
	s_addc_u32 s5, s5, 0
	global_load_ushort v234, v134, s[4:5]
	s_add_u32 s4, s4, 0xc00
	s_addc_u32 s5, s5, 0
	global_load_ushort v235, v134, s[4:5]
	s_add_u32 s4, s4, 0xc00
	s_addc_u32 s5, s5, 0
	global_load_ushort v236, v134, s[4:5]
	s_add_u32 s4, s4, 0xc00
	s_addc_u32 s5, s5, 0
	global_load_ushort v142, v134, s[4:5]
	s_add_u32 s4, s4, 0xc00
	s_addc_u32 s5, s5, 0
	global_load_ushort v143, v134, s[4:5]
	s_add_u32 s4, s4, 0xc00
	s_addc_u32 s5, s5, 0
	global_load_ushort v144, v151, s[4:5]
	v_bfe_u32 v255, v152, 6, 2
	v_and_b32_e32 v253, 15, v152
	v_lshl_add_u32 v255, v255, 4, v253
	v_add_u32_e32 v255, s56, v255
	v_lshlrev_b32_e32 v255, 2, v255
	global_load_dword v65, v255, s[24:25]
	global_load_dword v67, v255, s[24:25] offset:2048
	s_add_u32 s0, s24, 0x1000
	s_addc_u32 s1, s25, 0
	global_load_dword v68, v255, s[0:1]
	global_load_dword v70, v255, s[0:1] offset:2048
	global_load_dword v73, v255, s[26:27]
	s_add_u32 s0, s28, 0x0
	s_addc_u32 s1, s29, 0
	global_load_dword v75, v255, s[0:1]
	s_add_u32 s0, s30, 0x0
	s_addc_u32 s1, s31, 0
	global_load_dword v84, v255, s[0:1]
	s_add_u32 s0, s36, 0x0
	s_addc_u32 s1, s37, 0
	global_load_dword v85, v255, s[0:1]
	s_add_u32 s0, s28, 0x800
	s_addc_u32 s1, s29, 0
	global_load_dword v145, v255, s[0:1]
	s_add_u32 s0, s30, 0x800
	s_addc_u32 s1, s31, 0
	global_load_dword v146, v255, s[0:1]
	s_add_u32 s0, s36, 0x800
	s_addc_u32 s1, s37, 0
	global_load_dword v147, v255, s[0:1]
	s_lshl_b32 s0, s56, 8
	s_add_u32 s0, s0, 0x0
	s_add_u32 s4, s20, s0
	s_addc_u32 s5, s21, 0
	global_load_dwordx4 v[238:241], v251, s[4:5]
	global_load_dwordx4 v[242:245], v251, s[4:5] offset:64
	s_add_u32 s4, s4, 0x2000
	s_addc_u32 s5, s5, 0
	global_load_dwordx4 v[246:249], v251, s[4:5]
	global_load_dwordx4 v[194:197], v251, s[4:5] offset:64
	s_waitcnt vmcnt(0)
	v_mul_f32_e32 v75, 0xbfb8aa3b, v75
	v_mul_f32_e32 v84, 0xbfb8aa3b, v84
	v_sub_f32_e32 v138, 0, v85
	v_mul_f32_e32 v139, 0x3fb8aa3b, v138
	v_exp_f32_e32 v139, v139
	s_nop 0
	v_mul_f32_e32 v140, 0xbe800000, v139
	v_add_f32_e32 v140, 0x3eaaaaab, v140
	v_fma_f32 v140, -v139, v140, 0.5
	v_fma_f32 v140, -v139, v140, 1.0
	v_mul_f32_e32 v140, v139, v140
	v_add_f32_e32 v141, 1.0, v139
	v_log_f32_e32 v141, v141
	v_mov_b32_e32 v255, 0x3cf5c28f
	v_mul_f32_e32 v141, 0x3f317218, v141
	v_cmp_gt_f32_e32 vcc, v255, v139
	s_nop 1
	v_cndmask_b32_e32 v140, v141, v140, vcc
	v_mov_b32_e32 v255, 0x41a00000
	v_cmp_lt_f32_e32 vcc, v255, v138
	s_nop 1
	v_cndmask_b32_e32 v140, v140, v138, vcc
	v_mul_f32_e32 v85, 0xc138aa3b, v140
	v_mul_f32_e32 v145, 0xbfb8aa3b, v145
	v_mul_f32_e32 v146, 0xbfb8aa3b, v146
	v_sub_f32_e32 v138, 0, v147
	v_mul_f32_e32 v139, 0x3fb8aa3b, v138
	v_exp_f32_e32 v139, v139
	s_nop 0
	v_mul_f32_e32 v140, 0xbe800000, v139
	v_add_f32_e32 v140, 0x3eaaaaab, v140
	v_fma_f32 v140, -v139, v140, 0.5
	v_fma_f32 v140, -v139, v140, 1.0
	v_mul_f32_e32 v140, v139, v140
	v_add_f32_e32 v141, 1.0, v139
	v_log_f32_e32 v141, v141
	v_mov_b32_e32 v255, 0x3cf5c28f
	v_mul_f32_e32 v141, 0x3f317218, v141
	v_cmp_gt_f32_e32 vcc, v255, v139
	s_nop 1
	v_cndmask_b32_e32 v140, v141, v140, vcc
	v_mov_b32_e32 v255, 0x41a00000
	v_cmp_lt_f32_e32 vcc, v255, v138
	s_nop 1
	v_cndmask_b32_e32 v140, v140, v138, vcc
	v_mul_f32_e32 v147, 0xc138aa3b, v140
	v_mov_b32_e32 v132, 1.0

; __device__ __forceinline__ float bf2f(u16 h) { return __uint_as_float(((unsigned)h) << 16); }
; __device__ __forceinline__ void lru_tile(const Params& P, int chunk, int head, int pass, char* smem_raw) {
;     ...
;       for (int s = 0; s < 2; ++s) {
;         const bf16x8 af = *reinterpret_cast<const bf16x8*>(&sm_uc[(sb * 64 + wid * 16 + (lane & 15)) * LDSS + s * 32 + (lane >> 4) * 8]);
; #pragma unroll
;         for (int t = 0; t < 8; ++t) {
;           const bf16x8 bfr = *reinterpret_cast<const bf16x8*>(&sm_w[(t * 16 + (lane & 15)) * LDSS + s * 32 + (lane >> 4) * 8]);
;           acc[t] = __builtin_amdgcn_mfma_f32_16x16x32_bf16(af, bfr, acc[t], 0, 0, 0);
;         }
;       }
; #pragma unroll
;       for (int tc = 0; tc < 4; ++tc)
; #pragma unroll
;         for (int reg = 0; reg < 4; ++reg) {
;           const int tl = wid * 16 + (lane >> 4) * 4 + reg;
;           const int c = 16 * tc + (lane & 15);
;           const float r = __builtin_amdgcn_rcpf(1.f + __builtin_amdgcn_exp2f(acc[tc][reg] + ba[tc]));
;           const float ii = __builtin_amdgcn_rcpf(1.f + __builtin_amdgcn_exp2f(acc[tc + 4][reg] + bi[tc]));
;           const float la = -c8[tc] * r;
;           const float a = __builtin_amdgcn_exp2f(la);
;           const float ucv = bf2f(sm_uc[(sb * 64 + tl) * LDSS + c]);
;           const float bt = __builtin_amdgcn_sqrtf(fmaxf(1.f - a * a, 0.f)) * (ii * ucv);
;           sm_a[tl * 64 + c] = a;
;           sm_b[tl * 64 + c] = bt;
;         }
.Lmy_lrua_nopf:
	ds_read_b128 v[76:79], v131 offset:0
	ds_read_b128 v[80:83], v133 offset:0
	ds_read_b128 v[122:125], v131 offset:512
	ds_read_b128 v[126:129], v133 offset:512
	s_waitcnt lgkmcnt(3)
	v_mfma_f32_16x16x32_bf16 v[0:3], v[76:79], v[238:241], 0
	v_mfma_f32_16x16x32_bf16 v[90:93], v[76:79], v[246:249], 0
	ds_read_b128 v[76:79], v131 offset:1024
	s_waitcnt lgkmcnt(3)
	v_mfma_f32_16x16x32_bf16 v[0:3], v[80:83], v[242:245], v[0:3]
	v_mfma_f32_16x16x32_bf16 v[90:93], v[80:83], v[194:197], v[90:93]
	ds_read_b128 v[80:83], v133 offset:1024
	s_waitcnt lgkmcnt(3)
	v_mfma_f32_16x16x32_bf16 v[4:7], v[122:125], v[238:241], 0
	v_mfma_f32_16x16x32_bf16 v[94:97], v[122:125], v[246:249], 0
	ds_read_b128 v[122:125], v131 offset:1536
	s_waitcnt lgkmcnt(3)
	v_mfma_f32_16x16x32_bf16 v[4:7], v[126:129], v[242:245], v[4:7]
	v_mfma_f32_16x16x32_bf16 v[94:97], v[126:129], v[194:197], v[94:97]
	ds_read_b128 v[126:129], v133 offset:1536
	s_waitcnt lgkmcnt(3)
	v_mfma_f32_16x16x32_bf16 v[8:11], v[76:79], v[238:241], 0
	v_mfma_f32_16x16x32_bf16 v[98:101], v[76:79], v[246:249], 0
	ds_read_b128 v[76:79], v131 offset:2048
	s_waitcnt lgkmcnt(3)
	v_mfma_f32_16x16x32_bf16 v[8:11], v[80:83], v[242:245], v[8:11]
	v_mfma_f32_16x16x32_bf16 v[98:101], v[80:83], v[194:197], v[98:101]
	ds_read_b128 v[80:83], v133 offset:2048
	s_waitcnt lgkmcnt(3)
	v_mfma_f32_16x16x32_bf16 v[12:15], v[122:125], v[238:241], 0
	v_mfma_f32_16x16x32_bf16 v[102:105], v[122:125], v[246:249], 0
	ds_read_b128 v[122:125], v131 offset:2560
	s_waitcnt lgkmcnt(3)
	v_mfma_f32_16x16x32_bf16 v[12:15], v[126:129], v[242:245], v[12:15]
	v_mfma_f32_16x16x32_bf16 v[102:105], v[126:129], v[194:197], v[102:105]
	ds_read_b128 v[126:129], v133 offset:2560
	s_waitcnt lgkmcnt(3)
	v_mfma_f32_16x16x32_bf16 v[16:19], v[76:79], v[238:241], 0
	v_mfma_f32_16x16x32_bf16 v[106:109], v[76:79], v[246:249], 0
	ds_read_b128 v[76:79], v131 offset:3072
	s_waitcnt lgkmcnt(3)
	v_mfma_f32_16x16x32_bf16 v[16:19], v[80:83], v[242:245], v[16:19]
	v_mfma_f32_16x16x32_bf16 v[106:109], v[80:83], v[194:197], v[106:109]
	ds_read_b128 v[80:83], v133 offset:3072
	s_waitcnt lgkmcnt(3)
	v_mfma_f32_16x16x32_bf16 v[20:23], v[122:125], v[238:241], 0
	v_mfma_f32_16x16x32_bf16 v[110:113], v[122:125], v[246:249], 0
	ds_read_b128 v[122:125], v131 offset:3584
	s_waitcnt lgkmcnt(3)
	v_mfma_f32_16x16x32_bf16 v[20:23], v[126:129], v[242:245], v[20:23]
	v_mfma_f32_16x16x32_bf16 v[110:113], v[126:129], v[194:197], v[110:113]
	ds_read_b128 v[126:129], v133 offset:3584
	s_waitcnt lgkmcnt(3)
	v_mfma_f32_16x16x32_bf16 v[24:27], v[76:79], v[238:241], 0
	v_mfma_f32_16x16x32_bf16 v[114:117], v[76:79], v[246:249], 0
	s_waitcnt lgkmcnt(2)
	v_mfma_f32_16x16x32_bf16 v[24:27], v[80:83], v[242:245], v[24:27]
	v_mfma_f32_16x16x32_bf16 v[114:117], v[80:83], v[194:197], v[114:117]
	s_waitcnt lgkmcnt(1)
	v_mfma_f32_16x16x32_bf16 v[28:31], v[122:125], v[238:241], 0
	v_mfma_f32_16x16x32_bf16 v[118:121], v[122:125], v[246:249], 0
	s_waitcnt lgkmcnt(0)
	v_mfma_f32_16x16x32_bf16 v[28:31], v[126:129], v[242:245], v[28:31]
	v_mfma_f32_16x16x32_bf16 v[118:121], v[126:129], v[194:197], v[118:121]
	s_lshl_b32 s0, s56, 8
	s_add_u32 s0, s0, 0x20000
	s_add_u32 s4, s20, s0
	s_addc_u32 s5, s21, 0
	global_load_dwordx4 v[238:241], v251, s[4:5]
	global_load_dwordx4 v[242:245], v251, s[4:5] offset:64
	s_add_u32 s4, s4, 0x2000
	s_addc_u32 s5, s5, 0
	global_load_dwordx4 v[246:249], v251, s[4:5]
	global_load_dwordx4 v[194:197], v251, s[4:5] offset:64
	s_nop 7
	s_nop 7
	v_pk_add_f32 v[0:1], v[0:1], v[74:75] op_sel:[0,1]
	v_pk_add_f32 v[2:3], v[2:3], v[74:75] op_sel:[0,1]
	v_pk_add_f32 v[90:91], v[90:91], v[84:85] op_sel_hi:[1,0]
	v_pk_add_f32 v[92:93], v[92:93], v[84:85] op_sel_hi:[1,0]
	v_exp_f32_e32 v0, v0
	v_exp_f32_e32 v1, v1
	v_exp_f32_e32 v2, v2
	v_exp_f32_e32 v3, v3
	v_exp_f32_e32 v90, v90
	v_exp_f32_e32 v91, v91
	v_exp_f32_e32 v92, v92
	v_exp_f32_e32 v93, v93
	v_pk_add_f32 v[0:1], v[0:1], v[132:133] op_sel_hi:[1,0]
	v_pk_add_f32 v[2:3], v[2:3], v[132:133] op_sel_hi:[1,0]
	v_pk_add_f32 v[90:91], v[90:91], v[132:133] op_sel_hi:[1,0]
	v_pk_add_f32 v[92:93], v[92:93], v[132:133] op_sel_hi:[1,0]
	v_rcp_f32_e32 v0, v0
	v_rcp_f32_e32 v1, v1
	v_rcp_f32_e32 v2, v2
	v_rcp_f32_e32 v3, v3
	v_rcp_f32_e32 v90, v90
	v_rcp_f32_e32 v91, v91
	v_rcp_f32_e32 v92, v92
	v_rcp_f32_e32 v93, v93
	v_pk_mul_f32 v[0:1], v[0:1], v[84:85] op_sel:[0,1]
	v_pk_mul_f32 v[2:3], v[2:3], v[84:85] op_sel:[0,1]
	v_pk_mul_f32 v[90:91], v[90:91], v[162:163]
	v_pk_mul_f32 v[92:93], v[92:93], v[164:165]
	v_exp_f32_e32 v0, v0
	v_exp_f32_e32 v1, v1
	v_exp_f32_e32 v2, v2
	v_exp_f32_e32 v3, v3
	s_nop 0
	v_pk_fma_f32 v[138:139], v[0:1], v[0:1], v[132:133] op_sel_hi:[1,1,0] neg_lo:[1,0,0] neg_hi:[1,0,0]
	v_pk_fma_f32 v[140:141], v[2:3], v[2:3], v[132:133] op_sel_hi:[1,1,0] neg_lo:[1,0,0] neg_hi:[1,0,0]
	v_max_f32_e32 v138, 0, v138
	v_max_f32_e32 v139, 0, v139
	v_max_f32_e32 v140, 0, v140
	v_max_f32_e32 v141, 0, v141
	v_sqrt_f32_e32 v138, v138
	v_sqrt_f32_e32 v139, v139
	v_sqrt_f32_e32 v140, v140
	v_sqrt_f32_e32 v141, v141
	s_nop 0
	v_pk_mul_f32 v[90:91], v[138:139], v[90:91]
	v_pk_mul_f32 v[92:93], v[140:141], v[92:93]
	v_pk_add_f32 v[4:5], v[4:5], v[74:75] op_sel:[0,1]
	v_pk_add_f32 v[6:7], v[6:7], v[74:75] op_sel:[0,1]
	v_pk_add_f32 v[94:95], v[94:95], v[84:85] op_sel_hi:[1,0]
	v_pk_add_f32 v[96:97], v[96:97], v[84:85] op_sel_hi:[1,0]
	v_exp_f32_e32 v4, v4
	v_exp_f32_e32 v5, v5
	v_exp_f32_e32 v6, v6
	v_exp_f32_e32 v7, v7
	v_exp_f32_e32 v94, v94
	v_exp_f32_e32 v95, v95
	v_exp_f32_e32 v96, v96
	v_exp_f32_e32 v97, v97
	v_pk_add_f32 v[4:5], v[4:5], v[132:133] op_sel_hi:[1,0]
	v_pk_add_f32 v[6:7], v[6:7], v[132:133] op_sel_hi:[1,0]
; __device__ __forceinline__ float bf2f(u16 h) { return __uint_as_float(((unsigned)h) << 16); }
; __device__ __forceinline__ void lru_tile(const Params& P, int chunk, int head, int pass, char* smem_raw) {
;     ...
;       for (int tc = 0; tc < 4; ++tc)
; #pragma unroll
;         for (int reg = 0; reg < 4; ++reg) {
;           const int tl = wid * 16 + (lane >> 4) * 4 + reg;
;           const int c = 16 * tc + (lane & 15);
;           const float r = __builtin_amdgcn_rcpf(1.f + __builtin_amdgcn_exp2f(acc[tc][reg] + ba[tc]));
;           const float ii = __builtin_amdgcn_rcpf(1.f + __builtin_amdgcn_exp2f(acc[tc + 4][reg] + bi[tc]));
;           const float la = -c8[tc] * r;
;           const float a = __builtin_amdgcn_exp2f(la);
;           const float ucv = bf2f(sm_uc[(sb * 64 + tl) * LDSS + c]);
;           const float bt = __builtin_amdgcn_sqrtf(fmaxf(1.f - a * a, 0.f)) * (ii * ucv);
;           sm_a[tl * 64 + c] = a;
;           sm_b[tl * 64 + c] = bt;
;         }
	v_pk_add_f32 v[94:95], v[94:95], v[132:133] op_sel_hi:[1,0]
	v_pk_add_f32 v[96:97], v[96:97], v[132:133] op_sel_hi:[1,0]
	v_rcp_f32_e32 v4, v4
	v_rcp_f32_e32 v5, v5
	v_rcp_f32_e32 v6, v6
	v_rcp_f32_e32 v7, v7
	v_rcp_f32_e32 v94, v94
	v_rcp_f32_e32 v95, v95
	v_rcp_f32_e32 v96, v96
	v_rcp_f32_e32 v97, v97
	v_pk_mul_f32 v[4:5], v[4:5], v[84:85] op_sel:[0,1]
	v_pk_mul_f32 v[6:7], v[6:7], v[84:85] op_sel:[0,1]
	v_pk_mul_f32 v[94:95], v[94:95], v[166:167]
	v_pk_mul_f32 v[96:97], v[96:97], v[168:169]
	v_exp_f32_e32 v4, v4
	v_exp_f32_e32 v5, v5
	v_exp_f32_e32 v6, v6
	v_exp_f32_e32 v7, v7
	s_nop 0
	v_pk_fma_f32 v[138:139], v[4:5], v[4:5], v[132:133] op_sel_hi:[1,1,0] neg_lo:[1,0,0] neg_hi:[1,0,0]
	v_pk_fma_f32 v[140:141], v[6:7], v[6:7], v[132:133] op_sel_hi:[1,1,0] neg_lo:[1,0,0] neg_hi:[1,0,0]
	v_max_f32_e32 v138, 0, v138
	v_max_f32_e32 v139, 0, v139
	v_max_f32_e32 v140, 0, v140
	v_max_f32_e32 v141, 0, v141
	v_sqrt_f32_e32 v138, v138
	v_sqrt_f32_e32 v139, v139
	v_sqrt_f32_e32 v140, v140
	v_sqrt_f32_e32 v141, v141
	s_nop 0
	v_pk_mul_f32 v[94:95], v[138:139], v[94:95]
	v_pk_mul_f32 v[96:97], v[140:141], v[96:97]
	v_pk_add_f32 v[8:9], v[8:9], v[74:75] op_sel:[0,1]
	v_pk_add_f32 v[10:11], v[10:11], v[74:75] op_sel:[0,1]
	v_pk_add_f32 v[98:99], v[98:99], v[84:85] op_sel_hi:[1,0]
	v_pk_add_f32 v[100:101], v[100:101], v[84:85] op_sel_hi:[1,0]
	v_exp_f32_e32 v8, v8
	v_exp_f32_e32 v9, v9
	v_exp_f32_e32 v10, v10
	v_exp_f32_e32 v11, v11
	v_exp_f32_e32 v98, v98
	v_exp_f32_e32 v99, v99
	v_exp_f32_e32 v100, v100
	v_exp_f32_e32 v101, v101
	v_pk_add_f32 v[8:9], v[8:9], v[132:133] op_sel_hi:[1,0]
	v_pk_add_f32 v[10:11], v[10:11], v[132:133] op_sel_hi:[1,0]
	v_pk_add_f32 v[98:99], v[98:99], v[132:133] op_sel_hi:[1,0]
	v_pk_add_f32 v[100:101], v[100:101], v[132:133] op_sel_hi:[1,0]
	v_rcp_f32_e32 v8, v8
	v_rcp_f32_e32 v9, v9
	v_rcp_f32_e32 v10, v10
	v_rcp_f32_e32 v11, v11
	v_rcp_f32_e32 v98, v98
	v_rcp_f32_e32 v99, v99
	v_rcp_f32_e32 v100, v100
	v_rcp_f32_e32 v101, v101
	v_pk_mul_f32 v[8:9], v[8:9], v[84:85] op_sel:[0,1]
	v_pk_mul_f32 v[10:11], v[10:11], v[84:85] op_sel:[0,1]
	v_pk_mul_f32 v[98:99], v[98:99], v[170:171]
	v_pk_mul_f32 v[100:101], v[100:101], v[172:173]
	v_exp_f32_e32 v8, v8
	v_exp_f32_e32 v9, v9
	v_exp_f32_e32 v10, v10
	v_exp_f32_e32 v11, v11
	s_nop 0
	v_pk_fma_f32 v[138:139], v[8:9], v[8:9], v[132:133] op_sel_hi:[1,1,0] neg_lo:[1,0,0] neg_hi:[1,0,0]
	v_pk_fma_f32 v[140:141], v[10:11], v[10:11], v[132:133] op_sel_hi:[1,1,0] neg_lo:[1,0,0] neg_hi:[1,0,0]
	v_max_f32_e32 v138, 0, v138
	v_max_f32_e32 v139, 0, v139
	v_max_f32_e32 v140, 0, v140
	v_max_f32_e32 v141, 0, v141
	v_sqrt_f32_e32 v138, v138
	v_sqrt_f32_e32 v139, v139
	v_sqrt_f32_e32 v140, v140
	v_sqrt_f32_e32 v141, v141
	s_nop 0
	v_pk_mul_f32 v[98:99], v[138:139], v[98:99]
	v_pk_mul_f32 v[100:101], v[140:141], v[100:101]
	v_pk_add_f32 v[12:13], v[12:13], v[74:75] op_sel:[0,1]
	v_pk_add_f32 v[14:15], v[14:15], v[74:75] op_sel:[0,1]
	v_pk_add_f32 v[102:103], v[102:103], v[84:85] op_sel_hi:[1,0]
	v_pk_add_f32 v[104:105], v[104:105], v[84:85] op_sel_hi:[1,0]
	v_exp_f32_e32 v12, v12
	v_exp_f32_e32 v13, v13
	v_exp_f32_e32 v14, v14
	v_exp_f32_e32 v15, v15
	v_exp_f32_e32 v102, v102
	v_exp_f32_e32 v103, v103
	v_exp_f32_e32 v104, v104
	v_exp_f32_e32 v105, v105
	v_pk_add_f32 v[12:13], v[12:13], v[132:133] op_sel_hi:[1,0]
	v_pk_add_f32 v[14:15], v[14:15], v[132:133] op_sel_hi:[1,0]
	v_pk_add_f32 v[102:103], v[102:103], v[132:133] op_sel_hi:[1,0]
	v_pk_add_f32 v[104:105], v[104:105], v[132:133] op_sel_hi:[1,0]
	v_rcp_f32_e32 v12, v12
	v_rcp_f32_e32 v13, v13
	v_rcp_f32_e32 v14, v14
	v_rcp_f32_e32 v15, v15
	v_rcp_f32_e32 v102, v102
	v_rcp_f32_e32 v103, v103
	v_rcp_f32_e32 v104, v104
	v_rcp_f32_e32 v105, v105
	v_pk_mul_f32 v[12:13], v[12:13], v[84:85] op_sel:[0,1]
	v_pk_mul_f32 v[14:15], v[14:15], v[84:85] op_sel:[0,1]
	v_pk_mul_f32 v[102:103], v[102:103], v[174:175]
	v_pk_mul_f32 v[104:105], v[104:105], v[176:177]
	v_exp_f32_e32 v12, v12
	v_exp_f32_e32 v13, v13
	v_exp_f32_e32 v14, v14
	v_exp_f32_e32 v15, v15
	s_nop 0
	v_pk_fma_f32 v[138:139], v[12:13], v[12:13], v[132:133] op_sel_hi:[1,1,0] neg_lo:[1,0,0] neg_hi:[1,0,0]
	v_pk_fma_f32 v[140:141], v[14:15], v[14:15], v[132:133] op_sel_hi:[1,1,0] neg_lo:[1,0,0] neg_hi:[1,0,0]
	v_max_f32_e32 v138, 0, v138
	v_max_f32_e32 v139, 0, v139
	v_max_f32_e32 v140, 0, v140
	v_max_f32_e32 v141, 0, v141
	v_sqrt_f32_e32 v138, v138
	v_sqrt_f32_e32 v139, v139
	v_sqrt_f32_e32 v140, v140
	v_sqrt_f32_e32 v141, v141
	s_nop 0
	v_pk_mul_f32 v[102:103], v[138:139], v[102:103]
	v_pk_mul_f32 v[104:105], v[140:141], v[104:105]
	v_pk_add_f32 v[16:17], v[16:17], v[74:75] op_sel:[0,1]
	v_pk_add_f32 v[18:19], v[18:19], v[74:75] op_sel:[0,1]
	v_pk_add_f32 v[106:107], v[106:107], v[84:85] op_sel_hi:[1,0]
	v_pk_add_f32 v[108:109], v[108:109], v[84:85] op_sel_hi:[1,0]
	v_exp_f32_e32 v16, v16
	v_exp_f32_e32 v17, v17
	v_exp_f32_e32 v18, v18
	v_exp_f32_e32 v19, v19
	v_exp_f32_e32 v106, v106
	v_exp_f32_e32 v107, v107
	v_exp_f32_e32 v108, v108
	v_exp_f32_e32 v109, v109
	v_pk_add_f32 v[16:17], v[16:17], v[132:133] op_sel_hi:[1,0]
	v_pk_add_f32 v[18:19], v[18:19], v[132:133] op_sel_hi:[1,0]
	v_pk_add_f32 v[106:107], v[106:107], v[132:133] op_sel_hi:[1,0]
	v_pk_add_f32 v[108:109], v[108:109], v[132:133] op_sel_hi:[1,0]
	v_rcp_f32_e32 v16, v16
	v_rcp_f32_e32 v17, v17
	v_rcp_f32_e32 v18, v18
	v_rcp_f32_e32 v19, v19
	v_rcp_f32_e32 v106, v106
	v_rcp_f32_e32 v107, v107
	v_rcp_f32_e32 v108, v108
	v_rcp_f32_e32 v109, v109
	v_pk_mul_f32 v[16:17], v[16:17], v[84:85] op_sel:[0,1]
	v_pk_mul_f32 v[18:19], v[18:19], v[84:85] op_sel:[0,1]
	v_pk_mul_f32 v[106:107], v[106:107], v[178:179]
	v_pk_mul_f32 v[108:109], v[108:109], v[180:181]
; __device__ __forceinline__ float bf2f(u16 h) { return __uint_as_float(((unsigned)h) << 16); }
; __device__ __forceinline__ void lru_tile(const Params& P, int chunk, int head, int pass, char* smem_raw) {
;     ...
;       for (int tc = 0; tc < 4; ++tc)
; #pragma unroll
;         for (int reg = 0; reg < 4; ++reg) {
;           const int tl = wid * 16 + (lane >> 4) * 4 + reg;
;           const int c = 16 * tc + (lane & 15);
;           const float r = __builtin_amdgcn_rcpf(1.f + __builtin_amdgcn_exp2f(acc[tc][reg] + ba[tc]));
;           const float ii = __builtin_amdgcn_rcpf(1.f + __builtin_amdgcn_exp2f(acc[tc + 4][reg] + bi[tc]));
;           const float la = -c8[tc] * r;
;           const float a = __builtin_amdgcn_exp2f(la);
;           const float ucv = bf2f(sm_uc[(sb * 64 + tl) * LDSS + c]);
;           const float bt = __builtin_amdgcn_sqrtf(fmaxf(1.f - a * a, 0.f)) * (ii * ucv);
;           sm_a[tl * 64 + c] = a;
;           sm_b[tl * 64 + c] = bt;
;         }
	v_exp_f32_e32 v16, v16
	v_exp_f32_e32 v17, v17
	v_exp_f32_e32 v18, v18
	v_exp_f32_e32 v19, v19
	s_nop 0
	v_pk_fma_f32 v[138:139], v[16:17], v[16:17], v[132:133] op_sel_hi:[1,1,0] neg_lo:[1,0,0] neg_hi:[1,0,0]
	v_pk_fma_f32 v[140:141], v[18:19], v[18:19], v[132:133] op_sel_hi:[1,1,0] neg_lo:[1,0,0] neg_hi:[1,0,0]
	v_max_f32_e32 v138, 0, v138
	v_max_f32_e32 v139, 0, v139
	v_max_f32_e32 v140, 0, v140
	v_max_f32_e32 v141, 0, v141
	v_sqrt_f32_e32 v138, v138
	v_sqrt_f32_e32 v139, v139
	v_sqrt_f32_e32 v140, v140
	v_sqrt_f32_e32 v141, v141
	s_nop 0
	v_pk_mul_f32 v[106:107], v[138:139], v[106:107]
	v_pk_mul_f32 v[108:109], v[140:141], v[108:109]
	v_pk_add_f32 v[20:21], v[20:21], v[74:75] op_sel:[0,1]
	v_pk_add_f32 v[22:23], v[22:23], v[74:75] op_sel:[0,1]
	v_pk_add_f32 v[110:111], v[110:111], v[84:85] op_sel_hi:[1,0]
	v_pk_add_f32 v[112:113], v[112:113], v[84:85] op_sel_hi:[1,0]
	v_exp_f32_e32 v20, v20
	v_exp_f32_e32 v21, v21
	v_exp_f32_e32 v22, v22
	v_exp_f32_e32 v23, v23
	v_exp_f32_e32 v110, v110
	v_exp_f32_e32 v111, v111
	v_exp_f32_e32 v112, v112
	v_exp_f32_e32 v113, v113
	v_pk_add_f32 v[20:21], v[20:21], v[132:133] op_sel_hi:[1,0]
	v_pk_add_f32 v[22:23], v[22:23], v[132:133] op_sel_hi:[1,0]
	v_pk_add_f32 v[110:111], v[110:111], v[132:133] op_sel_hi:[1,0]
	v_pk_add_f32 v[112:113], v[112:113], v[132:133] op_sel_hi:[1,0]
	v_rcp_f32_e32 v20, v20
	v_rcp_f32_e32 v21, v21
	v_rcp_f32_e32 v22, v22
	v_rcp_f32_e32 v23, v23
	v_rcp_f32_e32 v110, v110
	v_rcp_f32_e32 v111, v111
	v_rcp_f32_e32 v112, v112
	v_rcp_f32_e32 v113, v113
	v_pk_mul_f32 v[20:21], v[20:21], v[84:85] op_sel:[0,1]
	v_pk_mul_f32 v[22:23], v[22:23], v[84:85] op_sel:[0,1]
	v_pk_mul_f32 v[110:111], v[110:111], v[182:183]
	v_pk_mul_f32 v[112:113], v[112:113], v[184:185]
	v_exp_f32_e32 v20, v20
	v_exp_f32_e32 v21, v21
	v_exp_f32_e32 v22, v22
	v_exp_f32_e32 v23, v23
	s_nop 0
	v_pk_fma_f32 v[138:139], v[20:21], v[20:21], v[132:133] op_sel_hi:[1,1,0] neg_lo:[1,0,0] neg_hi:[1,0,0]
	v_pk_fma_f32 v[140:141], v[22:23], v[22:23], v[132:133] op_sel_hi:[1,1,0] neg_lo:[1,0,0] neg_hi:[1,0,0]
	v_max_f32_e32 v138, 0, v138
	v_max_f32_e32 v139, 0, v139
	v_max_f32_e32 v140, 0, v140
	v_max_f32_e32 v141, 0, v141
	v_sqrt_f32_e32 v138, v138
	v_sqrt_f32_e32 v139, v139
	v_sqrt_f32_e32 v140, v140
	v_sqrt_f32_e32 v141, v141
	s_nop 0
	v_pk_mul_f32 v[110:111], v[138:139], v[110:111]
	v_pk_mul_f32 v[112:113], v[140:141], v[112:113]
	v_pk_add_f32 v[24:25], v[24:25], v[74:75] op_sel:[0,1]
	v_pk_add_f32 v[26:27], v[26:27], v[74:75] op_sel:[0,1]
	v_pk_add_f32 v[114:115], v[114:115], v[84:85] op_sel_hi:[1,0]
	v_pk_add_f32 v[116:117], v[116:117], v[84:85] op_sel_hi:[1,0]
	v_exp_f32_e32 v24, v24
	v_exp_f32_e32 v25, v25
	v_exp_f32_e32 v26, v26
	v_exp_f32_e32 v27, v27
	v_exp_f32_e32 v114, v114
	v_exp_f32_e32 v115, v115
	v_exp_f32_e32 v116, v116
	v_exp_f32_e32 v117, v117
	v_pk_add_f32 v[24:25], v[24:25], v[132:133] op_sel_hi:[1,0]
	v_pk_add_f32 v[26:27], v[26:27], v[132:133] op_sel_hi:[1,0]
	v_pk_add_f32 v[114:115], v[114:115], v[132:133] op_sel_hi:[1,0]
	v_pk_add_f32 v[116:117], v[116:117], v[132:133] op_sel_hi:[1,0]
	v_rcp_f32_e32 v24, v24
	v_rcp_f32_e32 v25, v25
	v_rcp_f32_e32 v26, v26
	v_rcp_f32_e32 v27, v27
	v_rcp_f32_e32 v114, v114
	v_rcp_f32_e32 v115, v115
	v_rcp_f32_e32 v116, v116
	v_rcp_f32_e32 v117, v117
	v_pk_mul_f32 v[24:25], v[24:25], v[84:85] op_sel:[0,1]
	v_pk_mul_f32 v[26:27], v[26:27], v[84:85] op_sel:[0,1]
	v_pk_mul_f32 v[114:115], v[114:115], v[186:187]
	v_pk_mul_f32 v[116:117], v[116:117], v[188:189]
	v_exp_f32_e32 v24, v24
	v_exp_f32_e32 v25, v25
	v_exp_f32_e32 v26, v26
	v_exp_f32_e32 v27, v27
	s_nop 0
	v_pk_fma_f32 v[138:139], v[24:25], v[24:25], v[132:133] op_sel_hi:[1,1,0] neg_lo:[1,0,0] neg_hi:[1,0,0]
	v_pk_fma_f32 v[140:141], v[26:27], v[26:27], v[132:133] op_sel_hi:[1,1,0] neg_lo:[1,0,0] neg_hi:[1,0,0]
	v_max_f32_e32 v138, 0, v138
	v_max_f32_e32 v139, 0, v139
	v_max_f32_e32 v140, 0, v140
	v_max_f32_e32 v141, 0, v141
	v_sqrt_f32_e32 v138, v138
	v_sqrt_f32_e32 v139, v139
	v_sqrt_f32_e32 v140, v140
	v_sqrt_f32_e32 v141, v141
	s_nop 0
	v_pk_mul_f32 v[114:115], v[138:139], v[114:115]
	v_pk_mul_f32 v[116:117], v[140:141], v[116:117]
	v_pk_add_f32 v[28:29], v[28:29], v[74:75] op_sel:[0,1]
	v_pk_add_f32 v[30:31], v[30:31], v[74:75] op_sel:[0,1]
	v_pk_add_f32 v[118:119], v[118:119], v[84:85] op_sel_hi:[1,0]
	v_pk_add_f32 v[120:121], v[120:121], v[84:85] op_sel_hi:[1,0]
	v_exp_f32_e32 v28, v28
	v_exp_f32_e32 v29, v29
	v_exp_f32_e32 v30, v30
	v_exp_f32_e32 v31, v31
	v_exp_f32_e32 v118, v118
	v_exp_f32_e32 v119, v119
	v_exp_f32_e32 v120, v120
	v_exp_f32_e32 v121, v121
	v_pk_add_f32 v[28:29], v[28:29], v[132:133] op_sel_hi:[1,0]
	v_pk_add_f32 v[30:31], v[30:31], v[132:133] op_sel_hi:[1,0]
	v_pk_add_f32 v[118:119], v[118:119], v[132:133] op_sel_hi:[1,0]
	v_pk_add_f32 v[120:121], v[120:121], v[132:133] op_sel_hi:[1,0]
	v_rcp_f32_e32 v28, v28
	v_rcp_f32_e32 v29, v29
	v_rcp_f32_e32 v30, v30
	v_rcp_f32_e32 v31, v31
	v_rcp_f32_e32 v118, v118
	v_rcp_f32_e32 v119, v119
	v_rcp_f32_e32 v120, v120
	v_rcp_f32_e32 v121, v121
	v_pk_mul_f32 v[28:29], v[28:29], v[84:85] op_sel:[0,1]
	v_pk_mul_f32 v[30:31], v[30:31], v[84:85] op_sel:[0,1]
	v_pk_mul_f32 v[118:119], v[118:119], v[190:191]
	v_pk_mul_f32 v[120:121], v[120:121], v[192:193]
	v_exp_f32_e32 v28, v28
	v_exp_f32_e32 v29, v29
	v_exp_f32_e32 v30, v30
	v_exp_f32_e32 v31, v31
	s_nop 0
	v_pk_fma_f32 v[138:139], v[28:29], v[28:29], v[132:133] op_sel_hi:[1,1,0] neg_lo:[1,0,0] neg_hi:[1,0,0]
	v_pk_fma_f32 v[140:141], v[30:31], v[30:31], v[132:133] op_sel_hi:[1,1,0] neg_lo:[1,0,0] neg_hi:[1,0,0]
	v_max_f32_e32 v138, 0, v138
	v_max_f32_e32 v139, 0, v139
	v_max_f32_e32 v140, 0, v140
; __device__ __forceinline__ float bf2f(u16 h) { return __uint_as_float(((unsigned)h) << 16); }
; __device__ __forceinline__ void lru_tile(const Params& P, int chunk, int head, int pass, char* smem_raw) {
;     ...
;           const float r = __builtin_amdgcn_rcpf(1.f + __builtin_amdgcn_exp2f(acc[tc][reg] + ba[tc]));
;           const float ii = __builtin_amdgcn_rcpf(1.f + __builtin_amdgcn_exp2f(acc[tc + 4][reg] + bi[tc]));
;           const float la = -c8[tc] * r;
;           const float a = __builtin_amdgcn_exp2f(la);
;           const float ucv = bf2f(sm_uc[(sb * 64 + tl) * LDSS + c]);
;           const float bt = __builtin_amdgcn_sqrtf(fmaxf(1.f - a * a, 0.f)) * (ii * ucv);
;           sm_a[tl * 64 + c] = a;
;           sm_b[tl * 64 + c] = bt;
;         }
;       __syncthreads();
;       const int pos = (d == 0) ? q : 3 - q;
;       {
;         float Pp = 1.f, H = 0.f;
; #pragma unroll 4
;         for (int i = 0; i < 16; ++i) {
;           const int tl = (d == 0) ? (q * 16 + i) : (q * 16 + 15 - i);
;           const float a = sm_a[tl * 64 + ch], b = sm_b[tl * 64 + ch];
;           H = a * H + b; Pp *= a;
;         }
;         sm_ph[pos * 64 + ch] = make_float2(Pp, H);
;     ...
;       cB = p0.x * cB + p0.y; cA *= p0.x;
;       cB = p1.x * cB + p1.y; cA *= p1.x;
;       cB = p2.x * cB + p2.y; cA *= p2.x;
;       cB = p3.x * cB + p3.y; cA *= p3.x;
;       __syncthreads();
;     }
;     if (pass == 1 && q == 0) P.summ[((long)d * 264 + chunk) * 512 + gch] = make_float2(cA, cB);
	v_max_f32_e32 v141, 0, v141
	v_sqrt_f32_e32 v138, v138
	v_sqrt_f32_e32 v139, v139
	v_sqrt_f32_e32 v140, v140
	v_sqrt_f32_e32 v141, v141
	s_nop 0
	v_pk_mul_f32 v[118:119], v[138:139], v[118:119]
	v_pk_mul_f32 v[120:121], v[140:141], v[120:121]
	v_mov_b32_e32 v253, v0
	v_mov_b32_e32 v254, v90
	v_fma_f32 v254, v1, v254, v91
	v_mul_f32_e32 v253, v253, v1
	v_fma_f32 v254, v2, v254, v92
	v_mul_f32_e32 v253, v253, v2
	v_fma_f32 v254, v3, v254, v93
	v_mul_f32_e32 v253, v253, v3
	v_fma_f32 v254, v4, v254, v94
	v_mul_f32_e32 v253, v253, v4
	v_fma_f32 v254, v5, v254, v95
	v_mul_f32_e32 v253, v253, v5
	v_fma_f32 v254, v6, v254, v96
	v_mul_f32_e32 v253, v253, v6
	v_fma_f32 v254, v7, v254, v97
	v_mul_f32_e32 v253, v253, v7
	v_fma_f32 v254, v8, v254, v98
	v_mul_f32_e32 v253, v253, v8
	v_fma_f32 v254, v9, v254, v99
	v_mul_f32_e32 v253, v253, v9
	v_fma_f32 v254, v10, v254, v100
	v_mul_f32_e32 v253, v253, v10
	v_fma_f32 v254, v11, v254, v101
	v_mul_f32_e32 v253, v253, v11
	v_fma_f32 v254, v12, v254, v102
	v_mul_f32_e32 v253, v253, v12
	v_fma_f32 v254, v13, v254, v103
	v_mul_f32_e32 v253, v253, v13
	v_fma_f32 v254, v14, v254, v104
	v_mul_f32_e32 v253, v253, v14
	v_fma_f32 v254, v15, v254, v105
	v_mul_f32_e32 v253, v253, v15
	v_fma_f32 v254, v16, v254, v106
	v_mul_f32_e32 v253, v253, v16
	v_fma_f32 v254, v17, v254, v107
	v_mul_f32_e32 v253, v253, v17
	v_fma_f32 v254, v18, v254, v108
	v_mul_f32_e32 v253, v253, v18
	v_fma_f32 v254, v19, v254, v109
	v_mul_f32_e32 v253, v253, v19
	v_fma_f32 v254, v20, v254, v110
	v_mul_f32_e32 v253, v253, v20
	v_fma_f32 v254, v21, v254, v111
	v_mul_f32_e32 v253, v253, v21
	v_fma_f32 v254, v22, v254, v112
	v_mul_f32_e32 v253, v253, v22
	v_fma_f32 v254, v23, v254, v113
	v_mul_f32_e32 v253, v253, v23
	v_fma_f32 v254, v24, v254, v114
	v_mul_f32_e32 v253, v253, v24
	v_fma_f32 v254, v25, v254, v115
	v_mul_f32_e32 v253, v253, v25
	v_fma_f32 v254, v26, v254, v116
	v_mul_f32_e32 v253, v253, v26
	v_fma_f32 v254, v27, v254, v117
	v_mul_f32_e32 v253, v253, v27
	v_fma_f32 v254, v28, v254, v118
	v_mul_f32_e32 v253, v253, v28
	v_fma_f32 v254, v29, v254, v119
	v_mul_f32_e32 v253, v253, v29
	v_fma_f32 v254, v30, v254, v120
	v_mul_f32_e32 v253, v253, v30
	v_fma_f32 v254, v31, v254, v121
	v_mul_f32_e32 v253, v253, v31
	v_mov_b32_e32 v138, v253
	v_mov_b32_e32 v139, v253
	s_nop 1
	v_permlane16_swap_b32_e32 v138, v139
	v_mov_b32_e32 v140, v138
	v_mov_b32_e32 v141, v139
	s_nop 1
	v_permlane32_swap_b32_e32 v138, v140
	v_permlane32_swap_b32_e32 v139, v141
	v_mov_b32_e32 v198, v254
	v_mov_b32_e32 v199, v254
	s_nop 1
	v_permlane16_swap_b32_e32 v198, v199
	v_mov_b32_e32 v200, v198
	v_mov_b32_e32 v201, v199
	s_nop 1
	v_permlane32_swap_b32_e32 v198, v200
	v_permlane32_swap_b32_e32 v199, v201
	v_mov_b32_e32 v136, 0
	v_fma_f32 v150, v138, v136, v198
	v_fma_f32 v151, v139, v150, v199
	v_fma_f32 v202, v140, v151, v200
	v_fma_f32 v254, v141, v202, v201
	v_mul_f32_e32 v253, v138, v139
	v_mul_f32_e32 v253, v253, v140
	v_mul_f32_e32 v200, v253, v141
	v_mov_b32_e32 v201, v254
	s_add_u32 s0, s71, 0
	s_lshl_b32 s0, s0, 12
	s_lshl_b32 s1, s56, 3
	s_add_u32 s0, s0, s1
	s_add_u32 s4, s18, s0
	s_addc_u32 s5, s19, 0
	global_store_dwordx2 v250, v[200:201], s[4:5]
	ds_read_b128 v[76:79], v131 offset:0
	ds_read_b128 v[80:83], v133 offset:0
	ds_read_b128 v[122:125], v131 offset:512
	ds_read_b128 v[126:129], v133 offset:512
	s_waitcnt vmcnt(1)
	s_waitcnt lgkmcnt(3)
	v_mfma_f32_16x16x32_bf16 v[0:3], v[76:79], v[238:241], 0
	v_mfma_f32_16x16x32_bf16 v[90:93], v[76:79], v[246:249], 0
	ds_read_b128 v[76:79], v131 offset:1024
	s_waitcnt lgkmcnt(3)
	v_mfma_f32_16x16x32_bf16 v[0:3], v[80:83], v[242:245], v[0:3]
	v_mfma_f32_16x16x32_bf16 v[90:93], v[80:83], v[194:197], v[90:93]
	ds_read_b128 v[80:83], v133 offset:1024
	s_waitcnt lgkmcnt(3)
	v_mfma_f32_16x16x32_bf16 v[4:7], v[122:125], v[238:241], 0
	v_mfma_f32_16x16x32_bf16 v[94:97], v[122:125], v[246:249], 0
	ds_read_b128 v[122:125], v131 offset:1536
	s_waitcnt lgkmcnt(3)
	v_mfma_f32_16x16x32_bf16 v[4:7], v[126:129], v[242:245], v[4:7]
	v_mfma_f32_16x16x32_bf16 v[94:97], v[126:129], v[194:197], v[94:97]
	ds_read_b128 v[126:129], v133 offset:1536
	s_waitcnt lgkmcnt(3)
	v_mfma_f32_16x16x32_bf16 v[8:11], v[76:79], v[238:241], 0
	v_mfma_f32_16x16x32_bf16 v[98:101], v[76:79], v[246:249], 0
	ds_read_b128 v[76:79], v131 offset:2048
	s_waitcnt lgkmcnt(3)
	v_mfma_f32_16x16x32_bf16 v[8:11], v[80:83], v[242:245], v[8:11]
	v_mfma_f32_16x16x32_bf16 v[98:101], v[80:83], v[194:197], v[98:101]
	ds_read_b128 v[80:83], v133 offset:2048
	s_waitcnt lgkmcnt(3)
	v_mfma_f32_16x16x32_bf16 v[12:15], v[122:125], v[238:241], 0
	v_mfma_f32_16x16x32_bf16 v[102:105], v[122:125], v[246:249], 0
	ds_read_b128 v[122:125], v131 offset:2560
	s_waitcnt lgkmcnt(3)
	v_mfma_f32_16x16x32_bf16 v[12:15], v[126:129], v[242:245], v[12:15]
	v_mfma_f32_16x16x32_bf16 v[102:105], v[126:129], v[194:197], v[102:105]
	ds_read_b128 v[126:129], v133 offset:2560
	s_waitcnt lgkmcnt(3)
	v_mfma_f32_16x16x32_bf16 v[16:19], v[76:79], v[238:241], 0
	v_mfma_f32_16x16x32_bf16 v[106:109], v[76:79], v[246:249], 0
	ds_read_b128 v[76:79], v131 offset:3072
	s_waitcnt lgkmcnt(3)
	v_mfma_f32_16x16x32_bf16 v[16:19], v[80:83], v[242:245], v[16:19]
	v_mfma_f32_16x16x32_bf16 v[106:109], v[80:83], v[194:197], v[106:109]
	ds_read_b128 v[80:83], v133 offset:3072
	s_waitcnt lgkmcnt(3)
	v_mfma_f32_16x16x32_bf16 v[20:23], v[122:125], v[238:241], 0
	v_mfma_f32_16x16x32_bf16 v[110:113], v[122:125], v[246:249], 0
	ds_read_b128 v[122:125], v131 offset:3584
	s_waitcnt lgkmcnt(3)
	v_mfma_f32_16x16x32_bf16 v[20:23], v[126:129], v[242:245], v[20:23]
	v_mfma_f32_16x16x32_bf16 v[110:113], v[126:129], v[194:197], v[110:113]
	ds_read_b128 v[126:129], v133 offset:3584
	s_waitcnt lgkmcnt(3)
; __device__ __forceinline__ float bf2f(u16 h) { return __uint_as_float(((unsigned)h) << 16); }
; __device__ __forceinline__ void lru_tile(const Params& P, int chunk, int head, int pass, char* smem_raw) {
;     ...
;       for (int s = 0; s < 2; ++s) {
;         const bf16x8 af = *reinterpret_cast<const bf16x8*>(&sm_uc[(sb * 64 + wid * 16 + (lane & 15)) * LDSS + s * 32 + (lane >> 4) * 8]);
; #pragma unroll
;         for (int t = 0; t < 8; ++t) {
;           const bf16x8 bfr = *reinterpret_cast<const bf16x8*>(&sm_w[(t * 16 + (lane & 15)) * LDSS + s * 32 + (lane >> 4) * 8]);
;           acc[t] = __builtin_amdgcn_mfma_f32_16x16x32_bf16(af, bfr, acc[t], 0, 0, 0);
;         }
;       }
; #pragma unroll
;       for (int tc = 0; tc < 4; ++tc)
; #pragma unroll
;         for (int reg = 0; reg < 4; ++reg) {
;           const int tl = wid * 16 + (lane >> 4) * 4 + reg;
;           const int c = 16 * tc + (lane & 15);
;           const float r = __builtin_amdgcn_rcpf(1.f + __builtin_amdgcn_exp2f(acc[tc][reg] + ba[tc]));
;           const float ii = __builtin_amdgcn_rcpf(1.f + __builtin_amdgcn_exp2f(acc[tc + 4][reg] + bi[tc]));
;           const float la = -c8[tc] * r;
;           const float a = __builtin_amdgcn_exp2f(la);
;           const float ucv = bf2f(sm_uc[(sb * 64 + tl) * LDSS + c]);
;           const float bt = __builtin_amdgcn_sqrtf(fmaxf(1.f - a * a, 0.f)) * (ii * ucv);
;           sm_a[tl * 64 + c] = a;
;           sm_b[tl * 64 + c] = bt;
;         }
	v_mfma_f32_16x16x32_bf16 v[24:27], v[76:79], v[238:241], 0
	v_mfma_f32_16x16x32_bf16 v[114:117], v[76:79], v[246:249], 0
	s_waitcnt lgkmcnt(2)
	v_mfma_f32_16x16x32_bf16 v[24:27], v[80:83], v[242:245], v[24:27]
	v_mfma_f32_16x16x32_bf16 v[114:117], v[80:83], v[194:197], v[114:117]
	s_waitcnt lgkmcnt(1)
	v_mfma_f32_16x16x32_bf16 v[28:31], v[122:125], v[238:241], 0
	v_mfma_f32_16x16x32_bf16 v[118:121], v[122:125], v[246:249], 0
	s_waitcnt lgkmcnt(0)
	v_mfma_f32_16x16x32_bf16 v[28:31], v[126:129], v[242:245], v[28:31]
	v_mfma_f32_16x16x32_bf16 v[118:121], v[126:129], v[194:197], v[118:121]
	s_lshl_b32 s0, s56, 8
	s_add_u32 s0, s0, 0x0
	s_add_u32 s4, s20, s0
	s_addc_u32 s5, s21, 0
	global_load_dwordx4 v[238:241], v251, s[4:5]
	global_load_dwordx4 v[242:245], v251, s[4:5] offset:64
	s_add_u32 s4, s4, 0x2000
	s_addc_u32 s5, s5, 0
	global_load_dwordx4 v[246:249], v251, s[4:5]
	global_load_dwordx4 v[194:197], v251, s[4:5] offset:64
	s_nop 7
	s_nop 7
	v_pk_add_f32 v[0:1], v[0:1], v[144:145] op_sel:[0,1]
	v_pk_add_f32 v[2:3], v[2:3], v[144:145] op_sel:[0,1]
	v_pk_add_f32 v[90:91], v[90:91], v[146:147] op_sel_hi:[1,0]
	v_pk_add_f32 v[92:93], v[92:93], v[146:147] op_sel_hi:[1,0]
	v_exp_f32_e32 v0, v0
	v_exp_f32_e32 v1, v1
	v_exp_f32_e32 v2, v2
	v_exp_f32_e32 v3, v3
	v_exp_f32_e32 v90, v90
	v_exp_f32_e32 v91, v91
	v_exp_f32_e32 v92, v92
	v_exp_f32_e32 v93, v93
	v_pk_add_f32 v[0:1], v[0:1], v[132:133] op_sel_hi:[1,0]
	v_pk_add_f32 v[2:3], v[2:3], v[132:133] op_sel_hi:[1,0]
	v_pk_add_f32 v[90:91], v[90:91], v[132:133] op_sel_hi:[1,0]
	v_pk_add_f32 v[92:93], v[92:93], v[132:133] op_sel_hi:[1,0]
	v_rcp_f32_e32 v0, v0
	v_rcp_f32_e32 v1, v1
	v_rcp_f32_e32 v2, v2
	v_rcp_f32_e32 v3, v3
	v_rcp_f32_e32 v90, v90
	v_rcp_f32_e32 v91, v91
	v_rcp_f32_e32 v92, v92
	v_rcp_f32_e32 v93, v93
	v_pk_mul_f32 v[0:1], v[0:1], v[146:147] op_sel:[0,1]
	v_pk_mul_f32 v[2:3], v[2:3], v[146:147] op_sel:[0,1]
	v_pk_mul_f32 v[90:91], v[90:91], v[162:163]
	v_pk_mul_f32 v[92:93], v[92:93], v[164:165]
	v_exp_f32_e32 v0, v0
	v_exp_f32_e32 v1, v1
	v_exp_f32_e32 v2, v2
	v_exp_f32_e32 v3, v3
	s_nop 0
	v_pk_fma_f32 v[138:139], v[0:1], v[0:1], v[132:133] op_sel_hi:[1,1,0] neg_lo:[1,0,0] neg_hi:[1,0,0]
	v_pk_fma_f32 v[140:141], v[2:3], v[2:3], v[132:133] op_sel_hi:[1,1,0] neg_lo:[1,0,0] neg_hi:[1,0,0]
	v_max_f32_e32 v138, 0, v138
	v_max_f32_e32 v139, 0, v139
	v_max_f32_e32 v140, 0, v140
	v_max_f32_e32 v141, 0, v141
	v_sqrt_f32_e32 v138, v138
	v_sqrt_f32_e32 v139, v139
	v_sqrt_f32_e32 v140, v140
	v_sqrt_f32_e32 v141, v141
	s_nop 0
	v_pk_mul_f32 v[90:91], v[138:139], v[90:91]
	v_pk_mul_f32 v[92:93], v[140:141], v[92:93]
	v_pk_add_f32 v[4:5], v[4:5], v[144:145] op_sel:[0,1]
	v_pk_add_f32 v[6:7], v[6:7], v[144:145] op_sel:[0,1]
	v_pk_add_f32 v[94:95], v[94:95], v[146:147] op_sel_hi:[1,0]
	v_pk_add_f32 v[96:97], v[96:97], v[146:147] op_sel_hi:[1,0]
	v_exp_f32_e32 v4, v4
	v_exp_f32_e32 v5, v5
	v_exp_f32_e32 v6, v6
	v_exp_f32_e32 v7, v7
	v_exp_f32_e32 v94, v94
	v_exp_f32_e32 v95, v95
	v_exp_f32_e32 v96, v96
	v_exp_f32_e32 v97, v97
	v_pk_add_f32 v[4:5], v[4:5], v[132:133] op_sel_hi:[1,0]
	v_pk_add_f32 v[6:7], v[6:7], v[132:133] op_sel_hi:[1,0]
	v_pk_add_f32 v[94:95], v[94:95], v[132:133] op_sel_hi:[1,0]
	v_pk_add_f32 v[96:97], v[96:97], v[132:133] op_sel_hi:[1,0]
	v_rcp_f32_e32 v4, v4
	v_rcp_f32_e32 v5, v5
	v_rcp_f32_e32 v6, v6
	v_rcp_f32_e32 v7, v7
	v_rcp_f32_e32 v94, v94
	v_rcp_f32_e32 v95, v95
	v_rcp_f32_e32 v96, v96
	v_rcp_f32_e32 v97, v97
	v_pk_mul_f32 v[4:5], v[4:5], v[146:147] op_sel:[0,1]
	v_pk_mul_f32 v[6:7], v[6:7], v[146:147] op_sel:[0,1]
	v_pk_mul_f32 v[94:95], v[94:95], v[166:167]
	v_pk_mul_f32 v[96:97], v[96:97], v[168:169]
	v_exp_f32_e32 v4, v4
	v_exp_f32_e32 v5, v5
	v_exp_f32_e32 v6, v6
	v_exp_f32_e32 v7, v7
	s_nop 0
	v_pk_fma_f32 v[138:139], v[4:5], v[4:5], v[132:133] op_sel_hi:[1,1,0] neg_lo:[1,0,0] neg_hi:[1,0,0]
	v_pk_fma_f32 v[140:141], v[6:7], v[6:7], v[132:133] op_sel_hi:[1,1,0] neg_lo:[1,0,0] neg_hi:[1,0,0]
	v_max_f32_e32 v138, 0, v138
	v_max_f32_e32 v139, 0, v139
	v_max_f32_e32 v140, 0, v140
	v_max_f32_e32 v141, 0, v141
	v_sqrt_f32_e32 v138, v138
	v_sqrt_f32_e32 v139, v139
	v_sqrt_f32_e32 v140, v140
	v_sqrt_f32_e32 v141, v141
	s_nop 0
	v_pk_mul_f32 v[94:95], v[138:139], v[94:95]
	v_pk_mul_f32 v[96:97], v[140:141], v[96:97]
	v_pk_add_f32 v[8:9], v[8:9], v[144:145] op_sel:[0,1]
	v_pk_add_f32 v[10:11], v[10:11], v[144:145] op_sel:[0,1]
	v_pk_add_f32 v[98:99], v[98:99], v[146:147] op_sel_hi:[1,0]
	v_pk_add_f32 v[100:101], v[100:101], v[146:147] op_sel_hi:[1,0]
	v_exp_f32_e32 v8, v8
	v_exp_f32_e32 v9, v9
	v_exp_f32_e32 v10, v10
	v_exp_f32_e32 v11, v11
	v_exp_f32_e32 v98, v98
	v_exp_f32_e32 v99, v99
	v_exp_f32_e32 v100, v100
	v_exp_f32_e32 v101, v101
	v_pk_add_f32 v[8:9], v[8:9], v[132:133] op_sel_hi:[1,0]
	v_pk_add_f32 v[10:11], v[10:11], v[132:133] op_sel_hi:[1,0]
	v_pk_add_f32 v[98:99], v[98:99], v[132:133] op_sel_hi:[1,0]
	v_pk_add_f32 v[100:101], v[100:101], v[132:133] op_sel_hi:[1,0]
	v_rcp_f32_e32 v8, v8
	v_rcp_f32_e32 v9, v9
	v_rcp_f32_e32 v10, v10
	v_rcp_f32_e32 v11, v11
	v_rcp_f32_e32 v98, v98
	v_rcp_f32_e32 v99, v99
	v_rcp_f32_e32 v100, v100
	v_rcp_f32_e32 v101, v101
	v_pk_mul_f32 v[8:9], v[8:9], v[146:147] op_sel:[0,1]
	v_pk_mul_f32 v[10:11], v[10:11], v[146:147] op_sel:[0,1]
	v_pk_mul_f32 v[98:99], v[98:99], v[170:171]
	v_pk_mul_f32 v[100:101], v[100:101], v[172:173]
	v_exp_f32_e32 v8, v8
	v_exp_f32_e32 v9, v9
	v_exp_f32_e32 v10, v10
	v_exp_f32_e32 v11, v11
	s_nop 0
	v_pk_fma_f32 v[138:139], v[8:9], v[8:9], v[132:133] op_sel_hi:[1,1,0] neg_lo:[1,0,0] neg_hi:[1,0,0]
	v_pk_fma_f32 v[140:141], v[10:11], v[10:11], v[132:133] op_sel_hi:[1,1,0] neg_lo:[1,0,0] neg_hi:[1,0,0]
; __device__ __forceinline__ float bf2f(u16 h) { return __uint_as_float(((unsigned)h) << 16); }
; __device__ __forceinline__ void lru_tile(const Params& P, int chunk, int head, int pass, char* smem_raw) {
;     ...
;       for (int tc = 0; tc < 4; ++tc)
; #pragma unroll
;         for (int reg = 0; reg < 4; ++reg) {
;           const int tl = wid * 16 + (lane >> 4) * 4 + reg;
;           const int c = 16 * tc + (lane & 15);
;           const float r = __builtin_amdgcn_rcpf(1.f + __builtin_amdgcn_exp2f(acc[tc][reg] + ba[tc]));
;           const float ii = __builtin_amdgcn_rcpf(1.f + __builtin_amdgcn_exp2f(acc[tc + 4][reg] + bi[tc]));
;           const float la = -c8[tc] * r;
;           const float a = __builtin_amdgcn_exp2f(la);
;           const float ucv = bf2f(sm_uc[(sb * 64 + tl) * LDSS + c]);
;           const float bt = __builtin_amdgcn_sqrtf(fmaxf(1.f - a * a, 0.f)) * (ii * ucv);
;           sm_a[tl * 64 + c] = a;
;           sm_b[tl * 64 + c] = bt;
;         }
	v_max_f32_e32 v138, 0, v138
	v_max_f32_e32 v139, 0, v139
	v_max_f32_e32 v140, 0, v140
	v_max_f32_e32 v141, 0, v141
	v_sqrt_f32_e32 v138, v138
	v_sqrt_f32_e32 v139, v139
	v_sqrt_f32_e32 v140, v140
	v_sqrt_f32_e32 v141, v141
	s_nop 0
	v_pk_mul_f32 v[98:99], v[138:139], v[98:99]
	v_pk_mul_f32 v[100:101], v[140:141], v[100:101]
	v_pk_add_f32 v[12:13], v[12:13], v[144:145] op_sel:[0,1]
	v_pk_add_f32 v[14:15], v[14:15], v[144:145] op_sel:[0,1]
	v_pk_add_f32 v[102:103], v[102:103], v[146:147] op_sel_hi:[1,0]
	v_pk_add_f32 v[104:105], v[104:105], v[146:147] op_sel_hi:[1,0]
	v_exp_f32_e32 v12, v12
	v_exp_f32_e32 v13, v13
	v_exp_f32_e32 v14, v14
	v_exp_f32_e32 v15, v15
	v_exp_f32_e32 v102, v102
	v_exp_f32_e32 v103, v103
	v_exp_f32_e32 v104, v104
	v_exp_f32_e32 v105, v105
	v_pk_add_f32 v[12:13], v[12:13], v[132:133] op_sel_hi:[1,0]
	v_pk_add_f32 v[14:15], v[14:15], v[132:133] op_sel_hi:[1,0]
	v_pk_add_f32 v[102:103], v[102:103], v[132:133] op_sel_hi:[1,0]
	v_pk_add_f32 v[104:105], v[104:105], v[132:133] op_sel_hi:[1,0]
	v_rcp_f32_e32 v12, v12
	v_rcp_f32_e32 v13, v13
	v_rcp_f32_e32 v14, v14
	v_rcp_f32_e32 v15, v15
	v_rcp_f32_e32 v102, v102
	v_rcp_f32_e32 v103, v103
	v_rcp_f32_e32 v104, v104
	v_rcp_f32_e32 v105, v105
	v_pk_mul_f32 v[12:13], v[12:13], v[146:147] op_sel:[0,1]
	v_pk_mul_f32 v[14:15], v[14:15], v[146:147] op_sel:[0,1]
	v_pk_mul_f32 v[102:103], v[102:103], v[174:175]
	v_pk_mul_f32 v[104:105], v[104:105], v[176:177]
	v_exp_f32_e32 v12, v12
	v_exp_f32_e32 v13, v13
	v_exp_f32_e32 v14, v14
	v_exp_f32_e32 v15, v15
	s_nop 0
	v_pk_fma_f32 v[138:139], v[12:13], v[12:13], v[132:133] op_sel_hi:[1,1,0] neg_lo:[1,0,0] neg_hi:[1,0,0]
	v_pk_fma_f32 v[140:141], v[14:15], v[14:15], v[132:133] op_sel_hi:[1,1,0] neg_lo:[1,0,0] neg_hi:[1,0,0]
	v_max_f32_e32 v138, 0, v138
	v_max_f32_e32 v139, 0, v139
	v_max_f32_e32 v140, 0, v140
	v_max_f32_e32 v141, 0, v141
	v_sqrt_f32_e32 v138, v138
	v_sqrt_f32_e32 v139, v139
	v_sqrt_f32_e32 v140, v140
	v_sqrt_f32_e32 v141, v141
	s_nop 0
	v_pk_mul_f32 v[102:103], v[138:139], v[102:103]
	v_pk_mul_f32 v[104:105], v[140:141], v[104:105]
	v_pk_add_f32 v[16:17], v[16:17], v[144:145] op_sel:[0,1]
	v_pk_add_f32 v[18:19], v[18:19], v[144:145] op_sel:[0,1]
	v_pk_add_f32 v[106:107], v[106:107], v[146:147] op_sel_hi:[1,0]
	v_pk_add_f32 v[108:109], v[108:109], v[146:147] op_sel_hi:[1,0]
	v_exp_f32_e32 v16, v16
	v_exp_f32_e32 v17, v17
	v_exp_f32_e32 v18, v18
	v_exp_f32_e32 v19, v19
	v_exp_f32_e32 v106, v106
	v_exp_f32_e32 v107, v107
	v_exp_f32_e32 v108, v108
	v_exp_f32_e32 v109, v109
	v_pk_add_f32 v[16:17], v[16:17], v[132:133] op_sel_hi:[1,0]
	v_pk_add_f32 v[18:19], v[18:19], v[132:133] op_sel_hi:[1,0]
	v_pk_add_f32 v[106:107], v[106:107], v[132:133] op_sel_hi:[1,0]
	v_pk_add_f32 v[108:109], v[108:109], v[132:133] op_sel_hi:[1,0]
	v_rcp_f32_e32 v16, v16
	v_rcp_f32_e32 v17, v17
	v_rcp_f32_e32 v18, v18
	v_rcp_f32_e32 v19, v19
	v_rcp_f32_e32 v106, v106
	v_rcp_f32_e32 v107, v107
	v_rcp_f32_e32 v108, v108
	v_rcp_f32_e32 v109, v109
	v_pk_mul_f32 v[16:17], v[16:17], v[146:147] op_sel:[0,1]
	v_pk_mul_f32 v[18:19], v[18:19], v[146:147] op_sel:[0,1]
	v_pk_mul_f32 v[106:107], v[106:107], v[178:179]
	v_pk_mul_f32 v[108:109], v[108:109], v[180:181]
	v_exp_f32_e32 v16, v16
	v_exp_f32_e32 v17, v17
	v_exp_f32_e32 v18, v18
	v_exp_f32_e32 v19, v19
	s_nop 0
	v_pk_fma_f32 v[138:139], v[16:17], v[16:17], v[132:133] op_sel_hi:[1,1,0] neg_lo:[1,0,0] neg_hi:[1,0,0]
	v_pk_fma_f32 v[140:141], v[18:19], v[18:19], v[132:133] op_sel_hi:[1,1,0] neg_lo:[1,0,0] neg_hi:[1,0,0]
	v_max_f32_e32 v138, 0, v138
	v_max_f32_e32 v139, 0, v139
	v_max_f32_e32 v140, 0, v140
	v_max_f32_e32 v141, 0, v141
	v_sqrt_f32_e32 v138, v138
	v_sqrt_f32_e32 v139, v139
	v_sqrt_f32_e32 v140, v140
	v_sqrt_f32_e32 v141, v141
	s_nop 0
	v_pk_mul_f32 v[106:107], v[138:139], v[106:107]
	v_pk_mul_f32 v[108:109], v[140:141], v[108:109]
	v_pk_add_f32 v[20:21], v[20:21], v[144:145] op_sel:[0,1]
	v_pk_add_f32 v[22:23], v[22:23], v[144:145] op_sel:[0,1]
	v_pk_add_f32 v[110:111], v[110:111], v[146:147] op_sel_hi:[1,0]
	v_pk_add_f32 v[112:113], v[112:113], v[146:147] op_sel_hi:[1,0]
	v_exp_f32_e32 v20, v20
	v_exp_f32_e32 v21, v21
	v_exp_f32_e32 v22, v22
	v_exp_f32_e32 v23, v23
	v_exp_f32_e32 v110, v110
	v_exp_f32_e32 v111, v111
	v_exp_f32_e32 v112, v112
	v_exp_f32_e32 v113, v113
	v_pk_add_f32 v[20:21], v[20:21], v[132:133] op_sel_hi:[1,0]
	v_pk_add_f32 v[22:23], v[22:23], v[132:133] op_sel_hi:[1,0]
	v_pk_add_f32 v[110:111], v[110:111], v[132:133] op_sel_hi:[1,0]
	v_pk_add_f32 v[112:113], v[112:113], v[132:133] op_sel_hi:[1,0]
	v_rcp_f32_e32 v20, v20
	v_rcp_f32_e32 v21, v21
	v_rcp_f32_e32 v22, v22
	v_rcp_f32_e32 v23, v23
	v_rcp_f32_e32 v110, v110
	v_rcp_f32_e32 v111, v111
	v_rcp_f32_e32 v112, v112
	v_rcp_f32_e32 v113, v113
	v_pk_mul_f32 v[20:21], v[20:21], v[146:147] op_sel:[0,1]
	v_pk_mul_f32 v[22:23], v[22:23], v[146:147] op_sel:[0,1]
	v_pk_mul_f32 v[110:111], v[110:111], v[182:183]
	v_pk_mul_f32 v[112:113], v[112:113], v[184:185]
	v_exp_f32_e32 v20, v20
	v_exp_f32_e32 v21, v21
	v_exp_f32_e32 v22, v22
	v_exp_f32_e32 v23, v23
	s_nop 0
	v_pk_fma_f32 v[138:139], v[20:21], v[20:21], v[132:133] op_sel_hi:[1,1,0] neg_lo:[1,0,0] neg_hi:[1,0,0]
	v_pk_fma_f32 v[140:141], v[22:23], v[22:23], v[132:133] op_sel_hi:[1,1,0] neg_lo:[1,0,0] neg_hi:[1,0,0]
	v_max_f32_e32 v138, 0, v138
	v_max_f32_e32 v139, 0, v139
	v_max_f32_e32 v140, 0, v140
	v_max_f32_e32 v141, 0, v141
	v_sqrt_f32_e32 v138, v138
	v_sqrt_f32_e32 v139, v139
	v_sqrt_f32_e32 v140, v140
	v_sqrt_f32_e32 v141, v141
	s_nop 0
	v_pk_mul_f32 v[110:111], v[138:139], v[110:111]
	v_pk_mul_f32 v[112:113], v[140:141], v[112:113]
	v_pk_add_f32 v[24:25], v[24:25], v[144:145] op_sel:[0,1]
; __device__ __forceinline__ float bf2f(u16 h) { return __uint_as_float(((unsigned)h) << 16); }
; __device__ __forceinline__ void lru_tile(const Params& P, int chunk, int head, int pass, char* smem_raw) {
;     ...
;       for (int tc = 0; tc < 4; ++tc)
; #pragma unroll
;         for (int reg = 0; reg < 4; ++reg) {
;           const int tl = wid * 16 + (lane >> 4) * 4 + reg;
;           const int c = 16 * tc + (lane & 15);
;           const float r = __builtin_amdgcn_rcpf(1.f + __builtin_amdgcn_exp2f(acc[tc][reg] + ba[tc]));
;           const float ii = __builtin_amdgcn_rcpf(1.f + __builtin_amdgcn_exp2f(acc[tc + 4][reg] + bi[tc]));
;           const float la = -c8[tc] * r;
;           const float a = __builtin_amdgcn_exp2f(la);
;           const float ucv = bf2f(sm_uc[(sb * 64 + tl) * LDSS + c]);
;           const float bt = __builtin_amdgcn_sqrtf(fmaxf(1.f - a * a, 0.f)) * (ii * ucv);
;           sm_a[tl * 64 + c] = a;
;           sm_b[tl * 64 + c] = bt;
;         }
;       __syncthreads();
;       const int pos = (d == 0) ? q : 3 - q;
;       {
;         float Pp = 1.f, H = 0.f;
; #pragma unroll 4
;         for (int i = 0; i < 16; ++i) {
;           const int tl = (d == 0) ? (q * 16 + i) : (q * 16 + 15 - i);
;           const float a = sm_a[tl * 64 + ch], b = sm_b[tl * 64 + ch];
;           H = a * H + b; Pp *= a;
;         }
;         sm_ph[pos * 64 + ch] = make_float2(Pp, H);
;     ...
;       cB = p0.x * cB + p0.y; cA *= p0.x;
;       cB = p1.x * cB + p1.y; cA *= p1.x;
;       cB = p2.x * cB + p2.y; cA *= p2.x;
;       cB = p3.x * cB + p3.y; cA *= p3.x;
;       __syncthreads();
;     }
;     if (pass == 1 && q == 0) P.summ[((long)d * 264 + chunk) * 512 + gch] = make_float2(cA, cB);
	v_pk_add_f32 v[26:27], v[26:27], v[144:145] op_sel:[0,1]
	v_pk_add_f32 v[114:115], v[114:115], v[146:147] op_sel_hi:[1,0]
	v_pk_add_f32 v[116:117], v[116:117], v[146:147] op_sel_hi:[1,0]
	v_exp_f32_e32 v24, v24
	v_exp_f32_e32 v25, v25
	v_exp_f32_e32 v26, v26
	v_exp_f32_e32 v27, v27
	v_exp_f32_e32 v114, v114
	v_exp_f32_e32 v115, v115
	v_exp_f32_e32 v116, v116
	v_exp_f32_e32 v117, v117
	v_pk_add_f32 v[24:25], v[24:25], v[132:133] op_sel_hi:[1,0]
	v_pk_add_f32 v[26:27], v[26:27], v[132:133] op_sel_hi:[1,0]
	v_pk_add_f32 v[114:115], v[114:115], v[132:133] op_sel_hi:[1,0]
	v_pk_add_f32 v[116:117], v[116:117], v[132:133] op_sel_hi:[1,0]
	v_rcp_f32_e32 v24, v24
	v_rcp_f32_e32 v25, v25
	v_rcp_f32_e32 v26, v26
	v_rcp_f32_e32 v27, v27
	v_rcp_f32_e32 v114, v114
	v_rcp_f32_e32 v115, v115
	v_rcp_f32_e32 v116, v116
	v_rcp_f32_e32 v117, v117
	v_pk_mul_f32 v[24:25], v[24:25], v[146:147] op_sel:[0,1]
	v_pk_mul_f32 v[26:27], v[26:27], v[146:147] op_sel:[0,1]
	v_pk_mul_f32 v[114:115], v[114:115], v[186:187]
	v_pk_mul_f32 v[116:117], v[116:117], v[188:189]
	v_exp_f32_e32 v24, v24
	v_exp_f32_e32 v25, v25
	v_exp_f32_e32 v26, v26
	v_exp_f32_e32 v27, v27
	s_nop 0
	v_pk_fma_f32 v[138:139], v[24:25], v[24:25], v[132:133] op_sel_hi:[1,1,0] neg_lo:[1,0,0] neg_hi:[1,0,0]
	v_pk_fma_f32 v[140:141], v[26:27], v[26:27], v[132:133] op_sel_hi:[1,1,0] neg_lo:[1,0,0] neg_hi:[1,0,0]
	v_max_f32_e32 v138, 0, v138
	v_max_f32_e32 v139, 0, v139
	v_max_f32_e32 v140, 0, v140
	v_max_f32_e32 v141, 0, v141
	v_sqrt_f32_e32 v138, v138
	v_sqrt_f32_e32 v139, v139
	v_sqrt_f32_e32 v140, v140
	v_sqrt_f32_e32 v141, v141
	s_nop 0
	v_pk_mul_f32 v[114:115], v[138:139], v[114:115]
	v_pk_mul_f32 v[116:117], v[140:141], v[116:117]
	v_pk_add_f32 v[28:29], v[28:29], v[144:145] op_sel:[0,1]
	v_pk_add_f32 v[30:31], v[30:31], v[144:145] op_sel:[0,1]
	v_pk_add_f32 v[118:119], v[118:119], v[146:147] op_sel_hi:[1,0]
	v_pk_add_f32 v[120:121], v[120:121], v[146:147] op_sel_hi:[1,0]
	v_exp_f32_e32 v28, v28
	v_exp_f32_e32 v29, v29
	v_exp_f32_e32 v30, v30
	v_exp_f32_e32 v31, v31
	v_exp_f32_e32 v118, v118
	v_exp_f32_e32 v119, v119
	v_exp_f32_e32 v120, v120
	v_exp_f32_e32 v121, v121
	v_pk_add_f32 v[28:29], v[28:29], v[132:133] op_sel_hi:[1,0]
	v_pk_add_f32 v[30:31], v[30:31], v[132:133] op_sel_hi:[1,0]
	v_pk_add_f32 v[118:119], v[118:119], v[132:133] op_sel_hi:[1,0]
	v_pk_add_f32 v[120:121], v[120:121], v[132:133] op_sel_hi:[1,0]
	v_rcp_f32_e32 v28, v28
	v_rcp_f32_e32 v29, v29
	v_rcp_f32_e32 v30, v30
	v_rcp_f32_e32 v31, v31
	v_rcp_f32_e32 v118, v118
	v_rcp_f32_e32 v119, v119
	v_rcp_f32_e32 v120, v120
	v_rcp_f32_e32 v121, v121
	v_pk_mul_f32 v[28:29], v[28:29], v[146:147] op_sel:[0,1]
	v_pk_mul_f32 v[30:31], v[30:31], v[146:147] op_sel:[0,1]
	v_pk_mul_f32 v[118:119], v[118:119], v[190:191]
	v_pk_mul_f32 v[120:121], v[120:121], v[192:193]
	v_exp_f32_e32 v28, v28
	v_exp_f32_e32 v29, v29
	v_exp_f32_e32 v30, v30
	v_exp_f32_e32 v31, v31
	s_nop 0
	v_pk_fma_f32 v[138:139], v[28:29], v[28:29], v[132:133] op_sel_hi:[1,1,0] neg_lo:[1,0,0] neg_hi:[1,0,0]
	v_pk_fma_f32 v[140:141], v[30:31], v[30:31], v[132:133] op_sel_hi:[1,1,0] neg_lo:[1,0,0] neg_hi:[1,0,0]
	v_max_f32_e32 v138, 0, v138
	v_max_f32_e32 v139, 0, v139
	v_max_f32_e32 v140, 0, v140
	v_max_f32_e32 v141, 0, v141
	v_sqrt_f32_e32 v138, v138
	v_sqrt_f32_e32 v139, v139
	v_sqrt_f32_e32 v140, v140
	v_sqrt_f32_e32 v141, v141
	s_nop 0
	v_pk_mul_f32 v[118:119], v[138:139], v[118:119]
	v_pk_mul_f32 v[120:121], v[140:141], v[120:121]
	v_mov_b32_e32 v253, v31
	v_mov_b32_e32 v254, v121
	v_fma_f32 v254, v30, v254, v120
	v_mul_f32_e32 v253, v253, v30
	v_fma_f32 v254, v29, v254, v119
	v_mul_f32_e32 v253, v253, v29
	v_fma_f32 v254, v28, v254, v118
	v_mul_f32_e32 v253, v253, v28
	v_fma_f32 v254, v27, v254, v117
	v_mul_f32_e32 v253, v253, v27
	v_fma_f32 v254, v26, v254, v116
	v_mul_f32_e32 v253, v253, v26
	v_fma_f32 v254, v25, v254, v115
	v_mul_f32_e32 v253, v253, v25
	v_fma_f32 v254, v24, v254, v114
	v_mul_f32_e32 v253, v253, v24
	v_fma_f32 v254, v23, v254, v113
	v_mul_f32_e32 v253, v253, v23
	v_fma_f32 v254, v22, v254, v112
	v_mul_f32_e32 v253, v253, v22
	v_fma_f32 v254, v21, v254, v111
	v_mul_f32_e32 v253, v253, v21
	v_fma_f32 v254, v20, v254, v110
	v_mul_f32_e32 v253, v253, v20
	v_fma_f32 v254, v19, v254, v109
	v_mul_f32_e32 v253, v253, v19
	v_fma_f32 v254, v18, v254, v108
	v_mul_f32_e32 v253, v253, v18
	v_fma_f32 v254, v17, v254, v107
	v_mul_f32_e32 v253, v253, v17
	v_fma_f32 v254, v16, v254, v106
	v_mul_f32_e32 v253, v253, v16
	v_fma_f32 v254, v15, v254, v105
	v_mul_f32_e32 v253, v253, v15
	v_fma_f32 v254, v14, v254, v104
	v_mul_f32_e32 v253, v253, v14
	v_fma_f32 v254, v13, v254, v103
	v_mul_f32_e32 v253, v253, v13
	v_fma_f32 v254, v12, v254, v102
	v_mul_f32_e32 v253, v253, v12
	v_fma_f32 v254, v11, v254, v101
	v_mul_f32_e32 v253, v253, v11
	v_fma_f32 v254, v10, v254, v100
	v_mul_f32_e32 v253, v253, v10
	v_fma_f32 v254, v9, v254, v99
	v_mul_f32_e32 v253, v253, v9
	v_fma_f32 v254, v8, v254, v98
	v_mul_f32_e32 v253, v253, v8
	v_fma_f32 v254, v7, v254, v97
	v_mul_f32_e32 v253, v253, v7
	v_fma_f32 v254, v6, v254, v96
	v_mul_f32_e32 v253, v253, v6
	v_fma_f32 v254, v5, v254, v95
	v_mul_f32_e32 v253, v253, v5
	v_fma_f32 v254, v4, v254, v94
	v_mul_f32_e32 v253, v253, v4
	v_fma_f32 v254, v3, v254, v93
	v_mul_f32_e32 v253, v253, v3
	v_fma_f32 v254, v2, v254, v92
	v_mul_f32_e32 v253, v253, v2
	v_fma_f32 v254, v1, v254, v91
	v_mul_f32_e32 v253, v253, v1
	v_fma_f32 v254, v0, v254, v90
	v_mul_f32_e32 v253, v253, v0
	v_mov_b32_e32 v138, v253
	v_mov_b32_e32 v139, v253
	s_nop 1
	v_permlane16_swap_b32_e32 v138, v139
	v_mov_b32_e32 v140, v138
	v_mov_b32_e32 v141, v139
	s_nop 1
	v_permlane32_swap_b32_e32 v138, v140
	v_permlane32_swap_b32_e32 v139, v141
	v_mov_b32_e32 v198, v254
	v_mov_b32_e32 v199, v254
	s_nop 1
	v_permlane16_swap_b32_e32 v198, v199
	v_mov_b32_e32 v200, v198
	v_mov_b32_e32 v201, v199
	s_nop 1
	v_permlane32_swap_b32_e32 v198, v200
	v_permlane32_swap_b32_e32 v199, v201
	v_mov_b32_e32 v202, 0
	v_fma_f32 v151, v141, v202, v201
	v_fma_f32 v150, v140, v151, v200
	v_fma_f32 v136, v139, v150, v199
	v_fma_f32 v254, v138, v136, v198
	v_mul_f32_e32 v253, v138, v139
	v_mul_f32_e32 v253, v253, v140
	v_mul_f32_e32 v200, v253, v141
	v_mov_b32_e32 v201, v254
	s_add_u32 s0, s71, 264
	s_lshl_b32 s0, s0, 12
	s_lshl_b32 s1, s56, 3
	s_add_u32 s0, s0, s1
	s_add_u32 s4, s18, s0
	s_addc_u32 s5, s19, 0
	global_store_dwordx2 v250, v[200:201], s[4:5]
	s_add_u32 s69, s69, 1
	s_cmp_lt_u32 s69, s70
	s_cbranch_scc1 .Lmy_lrua_tile
	s_waitcnt lgkmcnt(0)
	s_barrier

; __device__ __forceinline__ void lru_tile(const Params& P, int chunk, int head, int pass, char* smem_raw) {
;     ...
;   const int tid = VTID, lane = tid & 63, wid = tid >> 6;
;   const int q = tid >> 6, ch = tid & 63;
;   const int row0 = chunk * 128;
;   int seq_lo, seq_hi;
;   if (chunk < 256) { seq_lo = (chunk >> 6) << 13; seq_hi = seq_lo + 8192; }
;   else { const int b = (chunk - 256) >> 1; seq_lo = N_X + b * 256; seq_hi = seq_lo + 256; }
;   const int gch = head * 64 + ch;
.LBB0_477:
	v_readlane_b32 s0, v252, 0
	v_readlane_b32 s1, v252, 1
	v_readfirstlane_b32 s68, v153
	s_nop 3
	s_sub_u32 s0, s0, 0x170
	s_subb_u32 s1, s1, 0
	s_load_dwordx2 s[10:11], s[0:1], 0x148
	s_load_dwordx2 s[12:13], s[0:1], 0x158
	s_load_dwordx2 s[18:19], s[0:1], 0x130
	s_load_dwordx2 s[20:21], s[0:1], 0x128
	s_load_dwordx4 s[24:27], s[0:1], 0x70
	s_load_dwordx2 s[28:29], s[0:1], 0x88
	s_load_dwordx2 s[30:31], s[0:1], 0x98
	s_load_dwordx2 s[36:37], s[0:1], 0xa0
	s_lshl_b32 s4, s2, 1
	s_add_u32 s68, s4, s68
	s_mov_b32 s69, 0
	s_mov_b32 s70, 4
	s_cmp_lt_u32 s68, 64
	s_cselect_b32 s70, 5, 4
	s_mov_b32 s72, 0xffff0000
	s_mov_b32 s73, -1
	s_mov_b32 s74, 0
	s_mov_b32 s75, -1
	s_mov_b32 s76, 0
	s_mov_b32 s77, 0xffff0000
	s_mov_b32 s78, -1
	s_mov_b32 s79, 0x0000ffff
	s_mov_b32 s80, -1
	s_mov_b32 s81, 0
	s_mov_b32 s82, 0x0000ffff
	s_mov_b32 s83, 0
	v_and_b32_e32 v138, 63, v152
	v_lshrrev_b32_e32 v139, 4, v138
	v_and_b32_e32 v140, 15, v138
	v_bfe_u32 v141, v152, 6, 2
	v_lshl_add_u32 v255, v141, 4, v140
	v_mul_u32_u24_e32 v253, 0x12000, v153
	v_add_u32_e32 v253, 16, v253
	v_mul_u32_u24_e32 v134, 0x18000, v139
	v_lshl_add_u32 v134, v255, 1, v134
	v_lshlrev_b32_e32 v237, 16, v139
	v_lshl_add_u32 v237, v255, 1, v237
	v_lshlrev_b32_e32 v250, 3, v255
	v_lshlrev_b32_e32 v251, 7, v255
	v_lshl_add_u32 v251, v139, 4, v251
	v_lshrrev_b32_e32 v254, 3, v140
	v_lshl_add_u32 v254, v141, 1, v254
	v_lshlrev_b32_e32 v202, 1, v139
	v_xor_b32_e32 v89, v254, v202
	v_xor_b32_e32 v130, 1, v89
	v_and_b32_e32 v203, 7, v140
	v_lshl_add_u32 v202, v139, 12, v253
	v_lshl_add_u32 v202, v203, 1, v202
	v_lshl_add_u32 v89, v89, 4, v202
	v_lshl_add_u32 v130, v130, 4, v202
	v_lshrrev_b32_e32 v202, 2, v140
	v_and_b32_e32 v203, 3, v140
	v_lshl_add_u32 v254, v202, 5, v203
	v_lshl_add_u32 v254, v254, 7, v253
	v_lshrrev_b32_e32 v203, 1, v203
	v_lshl_add_u32 v202, v202, 1, v203
	v_xor_b32_e32 v202, v139, v202
	v_lshl_add_u32 v131, v202, 4, v254
	v_xor_b32_e32 v202, 4, v202
	v_lshl_add_u32 v133, v202, 4, v254
	v_cmp_eq_u32_e32 vcc, 0, v139
	s_mov_b64 s[84:85], vcc
	v_cmp_eq_u32_e32 vcc, 3, v139
	s_mov_b64 s[86:87], vcc
	s_waitcnt lgkmcnt(0)
; __device__ __forceinline__ float bf2f(u16 h) { return __uint_as_float(((unsigned)h) << 16); }
; __device__ __forceinline__ void lru_tile(const Params& P, int chunk, int head, int pass, char* smem_raw) {
;     ...
;     const float w0 = P.conv_w[gch], w1 = P.conv_w[512 + gch], w2 = P.conv_w[1024 + gch], w3 = P.conv_w[1536 + gch];
;     const float cb = P.conv_b[gch];
;     const u16* zu = P.zq + gch;
;     const int r = row0 + q * 32;
;     float uv[35];
; #pragma unroll
;     for (int i = 0; i < 35; ++i) {
;       const int rr = r - 2 + i;
;       uv[i] = (rr >= seq_lo && rr < seq_hi) ? bf2f(zu[(long)rr * 1536]) : 0.f;
;     ...
;     for (int tc = 0; tc < 4; ++tc) {
;       const int cidx = d * 512 + head * 64 + 16 * tc + (lane & 15);
;       ba[tc] = P.b_a[cidx] * -1.4426950408889634f; bi[tc] = P.b_i[cidx] * -1.4426950408889634f;
;       const float nl = -P.lam[cidx];
;       const float e_ = __expf(nl);
;       const float sp = (nl > 20.f) ? nl
;                      : (e_ < 0.03f ? e_ * (1.f - e_ * (0.5f - e_ * (0.33333334f - 0.25f * e_))) : __logf(1.f + e_));
;       c8[tc] = 8.f * 1.4426950408889634f * sp;
;     }
	s_and_b32 s56, s68, 7
	s_lshl_b32 s56, s56, 6
	s_lshr_b32 s59, s68, 3
	s_cmp_lt_u32 s59, 256
	s_cselect_b32 s60, 63, 1
	s_and_b32 s57, s59, s60
	s_cmp_eq_u32 s57, 0
	s_cselect_b64 s[0:1], s[84:85], 0
	s_cmp_eq_u32 s57, s60
	s_cselect_b64 s[4:5], s[86:87], 0
	v_mov_b32_e32 v255, 0x1800
	v_cndmask_b32_e64 v150, 0, v255, s[0:1]
	v_lshlrev_b32_e32 v136, 1, v150
	v_add_u32_e32 v136, v134, v136
	v_add_u32_e32 v150, v134, v150
	v_cndmask_b32_e64 v151, 0, v255, s[4:5]
	v_sub_u32_e32 v151, v134, v151
	s_lshl_b32 s61, s59, 7
	s_mul_i32 s0, s61, 0xc00
	s_lshl_b32 s1, s56, 1
	s_add_u32 s0, s0, s1
	s_add_u32 s4, s10, s0
	s_addc_u32 s5, s11, 0
	s_sub_u32 s4, s4, 0x1800
	s_subb_u32 s5, s5, 0
	global_load_ushort v32, v136, s[4:5]
	s_add_u32 s4, s4, 0xc00
	s_addc_u32 s5, s5, 0
	global_load_ushort v33, v150, s[4:5]
	s_add_u32 s4, s4, 0xc00
	s_addc_u32 s5, s5, 0
	global_load_ushort v34, v134, s[4:5]
	s_add_u32 s4, s4, 0xc00
	s_addc_u32 s5, s5, 0
	global_load_ushort v35, v134, s[4:5]
	s_add_u32 s4, s4, 0xc00
	s_addc_u32 s5, s5, 0
	global_load_ushort v36, v134, s[4:5]
	s_add_u32 s4, s4, 0xc00
	s_addc_u32 s5, s5, 0
	global_load_ushort v37, v134, s[4:5]
	s_add_u32 s4, s4, 0xc00
	s_addc_u32 s5, s5, 0
	global_load_ushort v38, v134, s[4:5]
	s_add_u32 s4, s4, 0xc00
	s_addc_u32 s5, s5, 0
	global_load_ushort v39, v134, s[4:5]
	s_add_u32 s4, s4, 0xc00
	s_addc_u32 s5, s5, 0
	global_load_ushort v40, v134, s[4:5]
	s_add_u32 s4, s4, 0xc00
	s_addc_u32 s5, s5, 0
	global_load_ushort v41, v134, s[4:5]
	s_add_u32 s4, s4, 0xc00
	s_addc_u32 s5, s5, 0
	global_load_ushort v42, v134, s[4:5]
	s_add_u32 s4, s4, 0xc00
	s_addc_u32 s5, s5, 0
	global_load_ushort v43, v134, s[4:5]
	s_add_u32 s4, s4, 0xc00
	s_addc_u32 s5, s5, 0
	global_load_ushort v44, v134, s[4:5]
	s_add_u32 s4, s4, 0xc00
	s_addc_u32 s5, s5, 0
	global_load_ushort v45, v134, s[4:5]
	s_add_u32 s4, s4, 0xc00
	s_addc_u32 s5, s5, 0
	global_load_ushort v46, v134, s[4:5]
	s_add_u32 s4, s4, 0xc00
	s_addc_u32 s5, s5, 0
	global_load_ushort v47, v134, s[4:5]
	s_add_u32 s4, s4, 0xc00
	s_addc_u32 s5, s5, 0
	global_load_ushort v48, v134, s[4:5]
	s_add_u32 s4, s4, 0xc00
	s_addc_u32 s5, s5, 0
	global_load_ushort v49, v134, s[4:5]
	s_add_u32 s4, s4, 0xc00
	s_addc_u32 s5, s5, 0
	global_load_ushort v50, v134, s[4:5]
	s_add_u32 s4, s4, 0xc00
	s_addc_u32 s5, s5, 0
	global_load_ushort v51, v134, s[4:5]
	s_add_u32 s4, s4, 0xc00
	s_addc_u32 s5, s5, 0
	global_load_ushort v52, v134, s[4:5]
	s_add_u32 s4, s4, 0xc00
	s_addc_u32 s5, s5, 0
	global_load_ushort v53, v134, s[4:5]
	s_add_u32 s4, s4, 0xc00
	s_addc_u32 s5, s5, 0
	global_load_ushort v54, v134, s[4:5]
	s_add_u32 s4, s4, 0xc00
	s_addc_u32 s5, s5, 0
	global_load_ushort v55, v134, s[4:5]
	s_add_u32 s4, s4, 0xc00
	s_addc_u32 s5, s5, 0
	global_load_ushort v56, v134, s[4:5]
	s_add_u32 s4, s4, 0xc00
	s_addc_u32 s5, s5, 0
	global_load_ushort v57, v134, s[4:5]
	s_add_u32 s4, s4, 0xc00
	s_addc_u32 s5, s5, 0
	global_load_ushort v58, v134, s[4:5]
	s_add_u32 s4, s4, 0xc00
	s_addc_u32 s5, s5, 0
	global_load_ushort v59, v134, s[4:5]
	s_add_u32 s4, s4, 0xc00
	s_addc_u32 s5, s5, 0
	global_load_ushort v60, v134, s[4:5]
	s_add_u32 s4, s4, 0xc00
	s_addc_u32 s5, s5, 0
	global_load_ushort v61, v134, s[4:5]
	s_add_u32 s4, s4, 0xc00
	s_addc_u32 s5, s5, 0
	global_load_ushort v62, v134, s[4:5]
	s_add_u32 s4, s4, 0xc00
	s_addc_u32 s5, s5, 0
	global_load_ushort v63, v134, s[4:5]
	s_add_u32 s4, s4, 0xc00
	s_addc_u32 s5, s5, 0
	global_load_ushort v64, v134, s[4:5]
	s_add_u32 s4, s4, 0xc00
	s_addc_u32 s5, s5, 0
	global_load_ushort v66, v134, s[4:5]
	s_add_u32 s4, s4, 0xc00
	s_addc_u32 s5, s5, 0
	global_load_ushort v69, v151, s[4:5]
	v_bfe_u32 v255, v152, 6, 2
	v_and_b32_e32 v253, 15, v152
	v_lshl_add_u32 v255, v255, 4, v253
	v_add_u32_e32 v255, s56, v255
	v_lshlrev_b32_e32 v255, 2, v255
	global_load_dword v65, v255, s[24:25]
	global_load_dword v67, v255, s[24:25] offset:2048
	s_add_u32 s0, s24, 0x1000
	s_addc_u32 s1, s25, 0
	global_load_dword v68, v255, s[0:1]
	global_load_dword v70, v255, s[0:1] offset:2048
	global_load_dword v73, v255, s[26:27]
	s_add_u32 s0, s28, 0x0
	s_addc_u32 s1, s29, 0
	global_load_dword v75, v255, s[0:1]
	s_add_u32 s0, s30, 0x0
	s_addc_u32 s1, s31, 0
	global_load_dword v84, v255, s[0:1]
	s_add_u32 s0, s36, 0x0
	s_addc_u32 s1, s37, 0
	global_load_dword v85, v255, s[0:1]
	s_add_u32 s0, s28, 0x800
	s_addc_u32 s1, s29, 0
	global_load_dword v145, v255, s[0:1]
	s_add_u32 s0, s30, 0x800
	s_addc_u32 s1, s31, 0
	global_load_dword v146, v255, s[0:1]
	s_add_u32 s0, s36, 0x800
	s_addc_u32 s1, s37, 0
	global_load_dword v147, v255, s[0:1]
	s_lshl_b32 s0, s56, 8
	s_add_u32 s0, s0, 0x0
	s_add_u32 s4, s20, s0
	s_addc_u32 s5, s21, 0
	global_load_dwordx4 v[238:241], v251, s[4:5]
	global_load_dwordx4 v[242:245], v251, s[4:5] offset:64
	s_add_u32 s4, s4, 0x2000
	s_addc_u32 s5, s5, 0
	global_load_dwordx4 v[246:249], v251, s[4:5]
	global_load_dwordx4 v[194:197], v251, s[4:5] offset:64
	s_waitcnt vmcnt(0)
	v_mul_f32_e32 v75, 0xbfb8aa3b, v75
	v_mul_f32_e32 v84, 0xbfb8aa3b, v84
	v_sub_f32_e32 v138, 0, v85
	v_mul_f32_e32 v139, 0x3fb8aa3b, v138
	v_exp_f32_e32 v139, v139
	s_nop 0
	v_mul_f32_e32 v140, 0xbe800000, v139
	v_add_f32_e32 v140, 0x3eaaaaab, v140
	v_fma_f32 v140, -v139, v140, 0.5
	v_fma_f32 v140, -v139, v140, 1.0
	v_mul_f32_e32 v140, v139, v140
	v_add_f32_e32 v141, 1.0, v139
	v_log_f32_e32 v141, v141
	v_mov_b32_e32 v255, 0x3cf5c28f
	v_mul_f32_e32 v141, 0x3f317218, v141
	v_cmp_gt_f32_e32 vcc, v255, v139
	s_nop 1
	v_cndmask_b32_e32 v140, v141, v140, vcc
	v_mov_b32_e32 v255, 0x41a00000
	v_cmp_lt_f32_e32 vcc, v255, v138
	s_nop 1
	v_cndmask_b32_e32 v140, v140, v138, vcc
	v_mul_f32_e32 v85, 0xc138aa3b, v140
	v_mul_f32_e32 v145, 0xbfb8aa3b, v145
	v_mul_f32_e32 v146, 0xbfb8aa3b, v146
	v_sub_f32_e32 v138, 0, v147
	v_mul_f32_e32 v139, 0x3fb8aa3b, v138
	v_exp_f32_e32 v139, v139
	s_nop 0
	v_mul_f32_e32 v140, 0xbe800000, v139
	v_add_f32_e32 v140, 0x3eaaaaab, v140
	v_fma_f32 v140, -v139, v140, 0.5
	v_fma_f32 v140, -v139, v140, 1.0
	v_mul_f32_e32 v140, v139, v140
	v_add_f32_e32 v141, 1.0, v139
	v_log_f32_e32 v141, v141
	v_mov_b32_e32 v255, 0x3cf5c28f
	v_mul_f32_e32 v141, 0x3f317218, v141
	v_cmp_gt_f32_e32 vcc, v255, v139
	s_nop 1
	v_cndmask_b32_e32 v140, v141, v140, vcc
	v_mov_b32_e32 v255, 0x41a00000
	v_cmp_lt_f32_e32 vcc, v255, v138
	s_nop 1
	v_cndmask_b32_e32 v140, v140, v138, vcc
	v_mul_f32_e32 v147, 0xc138aa3b, v140
	v_mov_b32_e32 v132, 1.0

; __device__ __forceinline__ float bf2f(u16 h) { return __uint_as_float(((unsigned)h) << 16); }
; __device__ __forceinline__ void lru_tile(const Params& P, int chunk, int head, int pass, char* smem_raw) {
;     ...
;       for (int s = 0; s < 2; ++s) {
;         const bf16x8 af = *reinterpret_cast<const bf16x8*>(&sm_uc[(sb * 64 + wid * 16 + (lane & 15)) * LDSS + s * 32 + (lane >> 4) * 8]);
; #pragma unroll
;         for (int t = 0; t < 8; ++t) {
;           const bf16x8 bfr = *reinterpret_cast<const bf16x8*>(&sm_w[(t * 16 + (lane & 15)) * LDSS + s * 32 + (lane >> 4) * 8]);
;           acc[t] = __builtin_amdgcn_mfma_f32_16x16x32_bf16(af, bfr, acc[t], 0, 0, 0);
;         }
;       }
; #pragma unroll
;       for (int tc = 0; tc < 4; ++tc)
; #pragma unroll
;         for (int reg = 0; reg < 4; ++reg) {
;           const int tl = wid * 16 + (lane >> 4) * 4 + reg;
;           const int c = 16 * tc + (lane & 15);
;           const float r = __builtin_amdgcn_rcpf(1.f + __builtin_amdgcn_exp2f(acc[tc][reg] + ba[tc]));
;           const float ii = __builtin_amdgcn_rcpf(1.f + __builtin_amdgcn_exp2f(acc[tc + 4][reg] + bi[tc]));
;           const float la = -c8[tc] * r;
;           const float a = __builtin_amdgcn_exp2f(la);
;           const float ucv = bf2f(sm_uc[(sb * 64 + tl) * LDSS + c]);
;           const float bt = __builtin_amdgcn_sqrtf(fmaxf(1.f - a * a, 0.f)) * (ii * ucv);
;           sm_a[tl * 64 + c] = a;
;           sm_b[tl * 64 + c] = bt;
;         }
.Lmy_lrub_nopf:
	ds_read_b128 v[76:79], v131 offset:0
	ds_read_b128 v[80:83], v133 offset:0
	ds_read_b128 v[122:125], v131 offset:512
	ds_read_b128 v[126:129], v133 offset:512
	s_waitcnt lgkmcnt(3)
	v_mfma_f32_16x16x32_bf16 v[0:3], v[76:79], v[238:241], 0
	v_mfma_f32_16x16x32_bf16 v[90:93], v[76:79], v[246:249], 0
	ds_read_b128 v[76:79], v131 offset:1024
	s_waitcnt lgkmcnt(3)
	v_mfma_f32_16x16x32_bf16 v[0:3], v[80:83], v[242:245], v[0:3]
	v_mfma_f32_16x16x32_bf16 v[90:93], v[80:83], v[194:197], v[90:93]
	ds_read_b128 v[80:83], v133 offset:1024
	s_waitcnt lgkmcnt(3)
	v_mfma_f32_16x16x32_bf16 v[4:7], v[122:125], v[238:241], 0
	v_mfma_f32_16x16x32_bf16 v[94:97], v[122:125], v[246:249], 0
	ds_read_b128 v[122:125], v131 offset:1536
	s_waitcnt lgkmcnt(3)
	v_mfma_f32_16x16x32_bf16 v[4:7], v[126:129], v[242:245], v[4:7]
	v_mfma_f32_16x16x32_bf16 v[94:97], v[126:129], v[194:197], v[94:97]
	ds_read_b128 v[126:129], v133 offset:1536
	s_waitcnt lgkmcnt(3)
	v_mfma_f32_16x16x32_bf16 v[8:11], v[76:79], v[238:241], 0
	v_mfma_f32_16x16x32_bf16 v[98:101], v[76:79], v[246:249], 0
	ds_read_b128 v[76:79], v131 offset:2048
	s_waitcnt lgkmcnt(3)
	v_mfma_f32_16x16x32_bf16 v[8:11], v[80:83], v[242:245], v[8:11]
	v_mfma_f32_16x16x32_bf16 v[98:101], v[80:83], v[194:197], v[98:101]
	ds_read_b128 v[80:83], v133 offset:2048
	s_waitcnt lgkmcnt(3)
	v_mfma_f32_16x16x32_bf16 v[12:15], v[122:125], v[238:241], 0
	v_mfma_f32_16x16x32_bf16 v[102:105], v[122:125], v[246:249], 0
	ds_read_b128 v[122:125], v131 offset:2560
	s_waitcnt lgkmcnt(3)
	v_mfma_f32_16x16x32_bf16 v[12:15], v[126:129], v[242:245], v[12:15]
	v_mfma_f32_16x16x32_bf16 v[102:105], v[126:129], v[194:197], v[102:105]
	ds_read_b128 v[126:129], v133 offset:2560
	s_waitcnt lgkmcnt(3)
	v_mfma_f32_16x16x32_bf16 v[16:19], v[76:79], v[238:241], 0
	v_mfma_f32_16x16x32_bf16 v[106:109], v[76:79], v[246:249], 0
	ds_read_b128 v[76:79], v131 offset:3072
	s_waitcnt lgkmcnt(3)
	v_mfma_f32_16x16x32_bf16 v[16:19], v[80:83], v[242:245], v[16:19]
	v_mfma_f32_16x16x32_bf16 v[106:109], v[80:83], v[194:197], v[106:109]
	ds_read_b128 v[80:83], v133 offset:3072
	s_waitcnt lgkmcnt(3)
	v_mfma_f32_16x16x32_bf16 v[20:23], v[122:125], v[238:241], 0
	v_mfma_f32_16x16x32_bf16 v[110:113], v[122:125], v[246:249], 0
	ds_read_b128 v[122:125], v131 offset:3584
	s_waitcnt lgkmcnt(3)
	v_mfma_f32_16x16x32_bf16 v[20:23], v[126:129], v[242:245], v[20:23]
	v_mfma_f32_16x16x32_bf16 v[110:113], v[126:129], v[194:197], v[110:113]
	ds_read_b128 v[126:129], v133 offset:3584
	s_waitcnt lgkmcnt(3)
	v_mfma_f32_16x16x32_bf16 v[24:27], v[76:79], v[238:241], 0
	v_mfma_f32_16x16x32_bf16 v[114:117], v[76:79], v[246:249], 0
	s_waitcnt lgkmcnt(2)
	v_mfma_f32_16x16x32_bf16 v[24:27], v[80:83], v[242:245], v[24:27]
	v_mfma_f32_16x16x32_bf16 v[114:117], v[80:83], v[194:197], v[114:117]
	s_waitcnt lgkmcnt(1)
	v_mfma_f32_16x16x32_bf16 v[28:31], v[122:125], v[238:241], 0
	v_mfma_f32_16x16x32_bf16 v[118:121], v[122:125], v[246:249], 0
	s_waitcnt lgkmcnt(0)
	v_mfma_f32_16x16x32_bf16 v[28:31], v[126:129], v[242:245], v[28:31]
	v_mfma_f32_16x16x32_bf16 v[118:121], v[126:129], v[194:197], v[118:121]
	s_lshl_b32 s0, s56, 8
	s_add_u32 s0, s0, 0x20000
	s_add_u32 s4, s20, s0
	s_addc_u32 s5, s21, 0
	global_load_dwordx4 v[238:241], v251, s[4:5]
	global_load_dwordx4 v[242:245], v251, s[4:5] offset:64
	s_add_u32 s4, s4, 0x2000
	s_addc_u32 s5, s5, 0
	global_load_dwordx4 v[246:249], v251, s[4:5]
	global_load_dwordx4 v[194:197], v251, s[4:5] offset:64
	s_nop 7
	s_nop 7
	v_pk_add_f32 v[0:1], v[0:1], v[74:75] op_sel:[0,1]
	v_pk_add_f32 v[2:3], v[2:3], v[74:75] op_sel:[0,1]
	v_pk_add_f32 v[90:91], v[90:91], v[84:85] op_sel_hi:[1,0]
	v_pk_add_f32 v[92:93], v[92:93], v[84:85] op_sel_hi:[1,0]
	v_exp_f32_e32 v0, v0
	v_exp_f32_e32 v1, v1
	v_exp_f32_e32 v2, v2
	v_exp_f32_e32 v3, v3
	v_exp_f32_e32 v90, v90
	v_exp_f32_e32 v91, v91
	v_exp_f32_e32 v92, v92
	v_exp_f32_e32 v93, v93
	v_pk_add_f32 v[0:1], v[0:1], v[132:133] op_sel_hi:[1,0]
	v_pk_add_f32 v[2:3], v[2:3], v[132:133] op_sel_hi:[1,0]
	v_pk_add_f32 v[90:91], v[90:91], v[132:133] op_sel_hi:[1,0]
	v_pk_add_f32 v[92:93], v[92:93], v[132:133] op_sel_hi:[1,0]
	v_rcp_f32_e32 v0, v0
	v_rcp_f32_e32 v1, v1
	v_rcp_f32_e32 v2, v2
	v_rcp_f32_e32 v3, v3
	v_rcp_f32_e32 v90, v90
	v_rcp_f32_e32 v91, v91
	v_rcp_f32_e32 v92, v92
	v_rcp_f32_e32 v93, v93
	v_pk_mul_f32 v[0:1], v[0:1], v[84:85] op_sel:[0,1]
	v_pk_mul_f32 v[2:3], v[2:3], v[84:85] op_sel:[0,1]
	v_pk_mul_f32 v[90:91], v[90:91], v[162:163]
	v_pk_mul_f32 v[92:93], v[92:93], v[164:165]
	v_exp_f32_e32 v0, v0
	v_exp_f32_e32 v1, v1
	v_exp_f32_e32 v2, v2
	v_exp_f32_e32 v3, v3
	s_nop 0
	v_pk_fma_f32 v[138:139], v[0:1], v[0:1], v[132:133] op_sel_hi:[1,1,0] neg_lo:[1,0,0] neg_hi:[1,0,0]
	v_pk_fma_f32 v[140:141], v[2:3], v[2:3], v[132:133] op_sel_hi:[1,1,0] neg_lo:[1,0,0] neg_hi:[1,0,0]
	v_max_f32_e32 v138, 0, v138
	v_max_f32_e32 v139, 0, v139
	v_max_f32_e32 v140, 0, v140
	v_max_f32_e32 v141, 0, v141
	v_sqrt_f32_e32 v138, v138
	v_sqrt_f32_e32 v139, v139
	v_sqrt_f32_e32 v140, v140
	v_sqrt_f32_e32 v141, v141
	s_nop 0
	v_pk_mul_f32 v[90:91], v[138:139], v[90:91]
	v_pk_mul_f32 v[92:93], v[140:141], v[92:93]
	v_pk_add_f32 v[4:5], v[4:5], v[74:75] op_sel:[0,1]
	v_pk_add_f32 v[6:7], v[6:7], v[74:75] op_sel:[0,1]
	v_pk_add_f32 v[94:95], v[94:95], v[84:85] op_sel_hi:[1,0]
	v_pk_add_f32 v[96:97], v[96:97], v[84:85] op_sel_hi:[1,0]
	v_exp_f32_e32 v4, v4
	v_exp_f32_e32 v5, v5
	v_exp_f32_e32 v6, v6
	v_exp_f32_e32 v7, v7
	v_exp_f32_e32 v94, v94
	v_exp_f32_e32 v95, v95
	v_exp_f32_e32 v96, v96
	v_exp_f32_e32 v97, v97
	v_pk_add_f32 v[4:5], v[4:5], v[132:133] op_sel_hi:[1,0]
	v_pk_add_f32 v[6:7], v[6:7], v[132:133] op_sel_hi:[1,0]
; __device__ __forceinline__ float bf2f(u16 h) { return __uint_as_float(((unsigned)h) << 16); }
; __device__ __forceinline__ void lru_tile(const Params& P, int chunk, int head, int pass, char* smem_raw) {
;     ...
;       for (int tc = 0; tc < 4; ++tc)
; #pragma unroll
;         for (int reg = 0; reg < 4; ++reg) {
;           const int tl = wid * 16 + (lane >> 4) * 4 + reg;
;           const int c = 16 * tc + (lane & 15);
;           const float r = __builtin_amdgcn_rcpf(1.f + __builtin_amdgcn_exp2f(acc[tc][reg] + ba[tc]));
;           const float ii = __builtin_amdgcn_rcpf(1.f + __builtin_amdgcn_exp2f(acc[tc + 4][reg] + bi[tc]));
;           const float la = -c8[tc] * r;
;           const float a = __builtin_amdgcn_exp2f(la);
;           const float ucv = bf2f(sm_uc[(sb * 64 + tl) * LDSS + c]);
;           const float bt = __builtin_amdgcn_sqrtf(fmaxf(1.f - a * a, 0.f)) * (ii * ucv);
;           sm_a[tl * 64 + c] = a;
;           sm_b[tl * 64 + c] = bt;
;         }
	v_pk_add_f32 v[94:95], v[94:95], v[132:133] op_sel_hi:[1,0]
	v_pk_add_f32 v[96:97], v[96:97], v[132:133] op_sel_hi:[1,0]
	v_rcp_f32_e32 v4, v4
	v_rcp_f32_e32 v5, v5
	v_rcp_f32_e32 v6, v6
	v_rcp_f32_e32 v7, v7
	v_rcp_f32_e32 v94, v94
	v_rcp_f32_e32 v95, v95
	v_rcp_f32_e32 v96, v96
	v_rcp_f32_e32 v97, v97
	v_pk_mul_f32 v[4:5], v[4:5], v[84:85] op_sel:[0,1]
	v_pk_mul_f32 v[6:7], v[6:7], v[84:85] op_sel:[0,1]
	v_pk_mul_f32 v[94:95], v[94:95], v[166:167]
	v_pk_mul_f32 v[96:97], v[96:97], v[168:169]
	v_exp_f32_e32 v4, v4
	v_exp_f32_e32 v5, v5
	v_exp_f32_e32 v6, v6
	v_exp_f32_e32 v7, v7
	s_nop 0
	v_pk_fma_f32 v[138:139], v[4:5], v[4:5], v[132:133] op_sel_hi:[1,1,0] neg_lo:[1,0,0] neg_hi:[1,0,0]
	v_pk_fma_f32 v[140:141], v[6:7], v[6:7], v[132:133] op_sel_hi:[1,1,0] neg_lo:[1,0,0] neg_hi:[1,0,0]
	v_max_f32_e32 v138, 0, v138
	v_max_f32_e32 v139, 0, v139
	v_max_f32_e32 v140, 0, v140
	v_max_f32_e32 v141, 0, v141
	v_sqrt_f32_e32 v138, v138
	v_sqrt_f32_e32 v139, v139
	v_sqrt_f32_e32 v140, v140
	v_sqrt_f32_e32 v141, v141
	s_nop 0
	v_pk_mul_f32 v[94:95], v[138:139], v[94:95]
	v_pk_mul_f32 v[96:97], v[140:141], v[96:97]
	v_pk_add_f32 v[8:9], v[8:9], v[74:75] op_sel:[0,1]
	v_pk_add_f32 v[10:11], v[10:11], v[74:75] op_sel:[0,1]
	v_pk_add_f32 v[98:99], v[98:99], v[84:85] op_sel_hi:[1,0]
	v_pk_add_f32 v[100:101], v[100:101], v[84:85] op_sel_hi:[1,0]
	v_exp_f32_e32 v8, v8
	v_exp_f32_e32 v9, v9
	v_exp_f32_e32 v10, v10
	v_exp_f32_e32 v11, v11
	v_exp_f32_e32 v98, v98
	v_exp_f32_e32 v99, v99
	v_exp_f32_e32 v100, v100
	v_exp_f32_e32 v101, v101
	v_pk_add_f32 v[8:9], v[8:9], v[132:133] op_sel_hi:[1,0]
	v_pk_add_f32 v[10:11], v[10:11], v[132:133] op_sel_hi:[1,0]
	v_pk_add_f32 v[98:99], v[98:99], v[132:133] op_sel_hi:[1,0]
	v_pk_add_f32 v[100:101], v[100:101], v[132:133] op_sel_hi:[1,0]
	v_rcp_f32_e32 v8, v8
	v_rcp_f32_e32 v9, v9
	v_rcp_f32_e32 v10, v10
	v_rcp_f32_e32 v11, v11
	v_rcp_f32_e32 v98, v98
	v_rcp_f32_e32 v99, v99
	v_rcp_f32_e32 v100, v100
	v_rcp_f32_e32 v101, v101
	v_pk_mul_f32 v[8:9], v[8:9], v[84:85] op_sel:[0,1]
	v_pk_mul_f32 v[10:11], v[10:11], v[84:85] op_sel:[0,1]
	v_pk_mul_f32 v[98:99], v[98:99], v[170:171]
	v_pk_mul_f32 v[100:101], v[100:101], v[172:173]
	v_exp_f32_e32 v8, v8
	v_exp_f32_e32 v9, v9
	v_exp_f32_e32 v10, v10
	v_exp_f32_e32 v11, v11
	s_nop 0
	v_pk_fma_f32 v[138:139], v[8:9], v[8:9], v[132:133] op_sel_hi:[1,1,0] neg_lo:[1,0,0] neg_hi:[1,0,0]
	v_pk_fma_f32 v[140:141], v[10:11], v[10:11], v[132:133] op_sel_hi:[1,1,0] neg_lo:[1,0,0] neg_hi:[1,0,0]
	v_max_f32_e32 v138, 0, v138
	v_max_f32_e32 v139, 0, v139
	v_max_f32_e32 v140, 0, v140
	v_max_f32_e32 v141, 0, v141
	v_sqrt_f32_e32 v138, v138
	v_sqrt_f32_e32 v139, v139
	v_sqrt_f32_e32 v140, v140
	v_sqrt_f32_e32 v141, v141
	s_nop 0
	v_pk_mul_f32 v[98:99], v[138:139], v[98:99]
	v_pk_mul_f32 v[100:101], v[140:141], v[100:101]
	v_pk_add_f32 v[12:13], v[12:13], v[74:75] op_sel:[0,1]
	v_pk_add_f32 v[14:15], v[14:15], v[74:75] op_sel:[0,1]
	v_pk_add_f32 v[102:103], v[102:103], v[84:85] op_sel_hi:[1,0]
	v_pk_add_f32 v[104:105], v[104:105], v[84:85] op_sel_hi:[1,0]
	v_exp_f32_e32 v12, v12
	v_exp_f32_e32 v13, v13
	v_exp_f32_e32 v14, v14
	v_exp_f32_e32 v15, v15
	v_exp_f32_e32 v102, v102
	v_exp_f32_e32 v103, v103
	v_exp_f32_e32 v104, v104
	v_exp_f32_e32 v105, v105
	v_pk_add_f32 v[12:13], v[12:13], v[132:133] op_sel_hi:[1,0]
	v_pk_add_f32 v[14:15], v[14:15], v[132:133] op_sel_hi:[1,0]
	v_pk_add_f32 v[102:103], v[102:103], v[132:133] op_sel_hi:[1,0]
	v_pk_add_f32 v[104:105], v[104:105], v[132:133] op_sel_hi:[1,0]
	v_rcp_f32_e32 v12, v12
	v_rcp_f32_e32 v13, v13
	v_rcp_f32_e32 v14, v14
	v_rcp_f32_e32 v15, v15
	v_rcp_f32_e32 v102, v102
	v_rcp_f32_e32 v103, v103
	v_rcp_f32_e32 v104, v104
	v_rcp_f32_e32 v105, v105
	v_pk_mul_f32 v[12:13], v[12:13], v[84:85] op_sel:[0,1]
	v_pk_mul_f32 v[14:15], v[14:15], v[84:85] op_sel:[0,1]
	v_pk_mul_f32 v[102:103], v[102:103], v[174:175]
	v_pk_mul_f32 v[104:105], v[104:105], v[176:177]
	v_exp_f32_e32 v12, v12
	v_exp_f32_e32 v13, v13
	v_exp_f32_e32 v14, v14
	v_exp_f32_e32 v15, v15
	s_nop 0
	v_pk_fma_f32 v[138:139], v[12:13], v[12:13], v[132:133] op_sel_hi:[1,1,0] neg_lo:[1,0,0] neg_hi:[1,0,0]
	v_pk_fma_f32 v[140:141], v[14:15], v[14:15], v[132:133] op_sel_hi:[1,1,0] neg_lo:[1,0,0] neg_hi:[1,0,0]
	v_max_f32_e32 v138, 0, v138
	v_max_f32_e32 v139, 0, v139
	v_max_f32_e32 v140, 0, v140
	v_max_f32_e32 v141, 0, v141
	v_sqrt_f32_e32 v138, v138
	v_sqrt_f32_e32 v139, v139
	v_sqrt_f32_e32 v140, v140
	v_sqrt_f32_e32 v141, v141
	s_nop 0
	v_pk_mul_f32 v[102:103], v[138:139], v[102:103]
	v_pk_mul_f32 v[104:105], v[140:141], v[104:105]
	v_pk_add_f32 v[16:17], v[16:17], v[74:75] op_sel:[0,1]
	v_pk_add_f32 v[18:19], v[18:19], v[74:75] op_sel:[0,1]
	v_pk_add_f32 v[106:107], v[106:107], v[84:85] op_sel_hi:[1,0]
	v_pk_add_f32 v[108:109], v[108:109], v[84:85] op_sel_hi:[1,0]
	v_exp_f32_e32 v16, v16
	v_exp_f32_e32 v17, v17
	v_exp_f32_e32 v18, v18
	v_exp_f32_e32 v19, v19
	v_exp_f32_e32 v106, v106
	v_exp_f32_e32 v107, v107
	v_exp_f32_e32 v108, v108
	v_exp_f32_e32 v109, v109
	v_pk_add_f32 v[16:17], v[16:17], v[132:133] op_sel_hi:[1,0]
	v_pk_add_f32 v[18:19], v[18:19], v[132:133] op_sel_hi:[1,0]
	v_pk_add_f32 v[106:107], v[106:107], v[132:133] op_sel_hi:[1,0]
	v_pk_add_f32 v[108:109], v[108:109], v[132:133] op_sel_hi:[1,0]
	v_rcp_f32_e32 v16, v16
	v_rcp_f32_e32 v17, v17
	v_rcp_f32_e32 v18, v18
	v_rcp_f32_e32 v19, v19
	v_rcp_f32_e32 v106, v106
	v_rcp_f32_e32 v107, v107
	v_rcp_f32_e32 v108, v108
	v_rcp_f32_e32 v109, v109
	v_pk_mul_f32 v[16:17], v[16:17], v[84:85] op_sel:[0,1]
	v_pk_mul_f32 v[18:19], v[18:19], v[84:85] op_sel:[0,1]
	v_pk_mul_f32 v[106:107], v[106:107], v[178:179]
	v_pk_mul_f32 v[108:109], v[108:109], v[180:181]
; __device__ __forceinline__ float bf2f(u16 h) { return __uint_as_float(((unsigned)h) << 16); }
; __device__ __forceinline__ void lru_tile(const Params& P, int chunk, int head, int pass, char* smem_raw) {
;     ...
;       for (int tc = 0; tc < 4; ++tc)
; #pragma unroll
;         for (int reg = 0; reg < 4; ++reg) {
;           const int tl = wid * 16 + (lane >> 4) * 4 + reg;
;           const int c = 16 * tc + (lane & 15);
;           const float r = __builtin_amdgcn_rcpf(1.f + __builtin_amdgcn_exp2f(acc[tc][reg] + ba[tc]));
;           const float ii = __builtin_amdgcn_rcpf(1.f + __builtin_amdgcn_exp2f(acc[tc + 4][reg] + bi[tc]));
;           const float la = -c8[tc] * r;
;           const float a = __builtin_amdgcn_exp2f(la);
;           const float ucv = bf2f(sm_uc[(sb * 64 + tl) * LDSS + c]);
;           const float bt = __builtin_amdgcn_sqrtf(fmaxf(1.f - a * a, 0.f)) * (ii * ucv);
;           sm_a[tl * 64 + c] = a;
;           sm_b[tl * 64 + c] = bt;
;         }
	v_exp_f32_e32 v16, v16
	v_exp_f32_e32 v17, v17
	v_exp_f32_e32 v18, v18
	v_exp_f32_e32 v19, v19
	s_nop 0
	v_pk_fma_f32 v[138:139], v[16:17], v[16:17], v[132:133] op_sel_hi:[1,1,0] neg_lo:[1,0,0] neg_hi:[1,0,0]
	v_pk_fma_f32 v[140:141], v[18:19], v[18:19], v[132:133] op_sel_hi:[1,1,0] neg_lo:[1,0,0] neg_hi:[1,0,0]
	v_max_f32_e32 v138, 0, v138
	v_max_f32_e32 v139, 0, v139
	v_max_f32_e32 v140, 0, v140
	v_max_f32_e32 v141, 0, v141
	v_sqrt_f32_e32 v138, v138
	v_sqrt_f32_e32 v139, v139
	v_sqrt_f32_e32 v140, v140
	v_sqrt_f32_e32 v141, v141
	s_nop 0
	v_pk_mul_f32 v[106:107], v[138:139], v[106:107]
	v_pk_mul_f32 v[108:109], v[140:141], v[108:109]
	v_pk_add_f32 v[20:21], v[20:21], v[74:75] op_sel:[0,1]
	v_pk_add_f32 v[22:23], v[22:23], v[74:75] op_sel:[0,1]
	v_pk_add_f32 v[110:111], v[110:111], v[84:85] op_sel_hi:[1,0]
	v_pk_add_f32 v[112:113], v[112:113], v[84:85] op_sel_hi:[1,0]
	v_exp_f32_e32 v20, v20
	v_exp_f32_e32 v21, v21
	v_exp_f32_e32 v22, v22
	v_exp_f32_e32 v23, v23
	v_exp_f32_e32 v110, v110
	v_exp_f32_e32 v111, v111
	v_exp_f32_e32 v112, v112
	v_exp_f32_e32 v113, v113
	v_pk_add_f32 v[20:21], v[20:21], v[132:133] op_sel_hi:[1,0]
	v_pk_add_f32 v[22:23], v[22:23], v[132:133] op_sel_hi:[1,0]
	v_pk_add_f32 v[110:111], v[110:111], v[132:133] op_sel_hi:[1,0]
	v_pk_add_f32 v[112:113], v[112:113], v[132:133] op_sel_hi:[1,0]
	v_rcp_f32_e32 v20, v20
	v_rcp_f32_e32 v21, v21
	v_rcp_f32_e32 v22, v22
	v_rcp_f32_e32 v23, v23
	v_rcp_f32_e32 v110, v110
	v_rcp_f32_e32 v111, v111
	v_rcp_f32_e32 v112, v112
	v_rcp_f32_e32 v113, v113
	v_pk_mul_f32 v[20:21], v[20:21], v[84:85] op_sel:[0,1]
	v_pk_mul_f32 v[22:23], v[22:23], v[84:85] op_sel:[0,1]
	v_pk_mul_f32 v[110:111], v[110:111], v[182:183]
	v_pk_mul_f32 v[112:113], v[112:113], v[184:185]
	v_exp_f32_e32 v20, v20
	v_exp_f32_e32 v21, v21
	v_exp_f32_e32 v22, v22
	v_exp_f32_e32 v23, v23
	s_nop 0
	v_pk_fma_f32 v[138:139], v[20:21], v[20:21], v[132:133] op_sel_hi:[1,1,0] neg_lo:[1,0,0] neg_hi:[1,0,0]
	v_pk_fma_f32 v[140:141], v[22:23], v[22:23], v[132:133] op_sel_hi:[1,1,0] neg_lo:[1,0,0] neg_hi:[1,0,0]
	v_max_f32_e32 v138, 0, v138
	v_max_f32_e32 v139, 0, v139
	v_max_f32_e32 v140, 0, v140
	v_max_f32_e32 v141, 0, v141
	v_sqrt_f32_e32 v138, v138
	v_sqrt_f32_e32 v139, v139
	v_sqrt_f32_e32 v140, v140
	v_sqrt_f32_e32 v141, v141
	s_nop 0
	v_pk_mul_f32 v[110:111], v[138:139], v[110:111]
	v_pk_mul_f32 v[112:113], v[140:141], v[112:113]
	v_pk_add_f32 v[24:25], v[24:25], v[74:75] op_sel:[0,1]
	v_pk_add_f32 v[26:27], v[26:27], v[74:75] op_sel:[0,1]
	v_pk_add_f32 v[114:115], v[114:115], v[84:85] op_sel_hi:[1,0]
	v_pk_add_f32 v[116:117], v[116:117], v[84:85] op_sel_hi:[1,0]
	v_exp_f32_e32 v24, v24
	v_exp_f32_e32 v25, v25
	v_exp_f32_e32 v26, v26
	v_exp_f32_e32 v27, v27
	v_exp_f32_e32 v114, v114
	v_exp_f32_e32 v115, v115
	v_exp_f32_e32 v116, v116
	v_exp_f32_e32 v117, v117
	v_pk_add_f32 v[24:25], v[24:25], v[132:133] op_sel_hi:[1,0]
	v_pk_add_f32 v[26:27], v[26:27], v[132:133] op_sel_hi:[1,0]
	v_pk_add_f32 v[114:115], v[114:115], v[132:133] op_sel_hi:[1,0]
	v_pk_add_f32 v[116:117], v[116:117], v[132:133] op_sel_hi:[1,0]
	v_rcp_f32_e32 v24, v24
	v_rcp_f32_e32 v25, v25
	v_rcp_f32_e32 v26, v26
	v_rcp_f32_e32 v27, v27
	v_rcp_f32_e32 v114, v114
	v_rcp_f32_e32 v115, v115
	v_rcp_f32_e32 v116, v116
	v_rcp_f32_e32 v117, v117
	v_pk_mul_f32 v[24:25], v[24:25], v[84:85] op_sel:[0,1]
	v_pk_mul_f32 v[26:27], v[26:27], v[84:85] op_sel:[0,1]
	v_pk_mul_f32 v[114:115], v[114:115], v[186:187]
	v_pk_mul_f32 v[116:117], v[116:117], v[188:189]
	v_exp_f32_e32 v24, v24
	v_exp_f32_e32 v25, v25
	v_exp_f32_e32 v26, v26
	v_exp_f32_e32 v27, v27
	s_nop 0
	v_pk_fma_f32 v[138:139], v[24:25], v[24:25], v[132:133] op_sel_hi:[1,1,0] neg_lo:[1,0,0] neg_hi:[1,0,0]
	v_pk_fma_f32 v[140:141], v[26:27], v[26:27], v[132:133] op_sel_hi:[1,1,0] neg_lo:[1,0,0] neg_hi:[1,0,0]
	v_max_f32_e32 v138, 0, v138
	v_max_f32_e32 v139, 0, v139
	v_max_f32_e32 v140, 0, v140
	v_max_f32_e32 v141, 0, v141
	v_sqrt_f32_e32 v138, v138
	v_sqrt_f32_e32 v139, v139
	v_sqrt_f32_e32 v140, v140
	v_sqrt_f32_e32 v141, v141
	s_nop 0
	v_pk_mul_f32 v[114:115], v[138:139], v[114:115]
	v_pk_mul_f32 v[116:117], v[140:141], v[116:117]
	v_pk_add_f32 v[28:29], v[28:29], v[74:75] op_sel:[0,1]
	v_pk_add_f32 v[30:31], v[30:31], v[74:75] op_sel:[0,1]
	v_pk_add_f32 v[118:119], v[118:119], v[84:85] op_sel_hi:[1,0]
	v_pk_add_f32 v[120:121], v[120:121], v[84:85] op_sel_hi:[1,0]
	v_exp_f32_e32 v28, v28
	v_exp_f32_e32 v29, v29
	v_exp_f32_e32 v30, v30
	v_exp_f32_e32 v31, v31
	v_exp_f32_e32 v118, v118
	v_exp_f32_e32 v119, v119
	v_exp_f32_e32 v120, v120
	v_exp_f32_e32 v121, v121
	v_pk_add_f32 v[28:29], v[28:29], v[132:133] op_sel_hi:[1,0]
	v_pk_add_f32 v[30:31], v[30:31], v[132:133] op_sel_hi:[1,0]
	v_pk_add_f32 v[118:119], v[118:119], v[132:133] op_sel_hi:[1,0]
	v_pk_add_f32 v[120:121], v[120:121], v[132:133] op_sel_hi:[1,0]
	v_rcp_f32_e32 v28, v28
	v_rcp_f32_e32 v29, v29
	v_rcp_f32_e32 v30, v30
	v_rcp_f32_e32 v31, v31
	v_rcp_f32_e32 v118, v118
	v_rcp_f32_e32 v119, v119
	v_rcp_f32_e32 v120, v120
	v_rcp_f32_e32 v121, v121
	v_pk_mul_f32 v[28:29], v[28:29], v[84:85] op_sel:[0,1]
	v_pk_mul_f32 v[30:31], v[30:31], v[84:85] op_sel:[0,1]
	v_pk_mul_f32 v[118:119], v[118:119], v[190:191]
	v_pk_mul_f32 v[120:121], v[120:121], v[192:193]
	v_exp_f32_e32 v28, v28
	v_exp_f32_e32 v29, v29
	v_exp_f32_e32 v30, v30
	v_exp_f32_e32 v31, v31
	s_nop 0
	v_pk_fma_f32 v[138:139], v[28:29], v[28:29], v[132:133] op_sel_hi:[1,1,0] neg_lo:[1,0,0] neg_hi:[1,0,0]
	v_pk_fma_f32 v[140:141], v[30:31], v[30:31], v[132:133] op_sel_hi:[1,1,0] neg_lo:[1,0,0] neg_hi:[1,0,0]
	v_max_f32_e32 v138, 0, v138
	v_max_f32_e32 v139, 0, v139
	v_max_f32_e32 v140, 0, v140
; __device__ __forceinline__ float bf2f(u16 h) { return __uint_as_float(((unsigned)h) << 16); }
; __device__ __forceinline__ void lru_tile(const Params& P, int chunk, int head, int pass, char* smem_raw) {
;     ...
;         float Pp = 1.f, H = 0.f;
; #pragma unroll 4
;         for (int i = 0; i < 16; ++i) {
;           const int tl = (d == 0) ? (q * 16 + i) : (q * 16 + 15 - i);
;           const float a = sm_a[tl * 64 + ch], b = sm_b[tl * 64 + ch];
;           H = a * H + b; Pp *= a;
;         }
;         sm_ph[pos * 64 + ch] = make_float2(Pp, H);
;       }
;       __syncthreads();
;       const float2 p0 = sm_ph[ch], p1 = sm_ph[64 + ch], p2 = sm_ph[128 + ch], p3 = sm_ph[192 + ch];
;       if (pass == 2) {
;         float hin = cB;
;         if (pos > 0) hin = p0.x * hin + p0.y;
;         if (pos > 1) hin = p1.x * hin + p1.y;
;         if (pos > 2) hin = p2.x * hin + p2.y;
;         float h = hin;
;         float hfp[16], gp[16];
;         if (d == 1) {
; #pragma unroll
;           for (int i = 0; i < 16; ++i) {
;             const long rowp = row0 + sb * 64 + q * 16 + 15 - i;
;             hfp[i] = hfbuf[rowp * 512 + gch];
;             gp[i] = bf2f(P.zq[rowp * 1536 + 512 + gch]);
;           }
;         }
; #pragma unroll
;         for (int i = 0; i < 16; ++i) {
;           const int tl = (d == 0) ? (q * 16 + i) : (q * 16 + 15 - i);
;           const float a = sm_a[tl * 64 + ch], b = sm_b[tl * 64 + ch];
;           h = a * h + b;
	v_max_f32_e32 v141, 0, v141
	v_sqrt_f32_e32 v138, v138
	v_sqrt_f32_e32 v139, v139
	v_sqrt_f32_e32 v140, v140
	v_sqrt_f32_e32 v141, v141
	s_nop 0
	v_pk_mul_f32 v[118:119], v[138:139], v[118:119]
	v_pk_mul_f32 v[120:121], v[140:141], v[120:121]
	v_mov_b32_e32 v253, v0
	v_mov_b32_e32 v254, v90
	v_fma_f32 v254, v1, v254, v91
	v_mul_f32_e32 v253, v253, v1
	v_fma_f32 v254, v2, v254, v92
	v_mul_f32_e32 v253, v253, v2
	v_fma_f32 v254, v3, v254, v93
	v_mul_f32_e32 v253, v253, v3
	v_fma_f32 v254, v4, v254, v94
	v_mul_f32_e32 v253, v253, v4
	v_fma_f32 v254, v5, v254, v95
	v_mul_f32_e32 v253, v253, v5
	v_fma_f32 v254, v6, v254, v96
	v_mul_f32_e32 v253, v253, v6
	v_fma_f32 v254, v7, v254, v97
	v_mul_f32_e32 v253, v253, v7
	v_fma_f32 v254, v8, v254, v98
	v_mul_f32_e32 v253, v253, v8
	v_fma_f32 v254, v9, v254, v99
	v_mul_f32_e32 v253, v253, v9
	v_fma_f32 v254, v10, v254, v100
	v_mul_f32_e32 v253, v253, v10
	v_fma_f32 v254, v11, v254, v101
	v_mul_f32_e32 v253, v253, v11
	v_fma_f32 v254, v12, v254, v102
	v_mul_f32_e32 v253, v253, v12
	v_fma_f32 v254, v13, v254, v103
	v_mul_f32_e32 v253, v253, v13
	v_fma_f32 v254, v14, v254, v104
	v_mul_f32_e32 v253, v253, v14
	v_fma_f32 v254, v15, v254, v105
	v_mul_f32_e32 v253, v253, v15
	v_fma_f32 v254, v16, v254, v106
	v_mul_f32_e32 v253, v253, v16
	v_fma_f32 v254, v17, v254, v107
	v_mul_f32_e32 v253, v253, v17
	v_fma_f32 v254, v18, v254, v108
	v_mul_f32_e32 v253, v253, v18
	v_fma_f32 v254, v19, v254, v109
	v_mul_f32_e32 v253, v253, v19
	v_fma_f32 v254, v20, v254, v110
	v_mul_f32_e32 v253, v253, v20
	v_fma_f32 v254, v21, v254, v111
	v_mul_f32_e32 v253, v253, v21
	v_fma_f32 v254, v22, v254, v112
	v_mul_f32_e32 v253, v253, v22
	v_fma_f32 v254, v23, v254, v113
	v_mul_f32_e32 v253, v253, v23
	v_fma_f32 v254, v24, v254, v114
	v_mul_f32_e32 v253, v253, v24
	v_fma_f32 v254, v25, v254, v115
	v_mul_f32_e32 v253, v253, v25
	v_fma_f32 v254, v26, v254, v116
	v_mul_f32_e32 v253, v253, v26
	v_fma_f32 v254, v27, v254, v117
	v_mul_f32_e32 v253, v253, v27
	v_fma_f32 v254, v28, v254, v118
	v_mul_f32_e32 v253, v253, v28
	v_fma_f32 v254, v29, v254, v119
	v_mul_f32_e32 v253, v253, v29
	v_fma_f32 v254, v30, v254, v120
	v_mul_f32_e32 v253, v253, v30
	v_fma_f32 v254, v31, v254, v121
	v_mul_f32_e32 v253, v253, v31
	v_mov_b32_e32 v138, v253
	v_mov_b32_e32 v139, v253
	s_nop 1
	v_permlane16_swap_b32_e32 v138, v139
	v_mov_b32_e32 v140, v138
	v_mov_b32_e32 v141, v139
	s_nop 1
	v_permlane32_swap_b32_e32 v138, v140
	v_permlane32_swap_b32_e32 v139, v141
	v_mov_b32_e32 v198, v254
	v_mov_b32_e32 v199, v254
	s_nop 1
	v_permlane16_swap_b32_e32 v198, v199
	v_mov_b32_e32 v200, v198
	v_mov_b32_e32 v201, v199
	s_nop 1
	v_permlane32_swap_b32_e32 v198, v200
	v_permlane32_swap_b32_e32 v199, v201
	v_mov_b32_e32 v136, v148
	v_fma_f32 v150, v138, v136, v198
	v_fma_f32 v151, v139, v150, v199
	v_fma_f32 v202, v140, v151, v200
	v_mov_b32_e32 v254, v136
	v_cndmask_b32_e64 v254, v254, v150, s[72:73]
	v_cndmask_b32_e64 v254, v254, v151, s[74:75]
	v_cndmask_b32_e64 v254, v254, v202, s[76:77]
	v_fma_f32 v205, v0, v254, v90
	v_fma_f32 v206, v1, v205, v91
	v_fma_f32 v207, v2, v206, v92
	v_fma_f32 v208, v3, v207, v93
	v_fma_f32 v209, v4, v208, v94
	v_fma_f32 v210, v5, v209, v95
	v_fma_f32 v211, v6, v210, v96
	v_fma_f32 v212, v7, v211, v97
	v_fma_f32 v213, v8, v212, v98
	v_fma_f32 v214, v9, v213, v99
	v_fma_f32 v215, v10, v214, v100
	v_fma_f32 v216, v11, v215, v101
	v_fma_f32 v217, v12, v216, v102
	v_fma_f32 v218, v13, v217, v103
	v_fma_f32 v219, v14, v218, v104
	v_fma_f32 v220, v15, v219, v105
	v_fma_f32 v221, v16, v220, v106
	v_fma_f32 v222, v17, v221, v107
	v_fma_f32 v223, v18, v222, v108
	v_fma_f32 v224, v19, v223, v109
	v_fma_f32 v225, v20, v224, v110
	v_fma_f32 v226, v21, v225, v111
	v_fma_f32 v227, v22, v226, v112
	v_fma_f32 v228, v23, v227, v113
	v_fma_f32 v229, v24, v228, v114
	v_fma_f32 v230, v25, v229, v115
	v_fma_f32 v231, v26, v230, v116
	v_fma_f32 v232, v27, v231, v117
	v_fma_f32 v233, v28, v232, v118
	v_fma_f32 v234, v29, v233, v119
	v_fma_f32 v235, v30, v234, v120
	v_fma_f32 v236, v31, v235, v121
	ds_read_b128 v[76:79], v131 offset:0
	ds_read_b128 v[80:83], v133 offset:0
	ds_read_b128 v[122:125], v131 offset:512
	ds_read_b128 v[126:129], v133 offset:512
	s_waitcnt vmcnt(0)
	s_waitcnt lgkmcnt(3)
	v_mfma_f32_16x16x32_bf16 v[0:3], v[76:79], v[238:241], 0
	v_mfma_f32_16x16x32_bf16 v[90:93], v[76:79], v[246:249], 0
	ds_read_b128 v[76:79], v131 offset:1024
	s_waitcnt lgkmcnt(3)
	v_mfma_f32_16x16x32_bf16 v[0:3], v[80:83], v[242:245], v[0:3]
	v_mfma_f32_16x16x32_bf16 v[90:93], v[80:83], v[194:197], v[90:93]
	ds_read_b128 v[80:83], v133 offset:1024
	s_waitcnt lgkmcnt(3)
	v_mfma_f32_16x16x32_bf16 v[4:7], v[122:125], v[238:241], 0
	v_mfma_f32_16x16x32_bf16 v[94:97], v[122:125], v[246:249], 0
	ds_read_b128 v[122:125], v131 offset:1536
	s_waitcnt lgkmcnt(3)
	v_mfma_f32_16x16x32_bf16 v[4:7], v[126:129], v[242:245], v[4:7]
	v_mfma_f32_16x16x32_bf16 v[94:97], v[126:129], v[194:197], v[94:97]
	ds_read_b128 v[126:129], v133 offset:1536
	s_waitcnt lgkmcnt(3)
	v_mfma_f32_16x16x32_bf16 v[8:11], v[76:79], v[238:241], 0
	v_mfma_f32_16x16x32_bf16 v[98:101], v[76:79], v[246:249], 0
	ds_read_b128 v[76:79], v131 offset:2048
	s_waitcnt lgkmcnt(3)
	v_mfma_f32_16x16x32_bf16 v[8:11], v[80:83], v[242:245], v[8:11]
	v_mfma_f32_16x16x32_bf16 v[98:101], v[80:83], v[194:197], v[98:101]
	ds_read_b128 v[80:83], v133 offset:2048
	s_waitcnt lgkmcnt(3)
	v_mfma_f32_16x16x32_bf16 v[12:15], v[122:125], v[238:241], 0
	v_mfma_f32_16x16x32_bf16 v[102:105], v[122:125], v[246:249], 0
	ds_read_b128 v[122:125], v131 offset:2560
	s_waitcnt lgkmcnt(3)
; __device__ __forceinline__ float bf2f(u16 h) { return __uint_as_float(((unsigned)h) << 16); }
; __device__ __forceinline__ void lru_tile(const Params& P, int chunk, int head, int pass, char* smem_raw) {
;     ...
;       for (int s = 0; s < 2; ++s) {
;         const bf16x8 af = *reinterpret_cast<const bf16x8*>(&sm_uc[(sb * 64 + wid * 16 + (lane & 15)) * LDSS + s * 32 + (lane >> 4) * 8]);
; #pragma unroll
;         for (int t = 0; t < 8; ++t) {
;           const bf16x8 bfr = *reinterpret_cast<const bf16x8*>(&sm_w[(t * 16 + (lane & 15)) * LDSS + s * 32 + (lane >> 4) * 8]);
;           acc[t] = __builtin_amdgcn_mfma_f32_16x16x32_bf16(af, bfr, acc[t], 0, 0, 0);
;         }
;       }
; #pragma unroll
;       for (int tc = 0; tc < 4; ++tc)
; #pragma unroll
;         for (int reg = 0; reg < 4; ++reg) {
;           const int tl = wid * 16 + (lane >> 4) * 4 + reg;
;           const int c = 16 * tc + (lane & 15);
;           const float r = __builtin_amdgcn_rcpf(1.f + __builtin_amdgcn_exp2f(acc[tc][reg] + ba[tc]));
;           const float ii = __builtin_amdgcn_rcpf(1.f + __builtin_amdgcn_exp2f(acc[tc + 4][reg] + bi[tc]));
;           const float la = -c8[tc] * r;
;           const float a = __builtin_amdgcn_exp2f(la);
;           const float ucv = bf2f(sm_uc[(sb * 64 + tl) * LDSS + c]);
;           const float bt = __builtin_amdgcn_sqrtf(fmaxf(1.f - a * a, 0.f)) * (ii * ucv);
;           sm_a[tl * 64 + c] = a;
;           sm_b[tl * 64 + c] = bt;
;         }
	v_mfma_f32_16x16x32_bf16 v[12:15], v[126:129], v[242:245], v[12:15]
	v_mfma_f32_16x16x32_bf16 v[102:105], v[126:129], v[194:197], v[102:105]
	ds_read_b128 v[126:129], v133 offset:2560
	s_waitcnt lgkmcnt(3)
	v_mfma_f32_16x16x32_bf16 v[16:19], v[76:79], v[238:241], 0
	v_mfma_f32_16x16x32_bf16 v[106:109], v[76:79], v[246:249], 0
	ds_read_b128 v[76:79], v131 offset:3072
	s_waitcnt lgkmcnt(3)
	v_mfma_f32_16x16x32_bf16 v[16:19], v[80:83], v[242:245], v[16:19]
	v_mfma_f32_16x16x32_bf16 v[106:109], v[80:83], v[194:197], v[106:109]
	ds_read_b128 v[80:83], v133 offset:3072
	s_waitcnt lgkmcnt(3)
	v_mfma_f32_16x16x32_bf16 v[20:23], v[122:125], v[238:241], 0
	v_mfma_f32_16x16x32_bf16 v[110:113], v[122:125], v[246:249], 0
	ds_read_b128 v[122:125], v131 offset:3584
	s_waitcnt lgkmcnt(3)
	v_mfma_f32_16x16x32_bf16 v[20:23], v[126:129], v[242:245], v[20:23]
	v_mfma_f32_16x16x32_bf16 v[110:113], v[126:129], v[194:197], v[110:113]
	ds_read_b128 v[126:129], v133 offset:3584
	s_waitcnt lgkmcnt(3)
	v_mfma_f32_16x16x32_bf16 v[24:27], v[76:79], v[238:241], 0
	v_mfma_f32_16x16x32_bf16 v[114:117], v[76:79], v[246:249], 0
	s_waitcnt lgkmcnt(2)
	v_mfma_f32_16x16x32_bf16 v[24:27], v[80:83], v[242:245], v[24:27]
	v_mfma_f32_16x16x32_bf16 v[114:117], v[80:83], v[194:197], v[114:117]
	s_waitcnt lgkmcnt(1)
	v_mfma_f32_16x16x32_bf16 v[28:31], v[122:125], v[238:241], 0
	v_mfma_f32_16x16x32_bf16 v[118:121], v[122:125], v[246:249], 0
	s_waitcnt lgkmcnt(0)
	v_mfma_f32_16x16x32_bf16 v[28:31], v[126:129], v[242:245], v[28:31]
	v_mfma_f32_16x16x32_bf16 v[118:121], v[126:129], v[194:197], v[118:121]
	s_lshl_b32 s0, s56, 8
	s_add_u32 s0, s0, 0x0
	s_add_u32 s4, s20, s0
	s_addc_u32 s5, s21, 0
	global_load_dwordx4 v[238:241], v251, s[4:5]
	global_load_dwordx4 v[242:245], v251, s[4:5] offset:64
	s_add_u32 s4, s4, 0x2000
	s_addc_u32 s5, s5, 0
	global_load_dwordx4 v[246:249], v251, s[4:5]
	global_load_dwordx4 v[194:197], v251, s[4:5] offset:64
	s_nop 7
	s_nop 7
	v_pk_add_f32 v[0:1], v[0:1], v[144:145] op_sel:[0,1]
	v_pk_add_f32 v[2:3], v[2:3], v[144:145] op_sel:[0,1]
	v_pk_add_f32 v[90:91], v[90:91], v[146:147] op_sel_hi:[1,0]
	v_pk_add_f32 v[92:93], v[92:93], v[146:147] op_sel_hi:[1,0]
	v_exp_f32_e32 v0, v0
	v_exp_f32_e32 v1, v1
	v_exp_f32_e32 v2, v2
	v_exp_f32_e32 v3, v3
	v_exp_f32_e32 v90, v90
	v_exp_f32_e32 v91, v91
	v_exp_f32_e32 v92, v92
	v_exp_f32_e32 v93, v93
	v_pk_add_f32 v[0:1], v[0:1], v[132:133] op_sel_hi:[1,0]
	v_pk_add_f32 v[2:3], v[2:3], v[132:133] op_sel_hi:[1,0]
	v_pk_add_f32 v[90:91], v[90:91], v[132:133] op_sel_hi:[1,0]
	v_pk_add_f32 v[92:93], v[92:93], v[132:133] op_sel_hi:[1,0]
	v_rcp_f32_e32 v0, v0
	v_rcp_f32_e32 v1, v1
	v_rcp_f32_e32 v2, v2
	v_rcp_f32_e32 v3, v3
	v_rcp_f32_e32 v90, v90
	v_rcp_f32_e32 v91, v91
	v_rcp_f32_e32 v92, v92
	v_rcp_f32_e32 v93, v93
	v_pk_mul_f32 v[0:1], v[0:1], v[146:147] op_sel:[0,1]
	v_pk_mul_f32 v[2:3], v[2:3], v[146:147] op_sel:[0,1]
	v_pk_mul_f32 v[90:91], v[90:91], v[162:163]
	v_pk_mul_f32 v[92:93], v[92:93], v[164:165]
	v_exp_f32_e32 v0, v0
	v_exp_f32_e32 v1, v1
	v_exp_f32_e32 v2, v2
	v_exp_f32_e32 v3, v3
	s_nop 0
	v_pk_fma_f32 v[138:139], v[0:1], v[0:1], v[132:133] op_sel_hi:[1,1,0] neg_lo:[1,0,0] neg_hi:[1,0,0]
	v_pk_fma_f32 v[140:141], v[2:3], v[2:3], v[132:133] op_sel_hi:[1,1,0] neg_lo:[1,0,0] neg_hi:[1,0,0]
	v_max_f32_e32 v138, 0, v138
	v_max_f32_e32 v139, 0, v139
	v_max_f32_e32 v140, 0, v140
	v_max_f32_e32 v141, 0, v141
	v_sqrt_f32_e32 v138, v138
	v_sqrt_f32_e32 v139, v139
	v_sqrt_f32_e32 v140, v140
	v_sqrt_f32_e32 v141, v141
	s_nop 0
	v_pk_mul_f32 v[90:91], v[138:139], v[90:91]
	v_pk_mul_f32 v[92:93], v[140:141], v[92:93]
	v_pk_add_f32 v[4:5], v[4:5], v[144:145] op_sel:[0,1]
	v_pk_add_f32 v[6:7], v[6:7], v[144:145] op_sel:[0,1]
	v_pk_add_f32 v[94:95], v[94:95], v[146:147] op_sel_hi:[1,0]
	v_pk_add_f32 v[96:97], v[96:97], v[146:147] op_sel_hi:[1,0]
	v_exp_f32_e32 v4, v4
	v_exp_f32_e32 v5, v5
	v_exp_f32_e32 v6, v6
	v_exp_f32_e32 v7, v7
	v_exp_f32_e32 v94, v94
	v_exp_f32_e32 v95, v95
	v_exp_f32_e32 v96, v96
	v_exp_f32_e32 v97, v97
	v_pk_add_f32 v[4:5], v[4:5], v[132:133] op_sel_hi:[1,0]
	v_pk_add_f32 v[6:7], v[6:7], v[132:133] op_sel_hi:[1,0]
	v_pk_add_f32 v[94:95], v[94:95], v[132:133] op_sel_hi:[1,0]
	v_pk_add_f32 v[96:97], v[96:97], v[132:133] op_sel_hi:[1,0]
	v_rcp_f32_e32 v4, v4
	v_rcp_f32_e32 v5, v5
	v_rcp_f32_e32 v6, v6
	v_rcp_f32_e32 v7, v7
	v_rcp_f32_e32 v94, v94
	v_rcp_f32_e32 v95, v95
	v_rcp_f32_e32 v96, v96
	v_rcp_f32_e32 v97, v97
	v_pk_mul_f32 v[4:5], v[4:5], v[146:147] op_sel:[0,1]
	v_pk_mul_f32 v[6:7], v[6:7], v[146:147] op_sel:[0,1]
	v_pk_mul_f32 v[94:95], v[94:95], v[166:167]
	v_pk_mul_f32 v[96:97], v[96:97], v[168:169]
	v_exp_f32_e32 v4, v4
	v_exp_f32_e32 v5, v5
	v_exp_f32_e32 v6, v6
	v_exp_f32_e32 v7, v7
	s_nop 0
	v_pk_fma_f32 v[138:139], v[4:5], v[4:5], v[132:133] op_sel_hi:[1,1,0] neg_lo:[1,0,0] neg_hi:[1,0,0]
	v_pk_fma_f32 v[140:141], v[6:7], v[6:7], v[132:133] op_sel_hi:[1,1,0] neg_lo:[1,0,0] neg_hi:[1,0,0]
	v_max_f32_e32 v138, 0, v138
	v_max_f32_e32 v139, 0, v139
	v_max_f32_e32 v140, 0, v140
	v_max_f32_e32 v141, 0, v141
	v_sqrt_f32_e32 v138, v138
	v_sqrt_f32_e32 v139, v139
	v_sqrt_f32_e32 v140, v140
	v_sqrt_f32_e32 v141, v141
	s_nop 0
	v_pk_mul_f32 v[94:95], v[138:139], v[94:95]
	v_pk_mul_f32 v[96:97], v[140:141], v[96:97]
	v_pk_add_f32 v[8:9], v[8:9], v[144:145] op_sel:[0,1]
	v_pk_add_f32 v[10:11], v[10:11], v[144:145] op_sel:[0,1]
	v_pk_add_f32 v[98:99], v[98:99], v[146:147] op_sel_hi:[1,0]
	v_pk_add_f32 v[100:101], v[100:101], v[146:147] op_sel_hi:[1,0]
	v_exp_f32_e32 v8, v8
	v_exp_f32_e32 v9, v9
	v_exp_f32_e32 v10, v10
	v_exp_f32_e32 v11, v11
	v_exp_f32_e32 v98, v98
	v_exp_f32_e32 v99, v99
; __device__ __forceinline__ float bf2f(u16 h) { return __uint_as_float(((unsigned)h) << 16); }
; __device__ __forceinline__ void lru_tile(const Params& P, int chunk, int head, int pass, char* smem_raw) {
;     ...
;       for (int tc = 0; tc < 4; ++tc)
; #pragma unroll
;         for (int reg = 0; reg < 4; ++reg) {
;           const int tl = wid * 16 + (lane >> 4) * 4 + reg;
;           const int c = 16 * tc + (lane & 15);
;           const float r = __builtin_amdgcn_rcpf(1.f + __builtin_amdgcn_exp2f(acc[tc][reg] + ba[tc]));
;           const float ii = __builtin_amdgcn_rcpf(1.f + __builtin_amdgcn_exp2f(acc[tc + 4][reg] + bi[tc]));
;           const float la = -c8[tc] * r;
;           const float a = __builtin_amdgcn_exp2f(la);
;           const float ucv = bf2f(sm_uc[(sb * 64 + tl) * LDSS + c]);
;           const float bt = __builtin_amdgcn_sqrtf(fmaxf(1.f - a * a, 0.f)) * (ii * ucv);
;           sm_a[tl * 64 + c] = a;
;           sm_b[tl * 64 + c] = bt;
;         }
	v_exp_f32_e32 v100, v100
	v_exp_f32_e32 v101, v101
	v_pk_add_f32 v[8:9], v[8:9], v[132:133] op_sel_hi:[1,0]
	v_pk_add_f32 v[10:11], v[10:11], v[132:133] op_sel_hi:[1,0]
	v_pk_add_f32 v[98:99], v[98:99], v[132:133] op_sel_hi:[1,0]
	v_pk_add_f32 v[100:101], v[100:101], v[132:133] op_sel_hi:[1,0]
	v_rcp_f32_e32 v8, v8
	v_rcp_f32_e32 v9, v9
	v_rcp_f32_e32 v10, v10
	v_rcp_f32_e32 v11, v11
	v_rcp_f32_e32 v98, v98
	v_rcp_f32_e32 v99, v99
	v_rcp_f32_e32 v100, v100
	v_rcp_f32_e32 v101, v101
	v_pk_mul_f32 v[8:9], v[8:9], v[146:147] op_sel:[0,1]
	v_pk_mul_f32 v[10:11], v[10:11], v[146:147] op_sel:[0,1]
	v_pk_mul_f32 v[98:99], v[98:99], v[170:171]
	v_pk_mul_f32 v[100:101], v[100:101], v[172:173]
	v_exp_f32_e32 v8, v8
	v_exp_f32_e32 v9, v9
	v_exp_f32_e32 v10, v10
	v_exp_f32_e32 v11, v11
	s_nop 0
	v_pk_fma_f32 v[138:139], v[8:9], v[8:9], v[132:133] op_sel_hi:[1,1,0] neg_lo:[1,0,0] neg_hi:[1,0,0]
	v_pk_fma_f32 v[140:141], v[10:11], v[10:11], v[132:133] op_sel_hi:[1,1,0] neg_lo:[1,0,0] neg_hi:[1,0,0]
	v_max_f32_e32 v138, 0, v138
	v_max_f32_e32 v139, 0, v139
	v_max_f32_e32 v140, 0, v140
	v_max_f32_e32 v141, 0, v141
	v_sqrt_f32_e32 v138, v138
	v_sqrt_f32_e32 v139, v139
	v_sqrt_f32_e32 v140, v140
	v_sqrt_f32_e32 v141, v141
	s_nop 0
	v_pk_mul_f32 v[98:99], v[138:139], v[98:99]
	v_pk_mul_f32 v[100:101], v[140:141], v[100:101]
	v_pk_add_f32 v[12:13], v[12:13], v[144:145] op_sel:[0,1]
	v_pk_add_f32 v[14:15], v[14:15], v[144:145] op_sel:[0,1]
	v_pk_add_f32 v[102:103], v[102:103], v[146:147] op_sel_hi:[1,0]
	v_pk_add_f32 v[104:105], v[104:105], v[146:147] op_sel_hi:[1,0]
	v_exp_f32_e32 v12, v12
	v_exp_f32_e32 v13, v13
	v_exp_f32_e32 v14, v14
	v_exp_f32_e32 v15, v15
	v_exp_f32_e32 v102, v102
	v_exp_f32_e32 v103, v103
	v_exp_f32_e32 v104, v104
	v_exp_f32_e32 v105, v105
	v_pk_add_f32 v[12:13], v[12:13], v[132:133] op_sel_hi:[1,0]
	v_pk_add_f32 v[14:15], v[14:15], v[132:133] op_sel_hi:[1,0]
	v_pk_add_f32 v[102:103], v[102:103], v[132:133] op_sel_hi:[1,0]
	v_pk_add_f32 v[104:105], v[104:105], v[132:133] op_sel_hi:[1,0]
	v_rcp_f32_e32 v12, v12
	v_rcp_f32_e32 v13, v13
	v_rcp_f32_e32 v14, v14
	v_rcp_f32_e32 v15, v15
	v_rcp_f32_e32 v102, v102
	v_rcp_f32_e32 v103, v103
	v_rcp_f32_e32 v104, v104
	v_rcp_f32_e32 v105, v105
	v_pk_mul_f32 v[12:13], v[12:13], v[146:147] op_sel:[0,1]
	v_pk_mul_f32 v[14:15], v[14:15], v[146:147] op_sel:[0,1]
	v_pk_mul_f32 v[102:103], v[102:103], v[174:175]
	v_pk_mul_f32 v[104:105], v[104:105], v[176:177]
	v_exp_f32_e32 v12, v12
	v_exp_f32_e32 v13, v13
	v_exp_f32_e32 v14, v14
	v_exp_f32_e32 v15, v15
	s_nop 0
	v_pk_fma_f32 v[138:139], v[12:13], v[12:13], v[132:133] op_sel_hi:[1,1,0] neg_lo:[1,0,0] neg_hi:[1,0,0]
	v_pk_fma_f32 v[140:141], v[14:15], v[14:15], v[132:133] op_sel_hi:[1,1,0] neg_lo:[1,0,0] neg_hi:[1,0,0]
	v_max_f32_e32 v138, 0, v138
	v_max_f32_e32 v139, 0, v139
	v_max_f32_e32 v140, 0, v140
	v_max_f32_e32 v141, 0, v141
	v_sqrt_f32_e32 v138, v138
	v_sqrt_f32_e32 v139, v139
	v_sqrt_f32_e32 v140, v140
	v_sqrt_f32_e32 v141, v141
	s_nop 0
	v_pk_mul_f32 v[102:103], v[138:139], v[102:103]
	v_pk_mul_f32 v[104:105], v[140:141], v[104:105]
	v_pk_add_f32 v[16:17], v[16:17], v[144:145] op_sel:[0,1]
	v_pk_add_f32 v[18:19], v[18:19], v[144:145] op_sel:[0,1]
	v_pk_add_f32 v[106:107], v[106:107], v[146:147] op_sel_hi:[1,0]
	v_pk_add_f32 v[108:109], v[108:109], v[146:147] op_sel_hi:[1,0]
	v_exp_f32_e32 v16, v16
	v_exp_f32_e32 v17, v17
	v_exp_f32_e32 v18, v18
	v_exp_f32_e32 v19, v19
	v_exp_f32_e32 v106, v106
	v_exp_f32_e32 v107, v107
	v_exp_f32_e32 v108, v108
	v_exp_f32_e32 v109, v109
	v_pk_add_f32 v[16:17], v[16:17], v[132:133] op_sel_hi:[1,0]
	v_pk_add_f32 v[18:19], v[18:19], v[132:133] op_sel_hi:[1,0]
	v_pk_add_f32 v[106:107], v[106:107], v[132:133] op_sel_hi:[1,0]
	v_pk_add_f32 v[108:109], v[108:109], v[132:133] op_sel_hi:[1,0]
	v_rcp_f32_e32 v16, v16
	v_rcp_f32_e32 v17, v17
	v_rcp_f32_e32 v18, v18
	v_rcp_f32_e32 v19, v19
	v_rcp_f32_e32 v106, v106
	v_rcp_f32_e32 v107, v107
	v_rcp_f32_e32 v108, v108
	v_rcp_f32_e32 v109, v109
	v_pk_mul_f32 v[16:17], v[16:17], v[146:147] op_sel:[0,1]
	v_pk_mul_f32 v[18:19], v[18:19], v[146:147] op_sel:[0,1]
	v_pk_mul_f32 v[106:107], v[106:107], v[178:179]
	v_pk_mul_f32 v[108:109], v[108:109], v[180:181]
	v_exp_f32_e32 v16, v16
	v_exp_f32_e32 v17, v17
	v_exp_f32_e32 v18, v18
	v_exp_f32_e32 v19, v19
	s_nop 0
	v_pk_fma_f32 v[138:139], v[16:17], v[16:17], v[132:133] op_sel_hi:[1,1,0] neg_lo:[1,0,0] neg_hi:[1,0,0]
	v_pk_fma_f32 v[140:141], v[18:19], v[18:19], v[132:133] op_sel_hi:[1,1,0] neg_lo:[1,0,0] neg_hi:[1,0,0]
	v_max_f32_e32 v138, 0, v138
	v_max_f32_e32 v139, 0, v139
	v_max_f32_e32 v140, 0, v140
	v_max_f32_e32 v141, 0, v141
	v_sqrt_f32_e32 v138, v138
	v_sqrt_f32_e32 v139, v139
	v_sqrt_f32_e32 v140, v140
	v_sqrt_f32_e32 v141, v141
	s_nop 0
	v_pk_mul_f32 v[106:107], v[138:139], v[106:107]
	v_pk_mul_f32 v[108:109], v[140:141], v[108:109]
	v_pk_add_f32 v[20:21], v[20:21], v[144:145] op_sel:[0,1]
	v_pk_add_f32 v[22:23], v[22:23], v[144:145] op_sel:[0,1]
	v_pk_add_f32 v[110:111], v[110:111], v[146:147] op_sel_hi:[1,0]
	v_pk_add_f32 v[112:113], v[112:113], v[146:147] op_sel_hi:[1,0]
	v_exp_f32_e32 v20, v20
	v_exp_f32_e32 v21, v21
	v_exp_f32_e32 v22, v22
	v_exp_f32_e32 v23, v23
	v_exp_f32_e32 v110, v110
	v_exp_f32_e32 v111, v111
	v_exp_f32_e32 v112, v112
	v_exp_f32_e32 v113, v113
	v_pk_add_f32 v[20:21], v[20:21], v[132:133] op_sel_hi:[1,0]
	v_pk_add_f32 v[22:23], v[22:23], v[132:133] op_sel_hi:[1,0]
	v_pk_add_f32 v[110:111], v[110:111], v[132:133] op_sel_hi:[1,0]
	v_pk_add_f32 v[112:113], v[112:113], v[132:133] op_sel_hi:[1,0]
	v_rcp_f32_e32 v20, v20
	v_rcp_f32_e32 v21, v21
	v_rcp_f32_e32 v22, v22
	v_rcp_f32_e32 v23, v23
; __device__ __forceinline__ float bf2f(u16 h) { return __uint_as_float(((unsigned)h) << 16); }
; __device__ __forceinline__ void lru_tile(const Params& P, int chunk, int head, int pass, char* smem_raw) {
;     ...
;           const float r = __builtin_amdgcn_rcpf(1.f + __builtin_amdgcn_exp2f(acc[tc][reg] + ba[tc]));
;           const float ii = __builtin_amdgcn_rcpf(1.f + __builtin_amdgcn_exp2f(acc[tc + 4][reg] + bi[tc]));
;           const float la = -c8[tc] * r;
;           const float a = __builtin_amdgcn_exp2f(la);
;           const float ucv = bf2f(sm_uc[(sb * 64 + tl) * LDSS + c]);
;           const float bt = __builtin_amdgcn_sqrtf(fmaxf(1.f - a * a, 0.f)) * (ii * ucv);
;     ...
;             const long rowp = row0 + sb * 64 + q * 16 + 15 - i;
;             hfp[i] = hfbuf[rowp * 512 + gch];
;             gp[i] = bf2f(P.zq[rowp * 1536 + 512 + gch]);
	v_rcp_f32_e32 v110, v110
	v_rcp_f32_e32 v111, v111
	v_rcp_f32_e32 v112, v112
	v_rcp_f32_e32 v113, v113
	v_pk_mul_f32 v[20:21], v[20:21], v[146:147] op_sel:[0,1]
	v_pk_mul_f32 v[22:23], v[22:23], v[146:147] op_sel:[0,1]
	v_pk_mul_f32 v[110:111], v[110:111], v[182:183]
	v_pk_mul_f32 v[112:113], v[112:113], v[184:185]
	v_exp_f32_e32 v20, v20
	v_exp_f32_e32 v21, v21
	v_exp_f32_e32 v22, v22
	v_exp_f32_e32 v23, v23
	s_nop 0
	v_pk_fma_f32 v[138:139], v[20:21], v[20:21], v[132:133] op_sel_hi:[1,1,0] neg_lo:[1,0,0] neg_hi:[1,0,0]
	v_pk_fma_f32 v[140:141], v[22:23], v[22:23], v[132:133] op_sel_hi:[1,1,0] neg_lo:[1,0,0] neg_hi:[1,0,0]
	v_max_f32_e32 v138, 0, v138
	v_max_f32_e32 v139, 0, v139
	v_max_f32_e32 v140, 0, v140
	v_max_f32_e32 v141, 0, v141
	v_sqrt_f32_e32 v138, v138
	v_sqrt_f32_e32 v139, v139
	v_sqrt_f32_e32 v140, v140
	v_sqrt_f32_e32 v141, v141
	s_nop 0
	v_pk_mul_f32 v[110:111], v[138:139], v[110:111]
	v_pk_mul_f32 v[112:113], v[140:141], v[112:113]
	v_pk_add_f32 v[24:25], v[24:25], v[144:145] op_sel:[0,1]
	v_pk_add_f32 v[26:27], v[26:27], v[144:145] op_sel:[0,1]
	v_pk_add_f32 v[114:115], v[114:115], v[146:147] op_sel_hi:[1,0]
	v_pk_add_f32 v[116:117], v[116:117], v[146:147] op_sel_hi:[1,0]
	v_exp_f32_e32 v24, v24
	v_exp_f32_e32 v25, v25
	v_exp_f32_e32 v26, v26
	v_exp_f32_e32 v27, v27
	v_exp_f32_e32 v114, v114
	v_exp_f32_e32 v115, v115
	v_exp_f32_e32 v116, v116
	v_exp_f32_e32 v117, v117
	v_pk_add_f32 v[24:25], v[24:25], v[132:133] op_sel_hi:[1,0]
	v_pk_add_f32 v[26:27], v[26:27], v[132:133] op_sel_hi:[1,0]
	v_pk_add_f32 v[114:115], v[114:115], v[132:133] op_sel_hi:[1,0]
	v_pk_add_f32 v[116:117], v[116:117], v[132:133] op_sel_hi:[1,0]
	v_rcp_f32_e32 v24, v24
	v_rcp_f32_e32 v25, v25
	v_rcp_f32_e32 v26, v26
	v_rcp_f32_e32 v27, v27
	v_rcp_f32_e32 v114, v114
	v_rcp_f32_e32 v115, v115
	v_rcp_f32_e32 v116, v116
	v_rcp_f32_e32 v117, v117
	v_pk_mul_f32 v[24:25], v[24:25], v[146:147] op_sel:[0,1]
	v_pk_mul_f32 v[26:27], v[26:27], v[146:147] op_sel:[0,1]
	v_pk_mul_f32 v[114:115], v[114:115], v[186:187]
	v_pk_mul_f32 v[116:117], v[116:117], v[188:189]
	v_exp_f32_e32 v24, v24
	v_exp_f32_e32 v25, v25
	v_exp_f32_e32 v26, v26
	v_exp_f32_e32 v27, v27
	s_nop 0
	v_pk_fma_f32 v[138:139], v[24:25], v[24:25], v[132:133] op_sel_hi:[1,1,0] neg_lo:[1,0,0] neg_hi:[1,0,0]
	v_pk_fma_f32 v[140:141], v[26:27], v[26:27], v[132:133] op_sel_hi:[1,1,0] neg_lo:[1,0,0] neg_hi:[1,0,0]
	v_max_f32_e32 v138, 0, v138
	v_max_f32_e32 v139, 0, v139
	v_max_f32_e32 v140, 0, v140
	v_max_f32_e32 v141, 0, v141
	v_sqrt_f32_e32 v138, v138
	v_sqrt_f32_e32 v139, v139
	v_sqrt_f32_e32 v140, v140
	v_sqrt_f32_e32 v141, v141
	s_nop 0
	v_pk_mul_f32 v[114:115], v[138:139], v[114:115]
	v_pk_mul_f32 v[116:117], v[140:141], v[116:117]
	v_pk_add_f32 v[28:29], v[28:29], v[144:145] op_sel:[0,1]
	v_pk_add_f32 v[30:31], v[30:31], v[144:145] op_sel:[0,1]
	v_pk_add_f32 v[118:119], v[118:119], v[146:147] op_sel_hi:[1,0]
	v_pk_add_f32 v[120:121], v[120:121], v[146:147] op_sel_hi:[1,0]
	v_exp_f32_e32 v28, v28
	v_exp_f32_e32 v29, v29
	v_exp_f32_e32 v30, v30
	v_exp_f32_e32 v31, v31
	v_exp_f32_e32 v118, v118
	v_exp_f32_e32 v119, v119
	v_exp_f32_e32 v120, v120
	v_exp_f32_e32 v121, v121
	v_pk_add_f32 v[28:29], v[28:29], v[132:133] op_sel_hi:[1,0]
	v_pk_add_f32 v[30:31], v[30:31], v[132:133] op_sel_hi:[1,0]
	v_pk_add_f32 v[118:119], v[118:119], v[132:133] op_sel_hi:[1,0]
	v_pk_add_f32 v[120:121], v[120:121], v[132:133] op_sel_hi:[1,0]
	v_rcp_f32_e32 v28, v28
	v_rcp_f32_e32 v29, v29
	v_rcp_f32_e32 v30, v30
	v_rcp_f32_e32 v31, v31
	v_rcp_f32_e32 v118, v118
	v_rcp_f32_e32 v119, v119
	v_rcp_f32_e32 v120, v120
	v_rcp_f32_e32 v121, v121
	v_pk_mul_f32 v[28:29], v[28:29], v[146:147] op_sel:[0,1]
	v_pk_mul_f32 v[30:31], v[30:31], v[146:147] op_sel:[0,1]
	v_pk_mul_f32 v[118:119], v[118:119], v[190:191]
	v_pk_mul_f32 v[120:121], v[120:121], v[192:193]
	v_exp_f32_e32 v28, v28
	v_exp_f32_e32 v29, v29
	v_exp_f32_e32 v30, v30
	v_exp_f32_e32 v31, v31
	s_nop 0
	v_pk_fma_f32 v[138:139], v[28:29], v[28:29], v[132:133] op_sel_hi:[1,1,0] neg_lo:[1,0,0] neg_hi:[1,0,0]
	v_pk_fma_f32 v[140:141], v[30:31], v[30:31], v[132:133] op_sel_hi:[1,1,0] neg_lo:[1,0,0] neg_hi:[1,0,0]
	v_max_f32_e32 v138, 0, v138
	v_max_f32_e32 v139, 0, v139
	v_max_f32_e32 v140, 0, v140
	v_max_f32_e32 v141, 0, v141
	v_sqrt_f32_e32 v138, v138
	v_sqrt_f32_e32 v139, v139
	v_sqrt_f32_e32 v140, v140
	v_sqrt_f32_e32 v141, v141
	s_nop 0
	v_pk_mul_f32 v[118:119], v[138:139], v[118:119]
	v_pk_mul_f32 v[120:121], v[140:141], v[120:121]
	s_mul_i32 s0, s71, 0x60000
	s_lshl_b32 s1, s56, 1
	s_add_u32 s0, s0, s1
	s_add_u32 s0, s0, 0x400
	s_add_u32 s4, s10, s0
	s_addc_u32 s5, s11, 0
	global_load_ushort v162, v134, s[4:5]
	s_add_u32 s4, s4, 0xc00
	s_addc_u32 s5, s5, 0
	global_load_ushort v163, v134, s[4:5]
	s_add_u32 s4, s4, 0xc00
	s_addc_u32 s5, s5, 0
	global_load_ushort v164, v134, s[4:5]
	s_add_u32 s4, s4, 0xc00
	s_addc_u32 s5, s5, 0
	global_load_ushort v165, v134, s[4:5]
	s_add_u32 s4, s4, 0xc00
	s_addc_u32 s5, s5, 0
	global_load_ushort v166, v134, s[4:5]
	s_add_u32 s4, s4, 0xc00
	s_addc_u32 s5, s5, 0
	global_load_ushort v167, v134, s[4:5]
	s_add_u32 s4, s4, 0xc00
	s_addc_u32 s5, s5, 0
	global_load_ushort v168, v134, s[4:5]
	s_add_u32 s4, s4, 0xc00
	s_addc_u32 s5, s5, 0
	global_load_ushort v169, v134, s[4:5]
	s_add_u32 s4, s4, 0xc00
	s_addc_u32 s5, s5, 0
	global_load_ushort v170, v134, s[4:5]
	s_add_u32 s4, s4, 0xc00
	s_addc_u32 s5, s5, 0
	global_load_ushort v171, v134, s[4:5]
	s_add_u32 s4, s4, 0xc00
	s_addc_u32 s5, s5, 0
	global_load_ushort v172, v134, s[4:5]
	s_add_u32 s4, s4, 0xc00
	s_addc_u32 s5, s5, 0
	global_load_ushort v173, v134, s[4:5]
	s_add_u32 s4, s4, 0xc00
; __device__ __forceinline__ float bf2f(u16 h) { return __uint_as_float(((unsigned)h) << 16); }
; __device__ __forceinline__ void lru_tile(const Params& P, int chunk, int head, int pass, char* smem_raw) {
;     ...
;       {
;         float Pp = 1.f, H = 0.f;
; #pragma unroll 4
;         for (int i = 0; i < 16; ++i) {
;           const int tl = (d == 0) ? (q * 16 + i) : (q * 16 + 15 - i);
;           const float a = sm_a[tl * 64 + ch], b = sm_b[tl * 64 + ch];
;           H = a * H + b; Pp *= a;
;         }
;         sm_ph[pos * 64 + ch] = make_float2(Pp, H);
;       }
;       __syncthreads();
;       const float2 p0 = sm_ph[ch], p1 = sm_ph[64 + ch], p2 = sm_ph[128 + ch], p3 = sm_ph[192 + ch];
;       if (pass == 2) {
;         float hin = cB;
;         if (pos > 0) hin = p0.x * hin + p0.y;
;         if (pos > 1) hin = p1.x * hin + p1.y;
;         if (pos > 2) hin = p2.x * hin + p2.y;
;         float h = hin;
;         float hfp[16], gp[16];
;         if (d == 1) {
; #pragma unroll
;           for (int i = 0; i < 16; ++i) {
;             const long rowp = row0 + sb * 64 + q * 16 + 15 - i;
;             hfp[i] = hfbuf[rowp * 512 + gch];
;             gp[i] = bf2f(P.zq[rowp * 1536 + 512 + gch]);
;           }
;         }
; #pragma unroll
;         for (int i = 0; i < 16; ++i) {
;           const int tl = (d == 0) ? (q * 16 + i) : (q * 16 + 15 - i);
;           const float a = sm_a[tl * 64 + ch], b = sm_b[tl * 64 + ch];
;           h = a * h + b;
	s_addc_u32 s5, s5, 0
	global_load_ushort v174, v134, s[4:5]
	s_add_u32 s4, s4, 0xc00
	s_addc_u32 s5, s5, 0
	global_load_ushort v175, v134, s[4:5]
	s_add_u32 s4, s4, 0xc00
	s_addc_u32 s5, s5, 0
	global_load_ushort v176, v134, s[4:5]
	s_add_u32 s4, s4, 0xc00
	s_addc_u32 s5, s5, 0
	global_load_ushort v177, v134, s[4:5]
	s_add_u32 s4, s4, 0xc00
	s_addc_u32 s5, s5, 0
	global_load_ushort v178, v134, s[4:5]
	s_add_u32 s4, s4, 0xc00
	s_addc_u32 s5, s5, 0
	global_load_ushort v179, v134, s[4:5]
	s_add_u32 s4, s4, 0xc00
	s_addc_u32 s5, s5, 0
	global_load_ushort v180, v134, s[4:5]
	s_add_u32 s4, s4, 0xc00
	s_addc_u32 s5, s5, 0
	global_load_ushort v181, v134, s[4:5]
	s_add_u32 s4, s4, 0xc00
	s_addc_u32 s5, s5, 0
	global_load_ushort v182, v134, s[4:5]
	s_add_u32 s4, s4, 0xc00
	s_addc_u32 s5, s5, 0
	global_load_ushort v183, v134, s[4:5]
	s_add_u32 s4, s4, 0xc00
	s_addc_u32 s5, s5, 0
	global_load_ushort v184, v134, s[4:5]
	s_add_u32 s4, s4, 0xc00
	s_addc_u32 s5, s5, 0
	global_load_ushort v185, v134, s[4:5]
	s_add_u32 s4, s4, 0xc00
	s_addc_u32 s5, s5, 0
	global_load_ushort v186, v134, s[4:5]
	s_add_u32 s4, s4, 0xc00
	s_addc_u32 s5, s5, 0
	global_load_ushort v187, v134, s[4:5]
	s_add_u32 s4, s4, 0xc00
	s_addc_u32 s5, s5, 0
	global_load_ushort v188, v134, s[4:5]
	s_add_u32 s4, s4, 0xc00
	s_addc_u32 s5, s5, 0
	global_load_ushort v189, v134, s[4:5]
	s_add_u32 s4, s4, 0xc00
	s_addc_u32 s5, s5, 0
	global_load_ushort v190, v134, s[4:5]
	s_add_u32 s4, s4, 0xc00
	s_addc_u32 s5, s5, 0
	global_load_ushort v191, v134, s[4:5]
	s_add_u32 s4, s4, 0xc00
	s_addc_u32 s5, s5, 0
	global_load_ushort v192, v134, s[4:5]
	s_add_u32 s4, s4, 0xc00
	s_addc_u32 s5, s5, 0
	global_load_ushort v193, v134, s[4:5]
	v_mov_b32_e32 v253, v31
	v_mov_b32_e32 v254, v121
	v_fma_f32 v254, v30, v254, v120
	v_mul_f32_e32 v253, v253, v30
	v_fma_f32 v254, v29, v254, v119
	v_mul_f32_e32 v253, v253, v29
	v_fma_f32 v254, v28, v254, v118
	v_mul_f32_e32 v253, v253, v28
	v_fma_f32 v254, v27, v254, v117
	v_mul_f32_e32 v253, v253, v27
	v_fma_f32 v254, v26, v254, v116
	v_mul_f32_e32 v253, v253, v26
	v_fma_f32 v254, v25, v254, v115
	v_mul_f32_e32 v253, v253, v25
	v_fma_f32 v254, v24, v254, v114
	v_mul_f32_e32 v253, v253, v24
	v_fma_f32 v254, v23, v254, v113
	v_mul_f32_e32 v253, v253, v23
	v_fma_f32 v254, v22, v254, v112
	v_mul_f32_e32 v253, v253, v22
	v_fma_f32 v254, v21, v254, v111
	v_mul_f32_e32 v253, v253, v21
	v_fma_f32 v254, v20, v254, v110
	v_mul_f32_e32 v253, v253, v20
	v_fma_f32 v254, v19, v254, v109
	v_mul_f32_e32 v253, v253, v19
	v_fma_f32 v254, v18, v254, v108
	v_mul_f32_e32 v253, v253, v18
	v_fma_f32 v254, v17, v254, v107
	v_mul_f32_e32 v253, v253, v17
	v_fma_f32 v254, v16, v254, v106
	v_mul_f32_e32 v253, v253, v16
	v_fma_f32 v254, v15, v254, v105
	v_mul_f32_e32 v253, v253, v15
	v_fma_f32 v254, v14, v254, v104
	v_mul_f32_e32 v253, v253, v14
	v_fma_f32 v254, v13, v254, v103
	v_mul_f32_e32 v253, v253, v13
	v_fma_f32 v254, v12, v254, v102
	v_mul_f32_e32 v253, v253, v12
	v_fma_f32 v254, v11, v254, v101
	v_mul_f32_e32 v253, v253, v11
	v_fma_f32 v254, v10, v254, v100
	v_mul_f32_e32 v253, v253, v10
	v_fma_f32 v254, v9, v254, v99
	v_mul_f32_e32 v253, v253, v9
	v_fma_f32 v254, v8, v254, v98
	v_mul_f32_e32 v253, v253, v8
	v_fma_f32 v254, v7, v254, v97
	v_mul_f32_e32 v253, v253, v7
	v_fma_f32 v254, v6, v254, v96
	v_mul_f32_e32 v253, v253, v6
	v_fma_f32 v254, v5, v254, v95
	v_mul_f32_e32 v253, v253, v5
	v_fma_f32 v254, v4, v254, v94
	v_mul_f32_e32 v253, v253, v4
	v_fma_f32 v254, v3, v254, v93
	v_mul_f32_e32 v253, v253, v3
	v_fma_f32 v254, v2, v254, v92
	v_mul_f32_e32 v253, v253, v2
	v_fma_f32 v254, v1, v254, v91
	v_mul_f32_e32 v253, v253, v1
	v_fma_f32 v254, v0, v254, v90
	v_mul_f32_e32 v253, v253, v0
	v_mov_b32_e32 v138, v253
	v_mov_b32_e32 v139, v253
	s_nop 1
	v_permlane16_swap_b32_e32 v138, v139
	v_mov_b32_e32 v140, v138
	v_mov_b32_e32 v141, v139
	s_nop 1
	v_permlane32_swap_b32_e32 v138, v140
	v_permlane32_swap_b32_e32 v139, v141
	v_mov_b32_e32 v198, v254
	v_mov_b32_e32 v199, v254
	s_nop 1
	v_permlane16_swap_b32_e32 v198, v199
	v_mov_b32_e32 v200, v198
	v_mov_b32_e32 v201, v199
	s_nop 1
	v_permlane32_swap_b32_e32 v198, v200
	v_permlane32_swap_b32_e32 v199, v201
	v_mov_b32_e32 v202, v149
	v_fma_f32 v151, v141, v202, v201
	v_fma_f32 v150, v140, v151, v200
	v_fma_f32 v136, v139, v150, v199
	v_mov_b32_e32 v254, v202
	v_cndmask_b32_e64 v254, v254, v151, s[78:79]
	v_cndmask_b32_e64 v254, v254, v150, s[80:81]
	v_cndmask_b32_e64 v254, v254, v136, s[82:83]
	v_fma_f32 v121, v31, v254, v121
	v_fma_f32 v120, v30, v121, v120
	v_fma_f32 v119, v29, v120, v119
	v_fma_f32 v118, v28, v119, v118
	v_fma_f32 v117, v27, v118, v117
	v_fma_f32 v116, v26, v117, v116
	v_fma_f32 v115, v25, v116, v115
	v_fma_f32 v114, v24, v115, v114
	v_fma_f32 v113, v23, v114, v113
	v_fma_f32 v112, v22, v113, v112
	v_fma_f32 v111, v21, v112, v111
	v_fma_f32 v110, v20, v111, v110
	v_fma_f32 v109, v19, v110, v109
	v_fma_f32 v108, v18, v109, v108
	v_fma_f32 v107, v17, v108, v107
	v_fma_f32 v106, v16, v107, v106
	v_fma_f32 v105, v15, v106, v105
	v_fma_f32 v104, v14, v105, v104
	v_fma_f32 v103, v13, v104, v103
	v_fma_f32 v102, v12, v103, v102
	v_fma_f32 v101, v11, v102, v101
	v_fma_f32 v100, v10, v101, v100
	v_fma_f32 v99, v9, v100, v99
	v_fma_f32 v98, v8, v99, v98
	v_fma_f32 v97, v7, v98, v97
	v_fma_f32 v96, v6, v97, v96
	v_fma_f32 v95, v5, v96, v95
	v_fma_f32 v94, v4, v95, v94
	v_fma_f32 v93, v3, v94, v93
	v_fma_f32 v92, v2, v93, v92
	v_fma_f32 v91, v1, v92, v91
	v_fma_f32 v90, v0, v91, v90
	s_waitcnt vmcnt(0)
; __device__ __forceinline__ void lru_tile(const Params& P, int chunk, int head, int pass, char* smem_raw) {
;     ...
;             const float hfv = hfp[i];
;             const float g = gp[i];
;             const float tz = 0.7978845608028654f * (g + 0.044715f * g * g * g);
;             const float th = 1.f - 2.f * __builtin_amdgcn_rcpf(1.f + __expf(2.f * tz));
;             const float ge = 0.5f * g * (1.f + th);
;             P.cat[row * 1024 + gch] = f2bf((hfv + h) * ge);
	v_lshlrev_b32_e32 v162, 16, v162
	v_lshlrev_b32_e32 v163, 16, v163
	v_lshlrev_b32_e32 v164, 16, v164
	v_lshlrev_b32_e32 v165, 16, v165
	v_lshlrev_b32_e32 v166, 16, v166
	v_lshlrev_b32_e32 v167, 16, v167
	v_lshlrev_b32_e32 v168, 16, v168
	v_lshlrev_b32_e32 v169, 16, v169
	v_lshlrev_b32_e32 v170, 16, v170
	v_lshlrev_b32_e32 v171, 16, v171
	v_lshlrev_b32_e32 v172, 16, v172
	v_lshlrev_b32_e32 v173, 16, v173
	v_lshlrev_b32_e32 v174, 16, v174
	v_lshlrev_b32_e32 v175, 16, v175
	v_lshlrev_b32_e32 v176, 16, v176
	v_lshlrev_b32_e32 v177, 16, v177
	v_lshlrev_b32_e32 v178, 16, v178
	v_lshlrev_b32_e32 v179, 16, v179
	v_lshlrev_b32_e32 v180, 16, v180
	v_lshlrev_b32_e32 v181, 16, v181
	v_lshlrev_b32_e32 v182, 16, v182
	v_lshlrev_b32_e32 v183, 16, v183
	v_lshlrev_b32_e32 v184, 16, v184
	v_lshlrev_b32_e32 v185, 16, v185
	v_lshlrev_b32_e32 v186, 16, v186
	v_lshlrev_b32_e32 v187, 16, v187
	v_lshlrev_b32_e32 v188, 16, v188
	v_lshlrev_b32_e32 v189, 16, v189
	v_lshlrev_b32_e32 v190, 16, v190
	v_lshlrev_b32_e32 v191, 16, v191
	v_lshlrev_b32_e32 v192, 16, v192
	v_lshlrev_b32_e32 v193, 16, v193
	v_mov_b32_e32 v202, 0x3d372713
	v_mul_f32_e32 v138, v162, v162
	v_mul_f32_e32 v139, v163, v163
	v_mul_f32_e32 v140, v164, v164
	v_mul_f32_e32 v141, v165, v165
	v_mul_f32_e32 v138, v138, v162
	v_mul_f32_e32 v139, v139, v163
	v_mul_f32_e32 v140, v140, v164
	v_mul_f32_e32 v141, v141, v165
	v_fma_f32 v138, v202, v138, v162
	v_fma_f32 v139, v202, v139, v163
	v_fma_f32 v140, v202, v140, v164
	v_fma_f32 v141, v202, v141, v165
	v_mul_f32_e32 v138, 0x40135761, v138
	v_mul_f32_e32 v139, 0x40135761, v139
	v_mul_f32_e32 v140, 0x40135761, v140
	v_mul_f32_e32 v141, 0x40135761, v141
	v_exp_f32_e32 v138, v138
	v_exp_f32_e32 v139, v139
	v_exp_f32_e32 v140, v140
	v_exp_f32_e32 v141, v141
	s_nop 0
	v_add_f32_e32 v138, 1.0, v138
	v_add_f32_e32 v139, 1.0, v139
	v_add_f32_e32 v140, 1.0, v140
	v_add_f32_e32 v141, 1.0, v141
	v_rcp_f32_e32 v138, v138
	v_rcp_f32_e32 v139, v139
	v_rcp_f32_e32 v140, v140
	v_rcp_f32_e32 v141, v141
	s_nop 0
	v_fma_f32 v138, -2.0, v138, 1.0
	v_fma_f32 v139, -2.0, v139, 1.0
	v_fma_f32 v140, -2.0, v140, 1.0
	v_fma_f32 v141, -2.0, v141, 1.0
	v_add_f32_e32 v138, 1.0, v138
	v_add_f32_e32 v139, 1.0, v139
	v_add_f32_e32 v140, 1.0, v140
	v_add_f32_e32 v141, 1.0, v141
	v_mul_f32_e32 v162, 0.5, v162
	v_mul_f32_e32 v163, 0.5, v163
	v_mul_f32_e32 v164, 0.5, v164
	v_mul_f32_e32 v165, 0.5, v165
	v_mul_f32_e32 v162, v162, v138
	v_mul_f32_e32 v163, v163, v139
	v_mul_f32_e32 v164, v164, v140
	v_mul_f32_e32 v165, v165, v141
	v_add_f32_e32 v90, v205, v90
	v_add_f32_e32 v91, v206, v91
	v_add_f32_e32 v92, v207, v92
	v_add_f32_e32 v93, v208, v93
	v_mul_f32_e32 v90, v90, v162
	v_mul_f32_e32 v91, v91, v163
	v_mul_f32_e32 v92, v92, v164
	v_mul_f32_e32 v93, v93, v165
	v_cvt_pk_bf16_f32 v90, v90, v90
	v_cvt_pk_bf16_f32 v91, v91, v91
	v_cvt_pk_bf16_f32 v92, v92, v92
	v_cvt_pk_bf16_f32 v93, v93, v93
	v_mul_f32_e32 v138, v166, v166
	v_mul_f32_e32 v139, v167, v167
	v_mul_f32_e32 v140, v168, v168
	v_mul_f32_e32 v141, v169, v169
	v_mul_f32_e32 v138, v138, v166
	v_mul_f32_e32 v139, v139, v167
	v_mul_f32_e32 v140, v140, v168
	v_mul_f32_e32 v141, v141, v169
	v_fma_f32 v138, v202, v138, v166
	v_fma_f32 v139, v202, v139, v167
	v_fma_f32 v140, v202, v140, v168
	v_fma_f32 v141, v202, v141, v169
	v_mul_f32_e32 v138, 0x40135761, v138
	v_mul_f32_e32 v139, 0x40135761, v139
	v_mul_f32_e32 v140, 0x40135761, v140
	v_mul_f32_e32 v141, 0x40135761, v141
	v_exp_f32_e32 v138, v138
	v_exp_f32_e32 v139, v139
	v_exp_f32_e32 v140, v140
	v_exp_f32_e32 v141, v141
	s_nop 0
	v_add_f32_e32 v138, 1.0, v138
	v_add_f32_e32 v139, 1.0, v139
	v_add_f32_e32 v140, 1.0, v140
	v_add_f32_e32 v141, 1.0, v141
	v_rcp_f32_e32 v138, v138
	v_rcp_f32_e32 v139, v139
	v_rcp_f32_e32 v140, v140
	v_rcp_f32_e32 v141, v141
	s_nop 0
	v_fma_f32 v138, -2.0, v138, 1.0
	v_fma_f32 v139, -2.0, v139, 1.0
	v_fma_f32 v140, -2.0, v140, 1.0
	v_fma_f32 v141, -2.0, v141, 1.0
	v_add_f32_e32 v138, 1.0, v138
	v_add_f32_e32 v139, 1.0, v139
	v_add_f32_e32 v140, 1.0, v140
	v_add_f32_e32 v141, 1.0, v141
	v_mul_f32_e32 v166, 0.5, v166
	v_mul_f32_e32 v167, 0.5, v167
	v_mul_f32_e32 v168, 0.5, v168
	v_mul_f32_e32 v169, 0.5, v169
	v_mul_f32_e32 v166, v166, v138
	v_mul_f32_e32 v167, v167, v139
	v_mul_f32_e32 v168, v168, v140
	v_mul_f32_e32 v169, v169, v141
	v_add_f32_e32 v94, v209, v94
	v_add_f32_e32 v95, v210, v95
	v_add_f32_e32 v96, v211, v96
	v_add_f32_e32 v97, v212, v97
	v_mul_f32_e32 v94, v94, v166
	v_mul_f32_e32 v95, v95, v167
	v_mul_f32_e32 v96, v96, v168
	v_mul_f32_e32 v97, v97, v169
	v_cvt_pk_bf16_f32 v94, v94, v94
	v_cvt_pk_bf16_f32 v95, v95, v95
	v_cvt_pk_bf16_f32 v96, v96, v96
	v_cvt_pk_bf16_f32 v97, v97, v97
	v_mul_f32_e32 v138, v170, v170
	v_mul_f32_e32 v139, v171, v171
	v_mul_f32_e32 v140, v172, v172
	v_mul_f32_e32 v141, v173, v173
	v_mul_f32_e32 v138, v138, v170
	v_mul_f32_e32 v139, v139, v171
	v_mul_f32_e32 v140, v140, v172
	v_mul_f32_e32 v141, v141, v173
	v_fma_f32 v138, v202, v138, v170
	v_fma_f32 v139, v202, v139, v171
	v_fma_f32 v140, v202, v140, v172
	v_fma_f32 v141, v202, v141, v173
	v_mul_f32_e32 v138, 0x40135761, v138
	v_mul_f32_e32 v139, 0x40135761, v139
	v_mul_f32_e32 v140, 0x40135761, v140
	v_mul_f32_e32 v141, 0x40135761, v141
	v_exp_f32_e32 v138, v138
	v_exp_f32_e32 v139, v139
	v_exp_f32_e32 v140, v140
	v_exp_f32_e32 v141, v141
	s_nop 0
	v_add_f32_e32 v138, 1.0, v138
	v_add_f32_e32 v139, 1.0, v139
	v_add_f32_e32 v140, 1.0, v140
	v_add_f32_e32 v141, 1.0, v141
	v_rcp_f32_e32 v138, v138
	v_rcp_f32_e32 v139, v139
	v_rcp_f32_e32 v140, v140
	v_rcp_f32_e32 v141, v141
	s_nop 0
	v_fma_f32 v138, -2.0, v138, 1.0
	v_fma_f32 v139, -2.0, v139, 1.0
; __device__ __forceinline__ void lru_tile(const Params& P, int chunk, int head, int pass, char* smem_raw) {
;     ...
;             const float hfv = hfp[i];
;             const float g = gp[i];
;             const float tz = 0.7978845608028654f * (g + 0.044715f * g * g * g);
;             const float th = 1.f - 2.f * __builtin_amdgcn_rcpf(1.f + __expf(2.f * tz));
;             const float ge = 0.5f * g * (1.f + th);
;             P.cat[row * 1024 + gch] = f2bf((hfv + h) * ge);
	v_fma_f32 v140, -2.0, v140, 1.0
	v_fma_f32 v141, -2.0, v141, 1.0
	v_add_f32_e32 v138, 1.0, v138
	v_add_f32_e32 v139, 1.0, v139
	v_add_f32_e32 v140, 1.0, v140
	v_add_f32_e32 v141, 1.0, v141
	v_mul_f32_e32 v170, 0.5, v170
	v_mul_f32_e32 v171, 0.5, v171
	v_mul_f32_e32 v172, 0.5, v172
	v_mul_f32_e32 v173, 0.5, v173
	v_mul_f32_e32 v170, v170, v138
	v_mul_f32_e32 v171, v171, v139
	v_mul_f32_e32 v172, v172, v140
	v_mul_f32_e32 v173, v173, v141
	v_add_f32_e32 v98, v213, v98
	v_add_f32_e32 v99, v214, v99
	v_add_f32_e32 v100, v215, v100
	v_add_f32_e32 v101, v216, v101
	v_mul_f32_e32 v98, v98, v170
	v_mul_f32_e32 v99, v99, v171
	v_mul_f32_e32 v100, v100, v172
	v_mul_f32_e32 v101, v101, v173
	v_cvt_pk_bf16_f32 v98, v98, v98
	v_cvt_pk_bf16_f32 v99, v99, v99
	v_cvt_pk_bf16_f32 v100, v100, v100
	v_cvt_pk_bf16_f32 v101, v101, v101
	v_mul_f32_e32 v138, v174, v174
	v_mul_f32_e32 v139, v175, v175
	v_mul_f32_e32 v140, v176, v176
	v_mul_f32_e32 v141, v177, v177
	v_mul_f32_e32 v138, v138, v174
	v_mul_f32_e32 v139, v139, v175
	v_mul_f32_e32 v140, v140, v176
	v_mul_f32_e32 v141, v141, v177
	v_fma_f32 v138, v202, v138, v174
	v_fma_f32 v139, v202, v139, v175
	v_fma_f32 v140, v202, v140, v176
	v_fma_f32 v141, v202, v141, v177
	v_mul_f32_e32 v138, 0x40135761, v138
	v_mul_f32_e32 v139, 0x40135761, v139
	v_mul_f32_e32 v140, 0x40135761, v140
	v_mul_f32_e32 v141, 0x40135761, v141
	v_exp_f32_e32 v138, v138
	v_exp_f32_e32 v139, v139
	v_exp_f32_e32 v140, v140
	v_exp_f32_e32 v141, v141
	s_nop 0
	v_add_f32_e32 v138, 1.0, v138
	v_add_f32_e32 v139, 1.0, v139
	v_add_f32_e32 v140, 1.0, v140
	v_add_f32_e32 v141, 1.0, v141
	v_rcp_f32_e32 v138, v138
	v_rcp_f32_e32 v139, v139
	v_rcp_f32_e32 v140, v140
	v_rcp_f32_e32 v141, v141
	s_nop 0
	v_fma_f32 v138, -2.0, v138, 1.0
	v_fma_f32 v139, -2.0, v139, 1.0
	v_fma_f32 v140, -2.0, v140, 1.0
	v_fma_f32 v141, -2.0, v141, 1.0
	v_add_f32_e32 v138, 1.0, v138
	v_add_f32_e32 v139, 1.0, v139
	v_add_f32_e32 v140, 1.0, v140
	v_add_f32_e32 v141, 1.0, v141
	v_mul_f32_e32 v174, 0.5, v174
	v_mul_f32_e32 v175, 0.5, v175
	v_mul_f32_e32 v176, 0.5, v176
	v_mul_f32_e32 v177, 0.5, v177
	v_mul_f32_e32 v174, v174, v138
	v_mul_f32_e32 v175, v175, v139
	v_mul_f32_e32 v176, v176, v140
	v_mul_f32_e32 v177, v177, v141
	v_add_f32_e32 v102, v217, v102
	v_add_f32_e32 v103, v218, v103
	v_add_f32_e32 v104, v219, v104
	v_add_f32_e32 v105, v220, v105
	v_mul_f32_e32 v102, v102, v174
	v_mul_f32_e32 v103, v103, v175
	v_mul_f32_e32 v104, v104, v176
	v_mul_f32_e32 v105, v105, v177
	v_cvt_pk_bf16_f32 v102, v102, v102
	v_cvt_pk_bf16_f32 v103, v103, v103
	v_cvt_pk_bf16_f32 v104, v104, v104
	v_cvt_pk_bf16_f32 v105, v105, v105
	v_mul_f32_e32 v138, v178, v178
	v_mul_f32_e32 v139, v179, v179
	v_mul_f32_e32 v140, v180, v180
	v_mul_f32_e32 v141, v181, v181
	v_mul_f32_e32 v138, v138, v178
	v_mul_f32_e32 v139, v139, v179
	v_mul_f32_e32 v140, v140, v180
	v_mul_f32_e32 v141, v141, v181
	v_fma_f32 v138, v202, v138, v178
	v_fma_f32 v139, v202, v139, v179
	v_fma_f32 v140, v202, v140, v180
	v_fma_f32 v141, v202, v141, v181
	v_mul_f32_e32 v138, 0x40135761, v138
	v_mul_f32_e32 v139, 0x40135761, v139
	v_mul_f32_e32 v140, 0x40135761, v140
	v_mul_f32_e32 v141, 0x40135761, v141
	v_exp_f32_e32 v138, v138
	v_exp_f32_e32 v139, v139
	v_exp_f32_e32 v140, v140
	v_exp_f32_e32 v141, v141
	s_nop 0
	v_add_f32_e32 v138, 1.0, v138
	v_add_f32_e32 v139, 1.0, v139
	v_add_f32_e32 v140, 1.0, v140
	v_add_f32_e32 v141, 1.0, v141
	v_rcp_f32_e32 v138, v138
	v_rcp_f32_e32 v139, v139
	v_rcp_f32_e32 v140, v140
	v_rcp_f32_e32 v141, v141
	s_nop 0
	v_fma_f32 v138, -2.0, v138, 1.0
	v_fma_f32 v139, -2.0, v139, 1.0
	v_fma_f32 v140, -2.0, v140, 1.0
	v_fma_f32 v141, -2.0, v141, 1.0
	v_add_f32_e32 v138, 1.0, v138
	v_add_f32_e32 v139, 1.0, v139
	v_add_f32_e32 v140, 1.0, v140
	v_add_f32_e32 v141, 1.0, v141
	v_mul_f32_e32 v178, 0.5, v178
	v_mul_f32_e32 v179, 0.5, v179
	v_mul_f32_e32 v180, 0.5, v180
	v_mul_f32_e32 v181, 0.5, v181
	v_mul_f32_e32 v178, v178, v138
	v_mul_f32_e32 v179, v179, v139
	v_mul_f32_e32 v180, v180, v140
	v_mul_f32_e32 v181, v181, v141
	v_add_f32_e32 v106, v221, v106
	v_add_f32_e32 v107, v222, v107
	v_add_f32_e32 v108, v223, v108
	v_add_f32_e32 v109, v224, v109
	v_mul_f32_e32 v106, v106, v178
	v_mul_f32_e32 v107, v107, v179
	v_mul_f32_e32 v108, v108, v180
	v_mul_f32_e32 v109, v109, v181
	v_cvt_pk_bf16_f32 v106, v106, v106
	v_cvt_pk_bf16_f32 v107, v107, v107
	v_cvt_pk_bf16_f32 v108, v108, v108
	v_cvt_pk_bf16_f32 v109, v109, v109
	v_mul_f32_e32 v138, v182, v182
	v_mul_f32_e32 v139, v183, v183
	v_mul_f32_e32 v140, v184, v184
	v_mul_f32_e32 v141, v185, v185
	v_mul_f32_e32 v138, v138, v182
	v_mul_f32_e32 v139, v139, v183
	v_mul_f32_e32 v140, v140, v184
	v_mul_f32_e32 v141, v141, v185
	v_fma_f32 v138, v202, v138, v182
	v_fma_f32 v139, v202, v139, v183
	v_fma_f32 v140, v202, v140, v184
	v_fma_f32 v141, v202, v141, v185
	v_mul_f32_e32 v138, 0x40135761, v138
	v_mul_f32_e32 v139, 0x40135761, v139
	v_mul_f32_e32 v140, 0x40135761, v140
	v_mul_f32_e32 v141, 0x40135761, v141
	v_exp_f32_e32 v138, v138
	v_exp_f32_e32 v139, v139
	v_exp_f32_e32 v140, v140
	v_exp_f32_e32 v141, v141
	s_nop 0
	v_add_f32_e32 v138, 1.0, v138
	v_add_f32_e32 v139, 1.0, v139
	v_add_f32_e32 v140, 1.0, v140
	v_add_f32_e32 v141, 1.0, v141
	v_rcp_f32_e32 v138, v138
	v_rcp_f32_e32 v139, v139
	v_rcp_f32_e32 v140, v140
	v_rcp_f32_e32 v141, v141
	s_nop 0
	v_fma_f32 v138, -2.0, v138, 1.0
	v_fma_f32 v139, -2.0, v139, 1.0
	v_fma_f32 v140, -2.0, v140, 1.0
	v_fma_f32 v141, -2.0, v141, 1.0
	v_add_f32_e32 v138, 1.0, v138
	v_add_f32_e32 v139, 1.0, v139
	v_add_f32_e32 v140, 1.0, v140
	v_add_f32_e32 v141, 1.0, v141
	v_mul_f32_e32 v182, 0.5, v182
	v_mul_f32_e32 v183, 0.5, v183
; __device__ __forceinline__ void lru_tile(const Params& P, int chunk, int head, int pass, char* smem_raw) {
;     ...
;             const float hfv = hfp[i];
;             const float g = gp[i];
;             const float tz = 0.7978845608028654f * (g + 0.044715f * g * g * g);
;             const float th = 1.f - 2.f * __builtin_amdgcn_rcpf(1.f + __expf(2.f * tz));
;             const float ge = 0.5f * g * (1.f + th);
;             P.cat[row * 1024 + gch] = f2bf((hfv + h) * ge);
	v_mul_f32_e32 v184, 0.5, v184
	v_mul_f32_e32 v185, 0.5, v185
	v_mul_f32_e32 v182, v182, v138
	v_mul_f32_e32 v183, v183, v139
	v_mul_f32_e32 v184, v184, v140
	v_mul_f32_e32 v185, v185, v141
	v_add_f32_e32 v110, v225, v110
	v_add_f32_e32 v111, v226, v111
	v_add_f32_e32 v112, v227, v112
	v_add_f32_e32 v113, v228, v113
	v_mul_f32_e32 v110, v110, v182
	v_mul_f32_e32 v111, v111, v183
	v_mul_f32_e32 v112, v112, v184
	v_mul_f32_e32 v113, v113, v185
	v_cvt_pk_bf16_f32 v110, v110, v110
	v_cvt_pk_bf16_f32 v111, v111, v111
	v_cvt_pk_bf16_f32 v112, v112, v112
	v_cvt_pk_bf16_f32 v113, v113, v113
	v_mul_f32_e32 v138, v186, v186
	v_mul_f32_e32 v139, v187, v187
	v_mul_f32_e32 v140, v188, v188
	v_mul_f32_e32 v141, v189, v189
	v_mul_f32_e32 v138, v138, v186
	v_mul_f32_e32 v139, v139, v187
	v_mul_f32_e32 v140, v140, v188
	v_mul_f32_e32 v141, v141, v189
	v_fma_f32 v138, v202, v138, v186
	v_fma_f32 v139, v202, v139, v187
	v_fma_f32 v140, v202, v140, v188
	v_fma_f32 v141, v202, v141, v189
	v_mul_f32_e32 v138, 0x40135761, v138
	v_mul_f32_e32 v139, 0x40135761, v139
	v_mul_f32_e32 v140, 0x40135761, v140
	v_mul_f32_e32 v141, 0x40135761, v141
	v_exp_f32_e32 v138, v138
	v_exp_f32_e32 v139, v139
	v_exp_f32_e32 v140, v140
	v_exp_f32_e32 v141, v141
	s_nop 0
	v_add_f32_e32 v138, 1.0, v138
	v_add_f32_e32 v139, 1.0, v139
	v_add_f32_e32 v140, 1.0, v140
	v_add_f32_e32 v141, 1.0, v141
	v_rcp_f32_e32 v138, v138
	v_rcp_f32_e32 v139, v139
	v_rcp_f32_e32 v140, v140
	v_rcp_f32_e32 v141, v141
	s_nop 0
	v_fma_f32 v138, -2.0, v138, 1.0
	v_fma_f32 v139, -2.0, v139, 1.0
	v_fma_f32 v140, -2.0, v140, 1.0
	v_fma_f32 v141, -2.0, v141, 1.0
	v_add_f32_e32 v138, 1.0, v138
	v_add_f32_e32 v139, 1.0, v139
	v_add_f32_e32 v140, 1.0, v140
	v_add_f32_e32 v141, 1.0, v141
	v_mul_f32_e32 v186, 0.5, v186
	v_mul_f32_e32 v187, 0.5, v187
	v_mul_f32_e32 v188, 0.5, v188
	v_mul_f32_e32 v189, 0.5, v189
	v_mul_f32_e32 v186, v186, v138
	v_mul_f32_e32 v187, v187, v139
	v_mul_f32_e32 v188, v188, v140
	v_mul_f32_e32 v189, v189, v141
	v_add_f32_e32 v114, v229, v114
	v_add_f32_e32 v115, v230, v115
	v_add_f32_e32 v116, v231, v116
	v_add_f32_e32 v117, v232, v117
	v_mul_f32_e32 v114, v114, v186
	v_mul_f32_e32 v115, v115, v187
	v_mul_f32_e32 v116, v116, v188
	v_mul_f32_e32 v117, v117, v189
	v_cvt_pk_bf16_f32 v114, v114, v114
	v_cvt_pk_bf16_f32 v115, v115, v115
	v_cvt_pk_bf16_f32 v116, v116, v116
	v_cvt_pk_bf16_f32 v117, v117, v117
	v_mul_f32_e32 v138, v190, v190
	v_mul_f32_e32 v139, v191, v191
	v_mul_f32_e32 v140, v192, v192
	v_mul_f32_e32 v141, v193, v193
	v_mul_f32_e32 v138, v138, v190
	v_mul_f32_e32 v139, v139, v191
	v_mul_f32_e32 v140, v140, v192
	v_mul_f32_e32 v141, v141, v193
	v_fma_f32 v138, v202, v138, v190
	v_fma_f32 v139, v202, v139, v191
	v_fma_f32 v140, v202, v140, v192
	v_fma_f32 v141, v202, v141, v193
	v_mul_f32_e32 v138, 0x40135761, v138
	v_mul_f32_e32 v139, 0x40135761, v139
	v_mul_f32_e32 v140, 0x40135761, v140
	v_mul_f32_e32 v141, 0x40135761, v141
	v_exp_f32_e32 v138, v138
	v_exp_f32_e32 v139, v139
	v_exp_f32_e32 v140, v140
	v_exp_f32_e32 v141, v141
	s_nop 0
	v_add_f32_e32 v138, 1.0, v138
	v_add_f32_e32 v139, 1.0, v139
	v_add_f32_e32 v140, 1.0, v140
	v_add_f32_e32 v141, 1.0, v141
	v_rcp_f32_e32 v138, v138
	v_rcp_f32_e32 v139, v139
	v_rcp_f32_e32 v140, v140
	v_rcp_f32_e32 v141, v141
	s_nop 0
	v_fma_f32 v138, -2.0, v138, 1.0
	v_fma_f32 v139, -2.0, v139, 1.0
	v_fma_f32 v140, -2.0, v140, 1.0
	v_fma_f32 v141, -2.0, v141, 1.0
	v_add_f32_e32 v138, 1.0, v138
	v_add_f32_e32 v139, 1.0, v139
	v_add_f32_e32 v140, 1.0, v140
	v_add_f32_e32 v141, 1.0, v141
	v_mul_f32_e32 v190, 0.5, v190
; __device__ __forceinline__ void lru_tile(const Params& P, int chunk, int head, int pass, char* smem_raw) {
;     ...
;             const float hfv = hfp[i];
;             const float g = gp[i];
;             const float tz = 0.7978845608028654f * (g + 0.044715f * g * g * g);
;             const float th = 1.f - 2.f * __builtin_amdgcn_rcpf(1.f + __expf(2.f * tz));
;             const float ge = 0.5f * g * (1.f + th);
;             P.cat[row * 1024 + gch] = f2bf((hfv + h) * ge);
;           }
;         }
	v_mul_f32_e32 v191, 0.5, v191
	v_mul_f32_e32 v192, 0.5, v192
	v_mul_f32_e32 v193, 0.5, v193
	v_mul_f32_e32 v190, v190, v138
	v_mul_f32_e32 v191, v191, v139
	v_mul_f32_e32 v192, v192, v140
	v_mul_f32_e32 v193, v193, v141
	v_add_f32_e32 v118, v233, v118
	v_add_f32_e32 v119, v234, v119
	v_add_f32_e32 v120, v235, v120
	v_add_f32_e32 v121, v236, v121
	v_mul_f32_e32 v118, v118, v190
	v_mul_f32_e32 v119, v119, v191
	v_mul_f32_e32 v120, v120, v192
	v_mul_f32_e32 v121, v121, v193
	v_cvt_pk_bf16_f32 v118, v118, v118
	v_cvt_pk_bf16_f32 v119, v119, v119
	v_cvt_pk_bf16_f32 v120, v120, v120
	v_cvt_pk_bf16_f32 v121, v121, v121
	s_lshl_b32 s0, s71, 18
	s_lshl_b32 s1, s56, 1
	s_add_u32 s0, s0, s1
	s_add_u32 s4, s12, s0
	s_addc_u32 s5, s13, 0
	global_store_short v237, v90, s[4:5]
	s_add_u32 s4, s4, 0x800
	s_addc_u32 s5, s5, 0
	global_store_short v237, v91, s[4:5]
	s_add_u32 s4, s4, 0x800
	s_addc_u32 s5, s5, 0
	global_store_short v237, v92, s[4:5]
	s_add_u32 s4, s4, 0x800
	s_addc_u32 s5, s5, 0
	global_store_short v237, v93, s[4:5]
	s_add_u32 s4, s4, 0x800
	s_addc_u32 s5, s5, 0
	global_store_short v237, v94, s[4:5]
	s_add_u32 s4, s4, 0x800
	s_addc_u32 s5, s5, 0
	global_store_short v237, v95, s[4:5]
	s_add_u32 s4, s4, 0x800
	s_addc_u32 s5, s5, 0
	global_store_short v237, v96, s[4:5]
	s_add_u32 s4, s4, 0x800
	s_addc_u32 s5, s5, 0
	global_store_short v237, v97, s[4:5]
	s_add_u32 s4, s4, 0x800
	s_addc_u32 s5, s5, 0
	global_store_short v237, v98, s[4:5]
	s_add_u32 s4, s4, 0x800
	s_addc_u32 s5, s5, 0
	global_store_short v237, v99, s[4:5]
	s_add_u32 s4, s4, 0x800
	s_addc_u32 s5, s5, 0
	global_store_short v237, v100, s[4:5]
	s_add_u32 s4, s4, 0x800
	s_addc_u32 s5, s5, 0
	global_store_short v237, v101, s[4:5]
	s_add_u32 s4, s4, 0x800
	s_addc_u32 s5, s5, 0
	global_store_short v237, v102, s[4:5]
	s_add_u32 s4, s4, 0x800
	s_addc_u32 s5, s5, 0
	global_store_short v237, v103, s[4:5]
	s_add_u32 s4, s4, 0x800
	s_addc_u32 s5, s5, 0
	global_store_short v237, v104, s[4:5]
	s_add_u32 s4, s4, 0x800
	s_addc_u32 s5, s5, 0
	global_store_short v237, v105, s[4:5]
	s_add_u32 s4, s4, 0x800
	s_addc_u32 s5, s5, 0
	global_store_short v237, v106, s[4:5]
	s_add_u32 s4, s4, 0x800
	s_addc_u32 s5, s5, 0
	global_store_short v237, v107, s[4:5]
	s_add_u32 s4, s4, 0x800
	s_addc_u32 s5, s5, 0
	global_store_short v237, v108, s[4:5]
	s_add_u32 s4, s4, 0x800
	s_addc_u32 s5, s5, 0
	global_store_short v237, v109, s[4:5]
	s_add_u32 s4, s4, 0x800
	s_addc_u32 s5, s5, 0
	global_store_short v237, v110, s[4:5]
	s_add_u32 s4, s4, 0x800
	s_addc_u32 s5, s5, 0
	global_store_short v237, v111, s[4:5]
	s_add_u32 s4, s4, 0x800
	s_addc_u32 s5, s5, 0
	global_store_short v237, v112, s[4:5]
	s_add_u32 s4, s4, 0x800
	s_addc_u32 s5, s5, 0
	global_store_short v237, v113, s[4:5]
	s_add_u32 s4, s4, 0x800
	s_addc_u32 s5, s5, 0
	global_store_short v237, v114, s[4:5]
	s_add_u32 s4, s4, 0x800
	s_addc_u32 s5, s5, 0
	global_store_short v237, v115, s[4:5]
	s_add_u32 s4, s4, 0x800
	s_addc_u32 s5, s5, 0
	global_store_short v237, v116, s[4:5]
	s_add_u32 s4, s4, 0x800
	s_addc_u32 s5, s5, 0
	global_store_short v237, v117, s[4:5]
	s_add_u32 s4, s4, 0x800
	s_addc_u32 s5, s5, 0
	global_store_short v237, v118, s[4:5]
	s_add_u32 s4, s4, 0x800
	s_addc_u32 s5, s5, 0
	global_store_short v237, v119, s[4:5]
	s_add_u32 s4, s4, 0x800
	s_addc_u32 s5, s5, 0
	global_store_short v237, v120, s[4:5]
	s_add_u32 s4, s4, 0x800
	s_addc_u32 s5, s5, 0
	global_store_short v237, v121, s[4:5]
	s_add_u32 s69, s69, 1
	s_cmp_lt_u32 s69, s70
	s_cbranch_scc1 .Lmy_lrub_tile
	s_waitcnt lgkmcnt(0)
	s_barrier
	s_branch .LBB0_680
